# movpk2: all 64-bit register moves in the NSA phase and the hoisted-load copies in GEMM epilogues / NSA prologues as v_pk_mov_b32
# baseline (speedup 1.0000x reference)
.LBB0_627:
	v_lshl_add_u32 v152, s0, 8, v154
	v_ashrrev_i32_e32 v153, 31, v152
	v_lshlrev_b64 v[150:151], 6, v[152:153]
	v_lshl_add_u64 v[150:151], v[140:141], 0, v[150:151]
	global_load_dwordx4 v[164:167], v[150:151], off
	global_load_dwordx4 v[188:191], v[150:151], off offset:1024
	global_load_dwordx4 v[192:195], v[150:151], off offset:2048
	global_load_dwordx4 v[196:199], v[150:151], off offset:3072
	v_mov_b32_e32 v216, 0x2000
	v_mov_b32_e32 v217, 0
	v_lshl_add_u64 v[216:217], v[150:151], 0, v[216:217]
	global_load_dwordx4 v[200:203], v[216:217], off
	global_load_dwordx4 v[204:207], v[216:217], off offset:1024
	global_load_dwordx4 v[208:211], v[216:217], off offset:2048
	global_load_dwordx4 v[212:215], v[216:217], off offset:3072
	v_and_b32_e32 v163, 64, v161
	v_xor_b32_e32 v153, 16, v161
	v_pk_mul_f32 v[170:171], v[114:115], v[122:123]
	v_add_u32_e32 v122, 64, v163
	v_cmp_lt_i32_e32 vcc, v153, v122
	v_pk_mul_f32 v[172:173], v[112:113], v[120:121]
	v_xor_b32_e32 v174, 32, v161
	v_cndmask_b32_e32 v120, v161, v153, vcc
	v_lshlrev_b32_e32 v123, 2, v120
	v_cmp_lt_i32_e32 vcc, v174, v122
	v_pk_mul_f32 v[126:127], v[118:119], v[126:127]
	v_pk_mul_f32 v[124:125], v[116:117], v[124:125]
	v_cndmask_b32_e32 v122, v161, v174, vcc
	v_lshlrev_b32_e32 v122, 2, v122
	v_lshl_or_b32 v168, s1, 7, v156
	v_ashrrev_i32_e32 v169, 31, v168
	v_mov_b64_e32 v[150:151], s[10:11]
	v_pk_mul_f32 v[110:111], v[102:103], v[110:111]
	v_pk_mul_f32 v[108:109], v[100:101], v[108:109]
	v_pk_mul_f32 v[106:107], v[98:99], v[106:107]
	v_pk_mul_f32 v[104:105], v[96:97], v[104:105]
	v_pk_mul_f32 v[94:95], v[86:87], v[94:95]
	v_pk_mul_f32 v[92:93], v[84:85], v[92:93]
	v_pk_mul_f32 v[90:91], v[82:83], v[90:91]
	v_pk_mul_f32 v[88:89], v[80:81], v[88:89]
	v_pk_mul_f32 v[78:79], v[70:71], v[78:79]
	v_pk_mul_f32 v[76:77], v[68:69], v[76:77]
	v_pk_mul_f32 v[74:75], v[66:67], v[74:75]
	v_pk_mul_f32 v[72:73], v[64:65], v[72:73]
	v_pk_mul_f32 v[62:63], v[54:55], v[62:63]
	v_pk_mul_f32 v[60:61], v[52:53], v[60:61]
	v_pk_mul_f32 v[58:59], v[50:51], v[58:59]
	v_pk_mul_f32 v[56:57], v[48:49], v[56:57]
	v_pk_mul_f32 v[46:47], v[38:39], v[46:47]
	v_pk_mul_f32 v[44:45], v[36:37], v[44:45]
	v_pk_mul_f32 v[42:43], v[34:35], v[42:43]
	v_pk_mul_f32 v[40:41], v[32:33], v[40:41]
	v_pk_mul_f32 v[30:31], v[22:23], v[30:31]
	v_pk_mul_f32 v[28:29], v[20:21], v[28:29]
	v_pk_mul_f32 v[26:27], v[18:19], v[26:27]
	v_pk_mul_f32 v[24:25], v[16:17], v[24:25]
	v_pk_mul_f32 v[14:15], v[6:7], v[14:15]
	v_pk_mul_f32 v[12:13], v[4:5], v[12:13]
	v_pk_mul_f32 v[10:11], v[2:3], v[10:11]
	v_pk_mul_f32 v[8:9], v[0:1], v[8:9]
	s_waitcnt vmcnt(0)
	v_mov_b32_e32 v120, v165
	v_mov_b32_e32 v121, v166
	v_mov_b32_e32 v165, v167
	v_pk_add_f32 v[120:121], v[120:121], v[164:165]
	v_or_b32_e32 v166, 16, v152
	v_add_f32_e32 v120, v120, v121
	v_mov_b32_e32 v121, v120
	s_nop 1
	v_permlane16_swap_b32_e32 v120, v121
	v_ashrrev_i32_e32 v167, 31, v166
	v_mad_i64_i32 v[164:165], s[0:1], v152, s49, v[150:151]
	s_waitcnt lgkmcnt(0)
	v_add_f32_e32 v153, v120, v121
	v_mov_b32_e32 v163, v153
	s_nop 1
	v_permlane32_swap_b32_e32 v153, v163
	v_lshlrev_b64 v[120:121], 1, v[168:169]
	v_lshlrev_b64 v[168:169], 6, v[166:167]
	v_lshl_add_u64 v[164:165], v[164:165], 0, v[120:121]
	v_lshl_add_u64 v[168:169], v[140:141], 0, v[168:169]
	s_waitcnt lgkmcnt(0)
	v_add_f32_e32 v153, v153, v163
	v_fmamk_f32 v153, v153, 0x3a800000, v162
	v_mul_f32_e32 v163, 0x4b800000, v153
	v_cmp_gt_f32_e32 vcc, s52, v153
	s_nop 1
	v_cndmask_b32_e32 v153, v153, v163, vcc
	v_rsq_f32_e32 v153, v153
	s_nop 0
	v_mul_f32_e32 v163, 0x45800000, v153
	v_cndmask_b32_e32 v153, v153, v163, vcc
	v_mul_f32_e32 v163, 0xbfb8aa3b, v153
	v_mul_f32_e32 v116, v116, v163
	v_mul_f32_e32 v117, v117, v163
	v_mul_f32_e32 v118, v118, v163
	v_mul_f32_e32 v119, v119, v163
	v_mul_f32_e32 v112, v112, v163
	v_mul_f32_e32 v113, v113, v163
	v_mul_f32_e32 v114, v114, v163
	v_mul_f32_e32 v115, v115, v163
	v_exp_f32_e32 v116, v116
	v_exp_f32_e32 v117, v117
	v_exp_f32_e32 v118, v118
	v_exp_f32_e32 v119, v119
	v_exp_f32_e32 v112, v112
	v_exp_f32_e32 v113, v113
	v_exp_f32_e32 v114, v114
	v_exp_f32_e32 v115, v115
	v_mul_f32_e32 v174, v153, v153
	v_add_f32_e32 v116, 1.0, v116
	v_add_f32_e32 v117, 1.0, v117
	v_add_f32_e32 v118, 1.0, v118
	v_add_f32_e32 v119, 1.0, v119
	v_add_f32_e32 v153, 1.0, v112
	v_add_f32_e32 v163, 1.0, v113
	v_add_f32_e32 v167, 1.0, v114
	v_add_f32_e32 v175, 1.0, v115
	v_rcp_f32_e32 v112, v116
	v_rcp_f32_e32 v113, v117
	v_rcp_f32_e32 v114, v118
	v_rcp_f32_e32 v115, v119
	v_rcp_f32_e32 v116, v153
	v_rcp_f32_e32 v117, v163
	v_rcp_f32_e32 v118, v167
	v_rcp_f32_e32 v119, v175
	v_pk_mul_f32 v[112:113], v[174:175], v[112:113] op_sel_hi:[0,1]
	v_pk_mul_f32 v[114:115], v[174:175], v[114:115] op_sel_hi:[0,1]
	v_pk_mul_f32 v[116:117], v[174:175], v[116:117] op_sel_hi:[0,1]
	v_pk_mul_f32 v[118:119], v[174:175], v[118:119] op_sel_hi:[0,1]
	v_pk_mul_f32 v[112:113], v[124:125], v[112:113]
	v_pk_mul_f32 v[114:115], v[126:127], v[114:115]
	v_pk_mul_f32 v[116:117], v[172:173], v[116:117]
	v_pk_mul_f32 v[118:119], v[170:171], v[118:119]
	v_cvt_pk_bf16_f32 v112, v112, v113
	v_cvt_pk_bf16_f32 v113, v114, v115
	v_cvt_pk_bf16_f32 v114, v116, v117
	v_cvt_pk_bf16_f32 v115, v118, v119
	global_store_dwordx4 v[164:165], v[112:115], off
	s_nop 1
	v_pk_mov_b32 v[112:113], v[188:189], v[188:189] op_sel:[0,1]
	v_pk_mov_b32 v[114:115], v[190:191], v[190:191] op_sel:[0,1]
	v_mov_b32_e32 v116, v113
	v_mov_b32_e32 v117, v114
	v_mov_b32_e32 v113, v115
	v_pk_add_f32 v[112:113], v[116:117], v[112:113]
	v_mad_i64_i32 v[114:115], s[0:1], v166, s49, v[150:151]
	v_add_f32_e32 v112, v112, v113
	v_mov_b32_e32 v113, v112
	s_nop 1
	v_permlane16_swap_b32_e32 v112, v113
	v_lshl_add_u64 v[114:115], v[114:115], 0, v[120:121]
	s_waitcnt lgkmcnt(0)
	v_add_f32_e32 v116, v112, v113
	v_mov_b32_e32 v117, v116
	s_nop 1
	v_permlane32_swap_b32_e32 v116, v117
	v_or_b32_e32 v112, 32, v152
	v_ashrrev_i32_e32 v113, 31, v112
	s_waitcnt lgkmcnt(0)
	v_add_f32_e32 v116, v116, v117
	v_fmamk_f32 v116, v116, 0x3a800000, v162
	v_mul_f32_e32 v117, 0x4b800000, v116
	v_cmp_gt_f32_e32 vcc, s52, v116
	s_nop 1
	v_cndmask_b32_e32 v116, v116, v117, vcc
	v_rsq_f32_e32 v118, v116
	v_lshlrev_b64 v[116:117], 6, v[112:113]
	v_lshl_add_u64 v[116:117], v[140:141], 0, v[116:117]
	v_mul_f32_e32 v113, 0x45800000, v118
	v_cndmask_b32_e32 v113, v118, v113, vcc
	v_mul_f32_e32 v119, 0xbfb8aa3b, v113
	v_mul_f32_e32 v100, v100, v119
	v_mul_f32_e32 v101, v101, v119
	v_mul_f32_e32 v102, v102, v119
	v_mul_f32_e32 v103, v103, v119
	v_mul_f32_e32 v96, v96, v119
	v_mul_f32_e32 v97, v97, v119
	v_mul_f32_e32 v98, v98, v119
	v_mul_f32_e32 v99, v99, v119
	v_exp_f32_e32 v100, v100
	v_exp_f32_e32 v101, v101
	v_exp_f32_e32 v102, v102
	v_exp_f32_e32 v103, v103
	v_exp_f32_e32 v96, v96
	v_exp_f32_e32 v97, v97
	v_exp_f32_e32 v98, v98
	v_exp_f32_e32 v99, v99
	v_mul_f32_e32 v118, v113, v113
	v_add_f32_e32 v100, 1.0, v100
	v_add_f32_e32 v101, 1.0, v101
	v_add_f32_e32 v102, 1.0, v102
	v_add_f32_e32 v103, 1.0, v103
	v_add_f32_e32 v113, 1.0, v96
	v_add_f32_e32 v119, 1.0, v97
	v_add_f32_e32 v124, 1.0, v98
	v_add_f32_e32 v125, 1.0, v99
	v_rcp_f32_e32 v96, v100
	v_rcp_f32_e32 v97, v101
	v_rcp_f32_e32 v98, v102
	v_rcp_f32_e32 v99, v103
	v_rcp_f32_e32 v100, v113
	v_rcp_f32_e32 v101, v119
	v_rcp_f32_e32 v102, v124
	v_rcp_f32_e32 v103, v125
	v_pk_mul_f32 v[96:97], v[118:119], v[96:97] op_sel_hi:[0,1]
	v_pk_mul_f32 v[98:99], v[118:119], v[98:99] op_sel_hi:[0,1]
	v_pk_mul_f32 v[100:101], v[118:119], v[100:101] op_sel_hi:[0,1]
	v_pk_mul_f32 v[102:103], v[118:119], v[102:103] op_sel_hi:[0,1]
	v_pk_mul_f32 v[96:97], v[108:109], v[96:97]
	v_pk_mul_f32 v[98:99], v[110:111], v[98:99]
	v_pk_mul_f32 v[100:101], v[104:105], v[100:101]
	v_pk_mul_f32 v[102:103], v[106:107], v[102:103]
	v_cvt_pk_bf16_f32 v96, v96, v97
	v_cvt_pk_bf16_f32 v97, v98, v99
	v_cvt_pk_bf16_f32 v98, v100, v101
	v_cvt_pk_bf16_f32 v99, v102, v103
	global_store_dwordx4 v[114:115], v[96:99], off
	s_nop 1
	v_pk_mov_b32 v[96:97], v[192:193], v[192:193] op_sel:[0,1]
	v_pk_mov_b32 v[98:99], v[194:195], v[194:195] op_sel:[0,1]
	v_mov_b32_e32 v100, v97
	v_mov_b32_e32 v101, v98
	v_mov_b32_e32 v97, v99
	v_pk_add_f32 v[96:97], v[100:101], v[96:97]
	v_mad_i64_i32 v[98:99], s[0:1], v112, s49, v[150:151]
	v_add_f32_e32 v96, v96, v97
	v_mov_b32_e32 v97, v96
	s_nop 1
	v_permlane16_swap_b32_e32 v96, v97
	v_lshl_add_u64 v[98:99], v[98:99], 0, v[120:121]
	s_waitcnt lgkmcnt(0)
	v_add_f32_e32 v100, v96, v97
	v_mov_b32_e32 v101, v100
	s_nop 1
	v_permlane32_swap_b32_e32 v100, v101
	v_or_b32_e32 v96, 48, v152
	v_ashrrev_i32_e32 v97, 31, v96
	s_waitcnt lgkmcnt(0)
	v_add_f32_e32 v100, v100, v101
	v_fmamk_f32 v100, v100, 0x3a800000, v162
	v_mul_f32_e32 v101, 0x4b800000, v100
	v_cmp_gt_f32_e32 vcc, s52, v100
	s_nop 1
	v_cndmask_b32_e32 v100, v100, v101, vcc
	v_rsq_f32_e32 v102, v100
	v_lshlrev_b64 v[100:101], 6, v[96:97]
	v_lshl_add_u64 v[100:101], v[140:141], 0, v[100:101]
	v_mul_f32_e32 v97, 0x45800000, v102
	v_cndmask_b32_e32 v97, v102, v97, vcc
	v_mul_f32_e32 v103, 0xbfb8aa3b, v97
	v_mul_f32_e32 v84, v84, v103
	v_mul_f32_e32 v85, v85, v103
	v_mul_f32_e32 v86, v86, v103
	v_mul_f32_e32 v87, v87, v103
	v_mul_f32_e32 v80, v80, v103
	v_mul_f32_e32 v81, v81, v103
	v_mul_f32_e32 v82, v82, v103
	v_mul_f32_e32 v83, v83, v103
	v_exp_f32_e32 v84, v84
	v_exp_f32_e32 v85, v85
	v_exp_f32_e32 v86, v86
	v_exp_f32_e32 v87, v87
	v_exp_f32_e32 v80, v80
	v_exp_f32_e32 v81, v81
	v_exp_f32_e32 v82, v82
	v_exp_f32_e32 v83, v83
	v_mul_f32_e32 v102, v97, v97
	v_add_f32_e32 v84, 1.0, v84
	v_add_f32_e32 v85, 1.0, v85
	v_add_f32_e32 v86, 1.0, v86
	v_add_f32_e32 v87, 1.0, v87
	v_add_f32_e32 v97, 1.0, v80
	v_add_f32_e32 v103, 1.0, v81
	v_add_f32_e32 v104, 1.0, v82
	v_add_f32_e32 v105, 1.0, v83
	v_rcp_f32_e32 v80, v84
	v_rcp_f32_e32 v81, v85
	v_rcp_f32_e32 v82, v86
	v_rcp_f32_e32 v83, v87
	v_rcp_f32_e32 v84, v97
	v_rcp_f32_e32 v85, v103
	v_rcp_f32_e32 v86, v104
	v_rcp_f32_e32 v87, v105
	v_pk_mul_f32 v[80:81], v[102:103], v[80:81] op_sel_hi:[0,1]
	v_pk_mul_f32 v[82:83], v[102:103], v[82:83] op_sel_hi:[0,1]
	v_pk_mul_f32 v[84:85], v[102:103], v[84:85] op_sel_hi:[0,1]
	v_pk_mul_f32 v[86:87], v[102:103], v[86:87] op_sel_hi:[0,1]
	v_pk_mul_f32 v[80:81], v[92:93], v[80:81]
	v_pk_mul_f32 v[82:83], v[94:95], v[82:83]
	v_pk_mul_f32 v[84:85], v[88:89], v[84:85]
	v_pk_mul_f32 v[86:87], v[90:91], v[86:87]
	v_cvt_pk_bf16_f32 v80, v80, v81
	v_cvt_pk_bf16_f32 v81, v82, v83
	v_cvt_pk_bf16_f32 v82, v84, v85
	v_cvt_pk_bf16_f32 v83, v86, v87
	global_store_dwordx4 v[98:99], v[80:83], off
	s_nop 1
	v_pk_mov_b32 v[80:81], v[196:197], v[196:197] op_sel:[0,1]
	v_pk_mov_b32 v[82:83], v[198:199], v[198:199] op_sel:[0,1]
	v_mov_b32_e32 v84, v81
	v_mov_b32_e32 v85, v82
	v_mov_b32_e32 v81, v83
	v_pk_add_f32 v[80:81], v[84:85], v[80:81]
	v_mad_i64_i32 v[82:83], s[0:1], v96, s49, v[150:151]
	v_add_f32_e32 v80, v80, v81
	v_mov_b32_e32 v81, v80
	s_nop 1
	v_permlane16_swap_b32_e32 v80, v81
	v_lshl_add_u64 v[82:83], v[82:83], 0, v[120:121]
	s_waitcnt lgkmcnt(0)
	v_add_f32_e32 v84, v80, v81
	v_mov_b32_e32 v85, v84
	s_nop 1
	v_permlane32_swap_b32_e32 v84, v85
	v_add_u32_e32 v80, 0x80, v152
	v_ashrrev_i32_e32 v81, 31, v80
	s_waitcnt lgkmcnt(0)
	v_add_f32_e32 v84, v84, v85
	v_fmamk_f32 v84, v84, 0x3a800000, v162
	v_mul_f32_e32 v85, 0x4b800000, v84
	v_cmp_gt_f32_e32 vcc, s52, v84
	s_nop 1
	v_cndmask_b32_e32 v84, v84, v85, vcc
	v_rsq_f32_e32 v86, v84
	v_lshlrev_b64 v[84:85], 6, v[80:81]
	v_lshl_add_u64 v[84:85], v[140:141], 0, v[84:85]
	v_mul_f32_e32 v81, 0x45800000, v86
	v_cndmask_b32_e32 v81, v86, v81, vcc
	v_mul_f32_e32 v87, 0xbfb8aa3b, v81
	v_mul_f32_e32 v68, v68, v87
	v_mul_f32_e32 v69, v69, v87
	v_mul_f32_e32 v70, v70, v87
	v_mul_f32_e32 v71, v71, v87
	v_mul_f32_e32 v64, v64, v87
	v_mul_f32_e32 v65, v65, v87
	v_mul_f32_e32 v66, v66, v87
	v_mul_f32_e32 v67, v67, v87
	v_exp_f32_e32 v68, v68
	v_exp_f32_e32 v69, v69
	v_exp_f32_e32 v70, v70
	v_exp_f32_e32 v71, v71
	v_exp_f32_e32 v64, v64
	v_exp_f32_e32 v65, v65
	v_exp_f32_e32 v66, v66
	v_exp_f32_e32 v67, v67
	v_mul_f32_e32 v86, v81, v81
	v_add_f32_e32 v68, 1.0, v68
	v_add_f32_e32 v69, 1.0, v69
	v_add_f32_e32 v70, 1.0, v70
	v_add_f32_e32 v71, 1.0, v71
	v_add_f32_e32 v81, 1.0, v64
	v_add_f32_e32 v87, 1.0, v65
	v_add_f32_e32 v88, 1.0, v66
	v_add_f32_e32 v89, 1.0, v67
	v_rcp_f32_e32 v64, v68
	v_rcp_f32_e32 v65, v69
	v_rcp_f32_e32 v66, v70
	v_rcp_f32_e32 v67, v71
	v_rcp_f32_e32 v68, v81
	v_rcp_f32_e32 v69, v87
	v_rcp_f32_e32 v70, v88
	v_rcp_f32_e32 v71, v89
	v_pk_mul_f32 v[64:65], v[86:87], v[64:65] op_sel_hi:[0,1]
	v_pk_mul_f32 v[66:67], v[86:87], v[66:67] op_sel_hi:[0,1]
	v_pk_mul_f32 v[68:69], v[86:87], v[68:69] op_sel_hi:[0,1]
	v_pk_mul_f32 v[70:71], v[86:87], v[70:71] op_sel_hi:[0,1]
	v_pk_mul_f32 v[64:65], v[76:77], v[64:65]
	v_pk_mul_f32 v[66:67], v[78:79], v[66:67]
	v_pk_mul_f32 v[68:69], v[72:73], v[68:69]
	v_pk_mul_f32 v[70:71], v[74:75], v[70:71]
	v_cvt_pk_bf16_f32 v64, v64, v65
	v_cvt_pk_bf16_f32 v65, v66, v67
	v_cvt_pk_bf16_f32 v66, v68, v69
	v_cvt_pk_bf16_f32 v67, v70, v71
	global_store_dwordx4 v[82:83], v[64:67], off
	s_nop 1
	v_pk_mov_b32 v[64:65], v[200:201], v[200:201] op_sel:[0,1]
	v_pk_mov_b32 v[66:67], v[202:203], v[202:203] op_sel:[0,1]
	v_mov_b32_e32 v68, v65
	v_mov_b32_e32 v69, v66
	v_mov_b32_e32 v65, v67
	v_pk_add_f32 v[64:65], v[68:69], v[64:65]
	v_mad_i64_i32 v[66:67], s[0:1], v80, s49, v[150:151]
	v_add_f32_e32 v64, v64, v65
	v_mov_b32_e32 v65, v64
	s_nop 1
	v_permlane16_swap_b32_e32 v64, v65
	v_lshl_add_u64 v[66:67], v[66:67], 0, v[120:121]
	s_waitcnt lgkmcnt(0)
	v_add_f32_e32 v68, v64, v65
	v_mov_b32_e32 v69, v68
	s_nop 1
	v_permlane32_swap_b32_e32 v68, v69
	v_add_u32_e32 v64, 0x90, v152
	v_ashrrev_i32_e32 v65, 31, v64
	s_waitcnt lgkmcnt(0)
	v_add_f32_e32 v68, v68, v69
	v_fmamk_f32 v68, v68, 0x3a800000, v162
	v_mul_f32_e32 v69, 0x4b800000, v68
	v_cmp_gt_f32_e32 vcc, s52, v68
	s_nop 1
	v_cndmask_b32_e32 v68, v68, v69, vcc
	v_rsq_f32_e32 v70, v68
	v_lshlrev_b64 v[68:69], 6, v[64:65]
	v_lshl_add_u64 v[68:69], v[140:141], 0, v[68:69]
	v_mul_f32_e32 v65, 0x45800000, v70
	v_cndmask_b32_e32 v65, v70, v65, vcc
	v_mul_f32_e32 v71, 0xbfb8aa3b, v65
	v_mul_f32_e32 v52, v52, v71
	v_mul_f32_e32 v53, v53, v71
	v_mul_f32_e32 v54, v54, v71
	v_mul_f32_e32 v55, v55, v71
	v_mul_f32_e32 v48, v48, v71
	v_mul_f32_e32 v49, v49, v71
	v_mul_f32_e32 v50, v50, v71
	v_mul_f32_e32 v51, v51, v71
	v_exp_f32_e32 v52, v52
	v_exp_f32_e32 v53, v53
	v_exp_f32_e32 v54, v54
	v_exp_f32_e32 v55, v55
	v_exp_f32_e32 v48, v48
	v_exp_f32_e32 v49, v49
	v_exp_f32_e32 v50, v50
	v_exp_f32_e32 v51, v51
	v_mul_f32_e32 v70, v65, v65
	v_add_f32_e32 v52, 1.0, v52
	v_add_f32_e32 v53, 1.0, v53
	v_add_f32_e32 v54, 1.0, v54
	v_add_f32_e32 v55, 1.0, v55
	v_add_f32_e32 v65, 1.0, v48
	v_add_f32_e32 v71, 1.0, v49
	v_add_f32_e32 v72, 1.0, v50
	v_add_f32_e32 v73, 1.0, v51
	v_rcp_f32_e32 v48, v52
	v_rcp_f32_e32 v49, v53
	v_rcp_f32_e32 v50, v54
	v_rcp_f32_e32 v51, v55
	v_rcp_f32_e32 v52, v65
	v_rcp_f32_e32 v53, v71
	v_rcp_f32_e32 v54, v72
	v_rcp_f32_e32 v55, v73
	v_pk_mul_f32 v[48:49], v[70:71], v[48:49] op_sel_hi:[0,1]
	v_pk_mul_f32 v[50:51], v[70:71], v[50:51] op_sel_hi:[0,1]
	v_pk_mul_f32 v[52:53], v[70:71], v[52:53] op_sel_hi:[0,1]
	v_pk_mul_f32 v[54:55], v[70:71], v[54:55] op_sel_hi:[0,1]
	v_pk_mul_f32 v[48:49], v[60:61], v[48:49]
	v_pk_mul_f32 v[50:51], v[62:63], v[50:51]
	v_pk_mul_f32 v[52:53], v[56:57], v[52:53]
	v_pk_mul_f32 v[54:55], v[58:59], v[54:55]
	v_cvt_pk_bf16_f32 v48, v48, v49
	v_cvt_pk_bf16_f32 v49, v50, v51
	v_cvt_pk_bf16_f32 v50, v52, v53
	v_cvt_pk_bf16_f32 v51, v54, v55
	global_store_dwordx4 v[66:67], v[48:51], off
	s_nop 1
	v_pk_mov_b32 v[48:49], v[204:205], v[204:205] op_sel:[0,1]
	v_pk_mov_b32 v[50:51], v[206:207], v[206:207] op_sel:[0,1]
	v_mov_b32_e32 v52, v49
	v_mov_b32_e32 v53, v50
	v_mov_b32_e32 v49, v51
	v_pk_add_f32 v[48:49], v[52:53], v[48:49]
	v_mad_i64_i32 v[50:51], s[0:1], v64, s49, v[150:151]
	v_add_f32_e32 v48, v48, v49
	v_mov_b32_e32 v49, v48
	s_nop 1
	v_permlane16_swap_b32_e32 v48, v49
	v_lshl_add_u64 v[50:51], v[50:51], 0, v[120:121]
	s_waitcnt lgkmcnt(0)
	v_add_f32_e32 v52, v48, v49
	v_mov_b32_e32 v53, v52
	s_nop 1
	v_permlane32_swap_b32_e32 v52, v53
	v_add_u32_e32 v48, 0xa0, v152
	v_ashrrev_i32_e32 v49, 31, v48
	s_waitcnt lgkmcnt(0)
	v_add_f32_e32 v52, v52, v53
	v_fmamk_f32 v52, v52, 0x3a800000, v162
	v_mul_f32_e32 v53, 0x4b800000, v52
	v_cmp_gt_f32_e32 vcc, s52, v52
	s_nop 1
	v_cndmask_b32_e32 v52, v52, v53, vcc
	v_rsq_f32_e32 v54, v52
	v_lshlrev_b64 v[52:53], 6, v[48:49]
	v_lshl_add_u64 v[52:53], v[140:141], 0, v[52:53]
	v_mul_f32_e32 v49, 0x45800000, v54
	v_cndmask_b32_e32 v49, v54, v49, vcc
	v_mul_f32_e32 v55, 0xbfb8aa3b, v49
	v_mul_f32_e32 v36, v36, v55
	v_mul_f32_e32 v37, v37, v55
	v_mul_f32_e32 v38, v38, v55
	v_mul_f32_e32 v39, v39, v55
	v_mul_f32_e32 v32, v32, v55
	v_mul_f32_e32 v33, v33, v55
	v_mul_f32_e32 v34, v34, v55
	v_mul_f32_e32 v35, v35, v55
	v_exp_f32_e32 v36, v36
	v_exp_f32_e32 v37, v37
	v_exp_f32_e32 v38, v38
	v_exp_f32_e32 v39, v39
	v_exp_f32_e32 v32, v32
	v_exp_f32_e32 v33, v33
	v_exp_f32_e32 v34, v34
	v_exp_f32_e32 v35, v35
	v_mul_f32_e32 v54, v49, v49
	v_add_f32_e32 v36, 1.0, v36
	v_add_f32_e32 v37, 1.0, v37
	v_add_f32_e32 v38, 1.0, v38
	v_add_f32_e32 v39, 1.0, v39
	v_add_f32_e32 v49, 1.0, v32
	v_add_f32_e32 v55, 1.0, v33
	v_add_f32_e32 v56, 1.0, v34
	v_add_f32_e32 v57, 1.0, v35
	v_rcp_f32_e32 v32, v36
	v_rcp_f32_e32 v33, v37
	v_rcp_f32_e32 v34, v38
	v_rcp_f32_e32 v35, v39
	v_rcp_f32_e32 v36, v49
	v_rcp_f32_e32 v37, v55
	v_rcp_f32_e32 v38, v56
	v_rcp_f32_e32 v39, v57
	v_pk_mul_f32 v[32:33], v[54:55], v[32:33] op_sel_hi:[0,1]
	v_pk_mul_f32 v[34:35], v[54:55], v[34:35] op_sel_hi:[0,1]
	v_pk_mul_f32 v[36:37], v[54:55], v[36:37] op_sel_hi:[0,1]
	v_pk_mul_f32 v[38:39], v[54:55], v[38:39] op_sel_hi:[0,1]
	v_pk_mul_f32 v[32:33], v[44:45], v[32:33]
	v_pk_mul_f32 v[34:35], v[46:47], v[34:35]
	v_pk_mul_f32 v[36:37], v[40:41], v[36:37]
	v_pk_mul_f32 v[38:39], v[42:43], v[38:39]
	v_cvt_pk_bf16_f32 v32, v32, v33
	v_cvt_pk_bf16_f32 v33, v34, v35
	v_cvt_pk_bf16_f32 v34, v36, v37
	v_cvt_pk_bf16_f32 v35, v38, v39
	global_store_dwordx4 v[50:51], v[32:35], off
	s_nop 1
	v_pk_mov_b32 v[32:33], v[208:209], v[208:209] op_sel:[0,1]
	v_pk_mov_b32 v[34:35], v[210:211], v[210:211] op_sel:[0,1]
	v_mov_b32_e32 v36, v33
	v_mov_b32_e32 v37, v34
	v_mov_b32_e32 v33, v35
	v_pk_add_f32 v[32:33], v[36:37], v[32:33]
	v_mad_i64_i32 v[34:35], s[0:1], v48, s49, v[150:151]
	v_add_f32_e32 v32, v32, v33
	v_mov_b32_e32 v33, v32
	s_nop 1
	v_permlane16_swap_b32_e32 v32, v33
	v_lshl_add_u64 v[34:35], v[34:35], 0, v[120:121]
	s_waitcnt lgkmcnt(0)
	v_add_f32_e32 v36, v32, v33
	v_mov_b32_e32 v37, v36
	s_nop 1
	v_permlane32_swap_b32_e32 v36, v37
	v_add_u32_e32 v32, 0xb0, v152
	v_ashrrev_i32_e32 v33, 31, v32
	s_waitcnt lgkmcnt(0)
	v_add_f32_e32 v36, v36, v37
	v_fmamk_f32 v36, v36, 0x3a800000, v162
	v_mul_f32_e32 v37, 0x4b800000, v36
	v_cmp_gt_f32_e32 vcc, s52, v36
	s_nop 1
	v_cndmask_b32_e32 v36, v36, v37, vcc
	v_rsq_f32_e32 v38, v36
	v_lshlrev_b64 v[36:37], 6, v[32:33]
	v_lshl_add_u64 v[36:37], v[140:141], 0, v[36:37]
	v_mul_f32_e32 v33, 0x45800000, v38
	v_cndmask_b32_e32 v33, v38, v33, vcc
	v_mul_f32_e32 v39, 0xbfb8aa3b, v33
	v_mul_f32_e32 v20, v20, v39
	v_mul_f32_e32 v21, v21, v39
	v_mul_f32_e32 v22, v22, v39
	v_mul_f32_e32 v23, v23, v39
	v_mul_f32_e32 v16, v16, v39
	v_mul_f32_e32 v17, v17, v39
	v_mul_f32_e32 v18, v18, v39
	v_mul_f32_e32 v19, v19, v39
	v_exp_f32_e32 v20, v20
	v_exp_f32_e32 v21, v21
	v_exp_f32_e32 v22, v22
	v_exp_f32_e32 v23, v23
	v_exp_f32_e32 v16, v16
	v_exp_f32_e32 v17, v17
	v_exp_f32_e32 v18, v18
	v_exp_f32_e32 v19, v19
	v_mul_f32_e32 v38, v33, v33
	v_add_f32_e32 v20, 1.0, v20
	v_add_f32_e32 v21, 1.0, v21
	v_add_f32_e32 v22, 1.0, v22
	v_add_f32_e32 v23, 1.0, v23
	v_add_f32_e32 v33, 1.0, v16
	v_add_f32_e32 v39, 1.0, v17
	v_add_f32_e32 v40, 1.0, v18
	v_add_f32_e32 v41, 1.0, v19
	v_rcp_f32_e32 v16, v20
	v_rcp_f32_e32 v17, v21
	v_rcp_f32_e32 v18, v22
	v_rcp_f32_e32 v19, v23
	v_rcp_f32_e32 v20, v33
	v_rcp_f32_e32 v21, v39
	v_rcp_f32_e32 v22, v40
	v_rcp_f32_e32 v23, v41
	v_pk_mul_f32 v[16:17], v[38:39], v[16:17] op_sel_hi:[0,1]
	v_pk_mul_f32 v[18:19], v[38:39], v[18:19] op_sel_hi:[0,1]
	v_pk_mul_f32 v[20:21], v[38:39], v[20:21] op_sel_hi:[0,1]
	v_pk_mul_f32 v[22:23], v[38:39], v[22:23] op_sel_hi:[0,1]
	v_pk_mul_f32 v[16:17], v[28:29], v[16:17]
	v_pk_mul_f32 v[18:19], v[30:31], v[18:19]
	v_pk_mul_f32 v[20:21], v[24:25], v[20:21]
	v_pk_mul_f32 v[22:23], v[26:27], v[22:23]
	v_cvt_pk_bf16_f32 v16, v16, v17
	v_cvt_pk_bf16_f32 v17, v18, v19
	v_cvt_pk_bf16_f32 v18, v20, v21
	v_cvt_pk_bf16_f32 v19, v22, v23
	global_store_dwordx4 v[34:35], v[16:19], off
	s_andn2_b64 vcc, exec, s[4:5]
	s_nop 1
	v_pk_mov_b32 v[16:17], v[212:213], v[212:213] op_sel:[0,1]
	v_pk_mov_b32 v[18:19], v[214:215], v[214:215] op_sel:[0,1]
	v_mov_b32_e32 v20, v17
	v_mov_b32_e32 v21, v18
	v_mov_b32_e32 v17, v19
	v_pk_add_f32 v[16:17], v[20:21], v[16:17]
	s_nop 0
	v_add_f32_e32 v16, v16, v17
	v_mov_b32_e32 v17, v16
	s_nop 1
	v_permlane16_swap_b32_e32 v16, v17
	s_waitcnt lgkmcnt(0)
	v_add_f32_e32 v16, v16, v17
	v_mov_b32_e32 v17, v16
	s_nop 1
	v_permlane32_swap_b32_e32 v16, v17
	s_waitcnt lgkmcnt(0)
	v_add_f32_e32 v16, v16, v17
	v_fmamk_f32 v16, v16, 0x3a800000, v162
	v_mul_f32_e32 v17, 0x4b800000, v16
	v_cmp_gt_f32_e64 s[0:1], s52, v16
	s_nop 1
	v_cndmask_b32_e64 v16, v16, v17, s[0:1]
	v_rsq_f32_e32 v18, v16
	v_mad_i64_i32 v[16:17], s[24:25], v32, s49, v[150:151]
	v_lshl_add_u64 v[16:17], v[16:17], 0, v[120:121]
	v_mul_f32_e32 v19, 0x45800000, v18
	v_cndmask_b32_e64 v18, v18, v19, s[0:1]
	v_mul_f32_e32 v19, 0xbfb8aa3b, v18
	v_mul_f32_e32 v4, v4, v19
	v_mul_f32_e32 v5, v5, v19
	v_mul_f32_e32 v6, v6, v19
	v_mul_f32_e32 v7, v7, v19
	v_mul_f32_e32 v0, v0, v19
	v_mul_f32_e32 v1, v1, v19
	v_mul_f32_e32 v2, v2, v19
	v_mul_f32_e32 v3, v3, v19
	v_exp_f32_e32 v4, v4
	v_exp_f32_e32 v5, v5
	v_exp_f32_e32 v6, v6
	v_exp_f32_e32 v7, v7
	v_exp_f32_e32 v0, v0
	v_exp_f32_e32 v1, v1
	v_exp_f32_e32 v2, v2
	v_exp_f32_e32 v3, v3
	v_add_f32_e32 v4, 1.0, v4
	v_add_f32_e32 v5, 1.0, v5
	v_add_f32_e32 v6, 1.0, v6
	v_add_f32_e32 v7, 1.0, v7
	v_add_f32_e32 v19, 1.0, v0
	v_add_f32_e32 v20, 1.0, v1
	v_add_f32_e32 v21, 1.0, v2
	v_add_f32_e32 v22, 1.0, v3
	v_rcp_f32_e32 v0, v4
	v_rcp_f32_e32 v1, v5
	v_rcp_f32_e32 v2, v6
	v_rcp_f32_e32 v3, v7
	v_rcp_f32_e32 v4, v19
	v_rcp_f32_e32 v5, v20
	v_rcp_f32_e32 v6, v21
	v_rcp_f32_e32 v7, v22
	v_mul_f32_e32 v18, v18, v18
	v_pk_mul_f32 v[0:1], v[18:19], v[0:1] op_sel_hi:[0,1]
	v_pk_mul_f32 v[2:3], v[18:19], v[2:3] op_sel_hi:[0,1]
	v_pk_mul_f32 v[4:5], v[18:19], v[4:5] op_sel_hi:[0,1]
	v_pk_mul_f32 v[6:7], v[18:19], v[6:7] op_sel_hi:[0,1]
	v_pk_mul_f32 v[0:1], v[12:13], v[0:1]
	v_pk_mul_f32 v[2:3], v[14:15], v[2:3]
	v_pk_mul_f32 v[4:5], v[8:9], v[4:5]
	v_pk_mul_f32 v[6:7], v[10:11], v[6:7]
	v_cvt_pk_bf16_f32 v0, v0, v1
	v_cvt_pk_bf16_f32 v1, v2, v3
	v_cvt_pk_bf16_f32 v2, v4, v5
	v_cvt_pk_bf16_f32 v3, v6, v7
	s_mov_b64 s[0:1], -1
	global_store_dwordx4 v[16:17], v[0:3], off
	s_cbranch_vccnz .LBB0_620
	s_andn2_b64 vcc, exec, s[8:9]
	s_cbranch_vccnz .LBB0_619
	s_barrier
	s_branch .LBB0_619

.LBB0_714:
	s_or_b64 exec, exec, s[26:27]
	v_or_b32_e32 v112, 16, v150
	s_waitcnt lgkmcnt(0)
	v_ashrrev_i32_e32 v113, 31, v112
	v_lshlrev_b64 v[114:115], 11, v[112:113]
	v_lshl_add_u64 v[114:115], s[14:15], 0, v[114:115]
	v_lshl_add_u64 v[122:123], v[148:149], 1, v[114:115]
	s_nop 1
	v_pk_mov_b32 v[114:115], v[184:185], v[184:185] op_sel:[0,1]
	v_pk_mov_b32 v[116:117], v[186:187], v[186:187] op_sel:[0,1]
	v_pk_mov_b32 v[118:119], v[188:189], v[188:189] op_sel:[0,1]
	v_pk_mov_b32 v[120:121], v[190:191], v[190:191] op_sel:[0,1]
	v_lshlrev_b32_e32 v124, 16, v114
	v_and_b32_e32 v125, 0xffff0000, v114
	v_lshlrev_b32_e32 v114, 16, v115
	v_and_b32_e32 v115, 0xffff0000, v115
	v_lshlrev_b32_e32 v126, 16, v116
	v_and_b32_e32 v127, 0xffff0000, v116
	v_lshlrev_b32_e32 v116, 16, v117
	v_and_b32_e32 v117, 0xffff0000, v117
	v_lshlrev_b32_e32 v162, 16, v118
	v_and_b32_e32 v163, 0xffff0000, v118
	v_lshlrev_b32_e32 v118, 16, v119
	v_and_b32_e32 v119, 0xffff0000, v119
	v_lshlrev_b32_e32 v164, 16, v120
	v_and_b32_e32 v165, 0xffff0000, v120
	v_lshlrev_b32_e32 v120, 16, v121
	v_and_b32_e32 v121, 0xffff0000, v121
	v_pk_add_f32 v[108:109], v[108:109], v[124:125]
	v_pk_add_f32 v[110:111], v[110:111], v[114:115]
	v_pk_add_f32 v[104:105], v[104:105], v[126:127]
	v_pk_add_f32 v[106:107], v[106:107], v[116:117]
	v_pk_add_f32 v[100:101], v[100:101], v[162:163]
	v_pk_add_f32 v[102:103], v[102:103], v[118:119]
	v_pk_add_f32 v[114:115], v[96:97], v[164:165]
	v_pk_add_f32 v[116:117], v[98:99], v[120:121]
	v_cvt_pk_bf16_f32 v96, v108, v109
	v_cvt_pk_bf16_f32 v97, v110, v111
	v_pk_mul_f32 v[98:99], v[108:109], v[108:109]
	v_pk_mul_f32 v[108:109], v[110:111], v[110:111]
	v_pk_mul_f32 v[110:111], v[104:105], v[104:105]
	v_pk_mul_f32 v[118:119], v[106:107], v[106:107]
	v_pk_mul_f32 v[120:121], v[100:101], v[100:101]
	v_pk_mul_f32 v[124:125], v[102:103], v[102:103]
	v_pk_mul_f32 v[126:127], v[114:115], v[114:115]
	v_pk_mul_f32 v[162:163], v[116:117], v[116:117]
	v_add_f32_e32 v126, v126, v127
	v_add_f32_e32 v151, v162, v163
	v_add_f32_e32 v124, v124, v125
	v_add_f32_e32 v120, v120, v121
	v_add_f32_e32 v118, v118, v119
	v_add_f32_e32 v110, v110, v111
	v_add_f32_e32 v108, v108, v109
	v_add_f32_e32 v98, v98, v99
	v_add_f32_e32 v99, v126, v151
	v_add_f32_e32 v109, v120, v124
	v_add_f32_e32 v110, v110, v118
	v_add_f32_e32 v98, v98, v108
	v_add_f32_e32 v99, v109, v99
	v_add_f32_e32 v98, v98, v110
	v_add_f32_e32 v108, v98, v99
	v_mov_b32_e32 v109, v108
	s_nop 1
	v_permlane16_swap_b32_e32 v108, v109
	v_cvt_pk_bf16_f32 v98, v104, v105
	v_cvt_pk_bf16_f32 v99, v106, v107
	global_store_dwordx4 v[122:123], v[96:99], off
	s_waitcnt lgkmcnt(0)
	s_nop 0
	v_add_f32_e32 v96, v108, v109
	v_mov_b32_e32 v97, v96
	s_nop 1
	v_permlane32_swap_b32_e32 v96, v97
	v_cvt_pk_bf16_f32 v98, v100, v101
	v_cvt_pk_bf16_f32 v99, v102, v103
	v_cvt_pk_bf16_f32 v100, v114, v115
	v_cvt_pk_bf16_f32 v101, v116, v117
	global_store_dwordx4 v[122:123], v[98:101], off offset:256
	s_and_saveexec_b64 s[26:27], s[4:5]
	s_cbranch_execz .LBB0_716
	v_lshlrev_b64 v[98:99], 6, v[112:113]
	v_lshl_add_u64 v[98:99], s[16:17], 0, v[98:99]
	v_lshl_add_u64 v[98:99], s[24:25], 2, v[98:99]
	s_lshl_b32 s10, s40, 2
	v_lshl_add_u64 v[98:99], v[98:99], 0, s[10:11]
	s_waitcnt lgkmcnt(0)
	v_add_f32_e32 v96, v96, v97
	global_store_dword v[98:99], v96, off
.LBB0_716:
	s_or_b64 exec, exec, s[26:27]
	v_or_b32_e32 v96, 32, v150
	s_waitcnt lgkmcnt(0)
	v_ashrrev_i32_e32 v97, 31, v96
	v_lshlrev_b64 v[98:99], 11, v[96:97]
	v_lshl_add_u64 v[98:99], s[14:15], 0, v[98:99]
	v_lshl_add_u64 v[106:107], v[148:149], 1, v[98:99]
	s_nop 1
	v_pk_mov_b32 v[98:99], v[192:193], v[192:193] op_sel:[0,1]
	v_pk_mov_b32 v[100:101], v[194:195], v[194:195] op_sel:[0,1]
	v_pk_mov_b32 v[102:103], v[196:197], v[196:197] op_sel:[0,1]
	v_pk_mov_b32 v[104:105], v[198:199], v[198:199] op_sel:[0,1]
	v_lshlrev_b32_e32 v108, 16, v98
	v_and_b32_e32 v109, 0xffff0000, v98
	v_lshlrev_b32_e32 v98, 16, v99
	v_and_b32_e32 v99, 0xffff0000, v99
	v_lshlrev_b32_e32 v110, 16, v100
	v_and_b32_e32 v111, 0xffff0000, v100
	v_lshlrev_b32_e32 v100, 16, v101
	v_and_b32_e32 v101, 0xffff0000, v101
	v_lshlrev_b32_e32 v112, 16, v102
	v_and_b32_e32 v113, 0xffff0000, v102
	v_lshlrev_b32_e32 v102, 16, v103
	v_and_b32_e32 v103, 0xffff0000, v103
	v_lshlrev_b32_e32 v114, 16, v104
	v_and_b32_e32 v115, 0xffff0000, v104
	v_lshlrev_b32_e32 v104, 16, v105
	v_and_b32_e32 v105, 0xffff0000, v105
	v_pk_add_f32 v[92:93], v[92:93], v[108:109]
	v_pk_add_f32 v[94:95], v[94:95], v[98:99]
	v_pk_add_f32 v[88:89], v[88:89], v[110:111]
	v_pk_add_f32 v[90:91], v[90:91], v[100:101]
	v_pk_add_f32 v[84:85], v[84:85], v[112:113]
	v_pk_add_f32 v[86:87], v[86:87], v[102:103]
	v_pk_add_f32 v[98:99], v[80:81], v[114:115]
	v_pk_add_f32 v[100:101], v[82:83], v[104:105]
	v_cvt_pk_bf16_f32 v80, v92, v93
	v_cvt_pk_bf16_f32 v81, v94, v95
	v_pk_mul_f32 v[82:83], v[92:93], v[92:93]
	v_pk_mul_f32 v[92:93], v[94:95], v[94:95]
	v_pk_mul_f32 v[94:95], v[88:89], v[88:89]
	v_pk_mul_f32 v[102:103], v[90:91], v[90:91]
	v_pk_mul_f32 v[104:105], v[84:85], v[84:85]
	v_pk_mul_f32 v[108:109], v[86:87], v[86:87]
	v_pk_mul_f32 v[110:111], v[98:99], v[98:99]
	v_pk_mul_f32 v[112:113], v[100:101], v[100:101]
	v_add_f32_e32 v110, v110, v111
	v_add_f32_e32 v112, v112, v113
	v_add_f32_e32 v108, v108, v109
	v_add_f32_e32 v104, v104, v105
	v_add_f32_e32 v102, v102, v103
	v_add_f32_e32 v94, v94, v95
	v_add_f32_e32 v92, v92, v93
	v_add_f32_e32 v82, v82, v83
	v_add_f32_e32 v83, v110, v112
	v_add_f32_e32 v93, v104, v108
	v_add_f32_e32 v94, v94, v102
	v_add_f32_e32 v82, v82, v92
	v_add_f32_e32 v83, v93, v83
	v_add_f32_e32 v82, v82, v94
	v_add_f32_e32 v92, v82, v83
	v_mov_b32_e32 v93, v92
	s_nop 1
	v_permlane16_swap_b32_e32 v92, v93
	v_cvt_pk_bf16_f32 v82, v88, v89
	v_cvt_pk_bf16_f32 v83, v90, v91
	global_store_dwordx4 v[106:107], v[80:83], off
	s_waitcnt lgkmcnt(0)
	s_nop 0
	v_add_f32_e32 v80, v92, v93
	v_mov_b32_e32 v81, v80
	s_nop 1
	v_permlane32_swap_b32_e32 v80, v81
	v_cvt_pk_bf16_f32 v82, v84, v85
	v_cvt_pk_bf16_f32 v83, v86, v87
	v_cvt_pk_bf16_f32 v84, v98, v99
	v_cvt_pk_bf16_f32 v85, v100, v101
	global_store_dwordx4 v[106:107], v[82:85], off offset:256
	s_and_saveexec_b64 s[26:27], s[4:5]
	s_cbranch_execz .LBB0_718
	v_lshlrev_b64 v[82:83], 6, v[96:97]
	v_lshl_add_u64 v[82:83], s[16:17], 0, v[82:83]
	v_lshl_add_u64 v[82:83], s[24:25], 2, v[82:83]
	s_lshl_b32 s10, s40, 2
	v_lshl_add_u64 v[82:83], v[82:83], 0, s[10:11]
	s_waitcnt lgkmcnt(0)
	v_add_f32_e32 v80, v80, v81
	global_store_dword v[82:83], v80, off
.LBB0_718:
	s_or_b64 exec, exec, s[26:27]
	v_or_b32_e32 v80, 48, v150
	s_waitcnt lgkmcnt(0)
	v_ashrrev_i32_e32 v81, 31, v80
	v_lshlrev_b64 v[82:83], 11, v[80:81]
	v_lshl_add_u64 v[82:83], s[14:15], 0, v[82:83]
	v_lshl_add_u64 v[90:91], v[148:149], 1, v[82:83]
	s_nop 1
	v_pk_mov_b32 v[82:83], v[200:201], v[200:201] op_sel:[0,1]
	v_pk_mov_b32 v[84:85], v[202:203], v[202:203] op_sel:[0,1]
	v_pk_mov_b32 v[86:87], v[204:205], v[204:205] op_sel:[0,1]
	v_pk_mov_b32 v[88:89], v[206:207], v[206:207] op_sel:[0,1]
	v_lshlrev_b32_e32 v92, 16, v82
	v_and_b32_e32 v93, 0xffff0000, v82
	v_lshlrev_b32_e32 v82, 16, v83
	v_and_b32_e32 v83, 0xffff0000, v83
	v_lshlrev_b32_e32 v94, 16, v84
	v_and_b32_e32 v95, 0xffff0000, v84
	v_lshlrev_b32_e32 v84, 16, v85
	v_and_b32_e32 v85, 0xffff0000, v85
	v_lshlrev_b32_e32 v96, 16, v86
	v_and_b32_e32 v97, 0xffff0000, v86
	v_lshlrev_b32_e32 v86, 16, v87
	v_and_b32_e32 v87, 0xffff0000, v87
	v_lshlrev_b32_e32 v98, 16, v88
	v_and_b32_e32 v99, 0xffff0000, v88
	v_lshlrev_b32_e32 v88, 16, v89
	v_and_b32_e32 v89, 0xffff0000, v89
	v_pk_add_f32 v[76:77], v[76:77], v[92:93]
	v_pk_add_f32 v[78:79], v[78:79], v[82:83]
	v_pk_add_f32 v[72:73], v[72:73], v[94:95]
	v_pk_add_f32 v[74:75], v[74:75], v[84:85]
	v_pk_add_f32 v[68:69], v[68:69], v[96:97]
	v_pk_add_f32 v[70:71], v[70:71], v[86:87]
	v_pk_add_f32 v[82:83], v[64:65], v[98:99]
	v_pk_add_f32 v[84:85], v[66:67], v[88:89]
	v_cvt_pk_bf16_f32 v64, v76, v77
	v_cvt_pk_bf16_f32 v65, v78, v79
	v_pk_mul_f32 v[66:67], v[76:77], v[76:77]
	v_pk_mul_f32 v[76:77], v[78:79], v[78:79]
	v_pk_mul_f32 v[78:79], v[72:73], v[72:73]
	v_pk_mul_f32 v[86:87], v[74:75], v[74:75]
	v_pk_mul_f32 v[88:89], v[68:69], v[68:69]
	v_pk_mul_f32 v[92:93], v[70:71], v[70:71]
	v_pk_mul_f32 v[94:95], v[82:83], v[82:83]
	v_pk_mul_f32 v[96:97], v[84:85], v[84:85]
	v_add_f32_e32 v94, v94, v95
	v_add_f32_e32 v96, v96, v97
	v_add_f32_e32 v92, v92, v93
	v_add_f32_e32 v88, v88, v89
	v_add_f32_e32 v86, v86, v87
	v_add_f32_e32 v78, v78, v79
	v_add_f32_e32 v76, v76, v77
	v_add_f32_e32 v66, v66, v67
	v_add_f32_e32 v67, v94, v96
	v_add_f32_e32 v77, v88, v92
	v_add_f32_e32 v78, v78, v86
	v_add_f32_e32 v66, v66, v76
	v_add_f32_e32 v67, v77, v67
	v_add_f32_e32 v66, v66, v78
	v_add_f32_e32 v76, v66, v67
	v_mov_b32_e32 v77, v76
	s_nop 1
	v_permlane16_swap_b32_e32 v76, v77
	v_cvt_pk_bf16_f32 v66, v72, v73
	v_cvt_pk_bf16_f32 v67, v74, v75
	global_store_dwordx4 v[90:91], v[64:67], off
	s_waitcnt lgkmcnt(0)
	s_nop 0
	v_add_f32_e32 v64, v76, v77
	v_mov_b32_e32 v65, v64
	s_nop 1
	v_permlane32_swap_b32_e32 v64, v65
	v_cvt_pk_bf16_f32 v66, v68, v69
	v_cvt_pk_bf16_f32 v67, v70, v71
	v_cvt_pk_bf16_f32 v68, v82, v83
	v_cvt_pk_bf16_f32 v69, v84, v85
	global_store_dwordx4 v[90:91], v[66:69], off offset:256
	s_and_saveexec_b64 s[26:27], s[4:5]
	s_cbranch_execz .LBB0_720
	v_lshlrev_b64 v[66:67], 6, v[80:81]
	v_lshl_add_u64 v[66:67], s[16:17], 0, v[66:67]
	v_lshl_add_u64 v[66:67], s[24:25], 2, v[66:67]
	s_lshl_b32 s10, s40, 2
	v_lshl_add_u64 v[66:67], v[66:67], 0, s[10:11]
	s_waitcnt lgkmcnt(0)
	v_add_f32_e32 v64, v64, v65
	global_store_dword v[66:67], v64, off
.LBB0_720:
	s_or_b64 exec, exec, s[26:27]
	v_add_u32_e32 v64, 0x80, v150
	s_waitcnt lgkmcnt(0)
	v_ashrrev_i32_e32 v65, 31, v64
	v_lshlrev_b64 v[66:67], 11, v[64:65]
	v_lshl_add_u64 v[66:67], s[14:15], 0, v[66:67]
	v_lshl_add_u64 v[74:75], v[148:149], 1, v[66:67]
	s_nop 1
	v_pk_mov_b32 v[66:67], v[208:209], v[208:209] op_sel:[0,1]
	v_pk_mov_b32 v[68:69], v[210:211], v[210:211] op_sel:[0,1]
	v_pk_mov_b32 v[70:71], v[212:213], v[212:213] op_sel:[0,1]
	v_pk_mov_b32 v[72:73], v[214:215], v[214:215] op_sel:[0,1]
	v_lshlrev_b32_e32 v76, 16, v66
	v_and_b32_e32 v77, 0xffff0000, v66
	v_lshlrev_b32_e32 v66, 16, v67
	v_and_b32_e32 v67, 0xffff0000, v67
	v_lshlrev_b32_e32 v78, 16, v68
	v_and_b32_e32 v79, 0xffff0000, v68
	v_lshlrev_b32_e32 v68, 16, v69
	v_and_b32_e32 v69, 0xffff0000, v69
	v_lshlrev_b32_e32 v80, 16, v70
	v_and_b32_e32 v81, 0xffff0000, v70
	v_lshlrev_b32_e32 v70, 16, v71
	v_and_b32_e32 v71, 0xffff0000, v71
	v_lshlrev_b32_e32 v82, 16, v72
	v_and_b32_e32 v83, 0xffff0000, v72
	v_lshlrev_b32_e32 v72, 16, v73
	v_and_b32_e32 v73, 0xffff0000, v73
	v_pk_add_f32 v[60:61], v[60:61], v[76:77]
	v_pk_add_f32 v[62:63], v[62:63], v[66:67]
	v_pk_add_f32 v[56:57], v[56:57], v[78:79]
	v_pk_add_f32 v[58:59], v[58:59], v[68:69]
	v_pk_add_f32 v[52:53], v[52:53], v[80:81]
	v_pk_add_f32 v[54:55], v[54:55], v[70:71]
	v_pk_add_f32 v[66:67], v[48:49], v[82:83]
	v_pk_add_f32 v[68:69], v[50:51], v[72:73]
	v_cvt_pk_bf16_f32 v48, v60, v61
	v_cvt_pk_bf16_f32 v49, v62, v63
	v_pk_mul_f32 v[50:51], v[60:61], v[60:61]
	v_pk_mul_f32 v[60:61], v[62:63], v[62:63]
	v_pk_mul_f32 v[62:63], v[56:57], v[56:57]
	v_pk_mul_f32 v[70:71], v[58:59], v[58:59]
	v_pk_mul_f32 v[72:73], v[52:53], v[52:53]
	v_pk_mul_f32 v[76:77], v[54:55], v[54:55]
	v_pk_mul_f32 v[78:79], v[66:67], v[66:67]
	v_pk_mul_f32 v[80:81], v[68:69], v[68:69]
	v_add_f32_e32 v78, v78, v79
	v_add_f32_e32 v80, v80, v81
	v_add_f32_e32 v76, v76, v77
	v_add_f32_e32 v72, v72, v73
	v_add_f32_e32 v70, v70, v71
	v_add_f32_e32 v62, v62, v63
	v_add_f32_e32 v60, v60, v61
	v_add_f32_e32 v50, v50, v51
	v_add_f32_e32 v51, v78, v80
	v_add_f32_e32 v61, v72, v76
	v_add_f32_e32 v62, v62, v70
	v_add_f32_e32 v50, v50, v60
	v_add_f32_e32 v51, v61, v51
	v_add_f32_e32 v50, v50, v62
	v_add_f32_e32 v60, v50, v51
	v_mov_b32_e32 v61, v60
	s_nop 1
	v_permlane16_swap_b32_e32 v60, v61
	v_cvt_pk_bf16_f32 v50, v56, v57
	v_cvt_pk_bf16_f32 v51, v58, v59
	global_store_dwordx4 v[74:75], v[48:51], off
	s_waitcnt lgkmcnt(0)
	s_nop 0
	v_add_f32_e32 v48, v60, v61
	v_mov_b32_e32 v49, v48
	s_nop 1
	v_permlane32_swap_b32_e32 v48, v49
	v_cvt_pk_bf16_f32 v50, v52, v53
	v_cvt_pk_bf16_f32 v51, v54, v55
	v_cvt_pk_bf16_f32 v52, v66, v67
	v_cvt_pk_bf16_f32 v53, v68, v69
	global_store_dwordx4 v[74:75], v[50:53], off offset:256
	s_and_saveexec_b64 s[26:27], s[4:5]
	s_cbranch_execz .LBB0_722
	v_lshlrev_b64 v[50:51], 6, v[64:65]
	v_lshl_add_u64 v[50:51], s[16:17], 0, v[50:51]
	v_lshl_add_u64 v[50:51], s[24:25], 2, v[50:51]
	s_lshl_b32 s10, s40, 2
	v_lshl_add_u64 v[50:51], v[50:51], 0, s[10:11]
	s_waitcnt lgkmcnt(0)
	v_add_f32_e32 v48, v48, v49
	global_store_dword v[50:51], v48, off
.LBB0_722:
	s_or_b64 exec, exec, s[26:27]
	v_add_u32_e32 v48, 0x90, v150
	s_waitcnt lgkmcnt(0)
	v_ashrrev_i32_e32 v49, 31, v48
	v_lshlrev_b64 v[50:51], 11, v[48:49]
	v_lshl_add_u64 v[50:51], s[14:15], 0, v[50:51]
	v_lshl_add_u64 v[58:59], v[148:149], 1, v[50:51]
	s_nop 1
	v_pk_mov_b32 v[50:51], v[216:217], v[216:217] op_sel:[0,1]
	v_pk_mov_b32 v[52:53], v[218:219], v[218:219] op_sel:[0,1]
	v_pk_mov_b32 v[54:55], v[220:221], v[220:221] op_sel:[0,1]
	v_pk_mov_b32 v[56:57], v[222:223], v[222:223] op_sel:[0,1]
	v_lshlrev_b32_e32 v60, 16, v50
	v_and_b32_e32 v61, 0xffff0000, v50
	v_lshlrev_b32_e32 v50, 16, v51
	v_and_b32_e32 v51, 0xffff0000, v51
	v_lshlrev_b32_e32 v62, 16, v52
	v_and_b32_e32 v63, 0xffff0000, v52
	v_lshlrev_b32_e32 v52, 16, v53
	v_and_b32_e32 v53, 0xffff0000, v53
	v_lshlrev_b32_e32 v64, 16, v54
	v_and_b32_e32 v65, 0xffff0000, v54
	v_lshlrev_b32_e32 v54, 16, v55
	v_and_b32_e32 v55, 0xffff0000, v55
	v_lshlrev_b32_e32 v66, 16, v56
	v_and_b32_e32 v67, 0xffff0000, v56
	v_lshlrev_b32_e32 v56, 16, v57
	v_and_b32_e32 v57, 0xffff0000, v57
	v_pk_add_f32 v[44:45], v[44:45], v[60:61]
	v_pk_add_f32 v[46:47], v[46:47], v[50:51]
	v_pk_add_f32 v[40:41], v[40:41], v[62:63]
	v_pk_add_f32 v[42:43], v[42:43], v[52:53]
	v_pk_add_f32 v[36:37], v[36:37], v[64:65]
	v_pk_add_f32 v[38:39], v[38:39], v[54:55]
	v_pk_add_f32 v[50:51], v[32:33], v[66:67]
	v_pk_add_f32 v[52:53], v[34:35], v[56:57]
	v_cvt_pk_bf16_f32 v32, v44, v45
	v_cvt_pk_bf16_f32 v33, v46, v47
	v_pk_mul_f32 v[34:35], v[44:45], v[44:45]
	v_pk_mul_f32 v[44:45], v[46:47], v[46:47]
	v_pk_mul_f32 v[46:47], v[40:41], v[40:41]
	v_pk_mul_f32 v[54:55], v[42:43], v[42:43]
	v_pk_mul_f32 v[56:57], v[36:37], v[36:37]
	v_pk_mul_f32 v[60:61], v[38:39], v[38:39]
	v_pk_mul_f32 v[62:63], v[50:51], v[50:51]
	v_pk_mul_f32 v[64:65], v[52:53], v[52:53]
	v_add_f32_e32 v62, v62, v63
	v_add_f32_e32 v64, v64, v65
	v_add_f32_e32 v60, v60, v61
	v_add_f32_e32 v56, v56, v57
	v_add_f32_e32 v54, v54, v55
	v_add_f32_e32 v46, v46, v47
	v_add_f32_e32 v44, v44, v45
	v_add_f32_e32 v34, v34, v35
	v_add_f32_e32 v35, v62, v64
	v_add_f32_e32 v45, v56, v60
	v_add_f32_e32 v46, v46, v54
	v_add_f32_e32 v34, v34, v44
	v_add_f32_e32 v35, v45, v35
	v_add_f32_e32 v34, v34, v46
	v_add_f32_e32 v44, v34, v35
	v_mov_b32_e32 v45, v44
	s_nop 1
	v_permlane16_swap_b32_e32 v44, v45
	v_cvt_pk_bf16_f32 v34, v40, v41
	v_cvt_pk_bf16_f32 v35, v42, v43
	global_store_dwordx4 v[58:59], v[32:35], off
	s_waitcnt lgkmcnt(0)
	s_nop 0
	v_add_f32_e32 v32, v44, v45
	v_mov_b32_e32 v33, v32
	s_nop 1
	v_permlane32_swap_b32_e32 v32, v33
	v_cvt_pk_bf16_f32 v34, v36, v37
	v_cvt_pk_bf16_f32 v35, v38, v39
	v_cvt_pk_bf16_f32 v36, v50, v51
	v_cvt_pk_bf16_f32 v37, v52, v53
	global_store_dwordx4 v[58:59], v[34:37], off offset:256
	s_and_saveexec_b64 s[26:27], s[4:5]
	s_cbranch_execz .LBB0_724
	v_lshlrev_b64 v[34:35], 6, v[48:49]
	v_lshl_add_u64 v[34:35], s[16:17], 0, v[34:35]
	v_lshl_add_u64 v[34:35], s[24:25], 2, v[34:35]
	s_lshl_b32 s10, s40, 2
	v_lshl_add_u64 v[34:35], v[34:35], 0, s[10:11]
	s_waitcnt lgkmcnt(0)
	v_add_f32_e32 v32, v32, v33
	global_store_dword v[34:35], v32, off
.LBB0_724:
	s_or_b64 exec, exec, s[26:27]
	v_add_u32_e32 v32, 0xa0, v150
	s_waitcnt lgkmcnt(0)
	v_ashrrev_i32_e32 v33, 31, v32
	v_lshlrev_b64 v[34:35], 11, v[32:33]
	v_lshl_add_u64 v[34:35], s[14:15], 0, v[34:35]
	v_lshl_add_u64 v[42:43], v[148:149], 1, v[34:35]
	s_nop 1
	v_pk_mov_b32 v[34:35], v[224:225], v[224:225] op_sel:[0,1]
	v_pk_mov_b32 v[36:37], v[226:227], v[226:227] op_sel:[0,1]
	v_pk_mov_b32 v[38:39], v[228:229], v[228:229] op_sel:[0,1]
	v_pk_mov_b32 v[40:41], v[230:231], v[230:231] op_sel:[0,1]
	v_lshlrev_b32_e32 v44, 16, v34
	v_and_b32_e32 v45, 0xffff0000, v34
	v_lshlrev_b32_e32 v34, 16, v35
	v_and_b32_e32 v35, 0xffff0000, v35
	v_lshlrev_b32_e32 v46, 16, v36
	v_and_b32_e32 v47, 0xffff0000, v36
	v_lshlrev_b32_e32 v36, 16, v37
	v_and_b32_e32 v37, 0xffff0000, v37
	v_lshlrev_b32_e32 v48, 16, v38
	v_and_b32_e32 v49, 0xffff0000, v38
	v_lshlrev_b32_e32 v38, 16, v39
	v_and_b32_e32 v39, 0xffff0000, v39
	v_lshlrev_b32_e32 v50, 16, v40
	v_and_b32_e32 v51, 0xffff0000, v40
	v_lshlrev_b32_e32 v40, 16, v41
	v_and_b32_e32 v41, 0xffff0000, v41
	v_pk_add_f32 v[28:29], v[28:29], v[44:45]
	v_pk_add_f32 v[30:31], v[30:31], v[34:35]
	v_pk_add_f32 v[24:25], v[24:25], v[46:47]
	v_pk_add_f32 v[26:27], v[26:27], v[36:37]
	v_pk_add_f32 v[20:21], v[20:21], v[48:49]
	v_pk_add_f32 v[22:23], v[22:23], v[38:39]
	v_pk_add_f32 v[34:35], v[16:17], v[50:51]
	v_pk_add_f32 v[36:37], v[18:19], v[40:41]
	v_cvt_pk_bf16_f32 v16, v28, v29
	v_cvt_pk_bf16_f32 v17, v30, v31
	v_pk_mul_f32 v[18:19], v[28:29], v[28:29]
	v_pk_mul_f32 v[28:29], v[30:31], v[30:31]
	v_pk_mul_f32 v[30:31], v[24:25], v[24:25]
	v_pk_mul_f32 v[38:39], v[26:27], v[26:27]
	v_pk_mul_f32 v[40:41], v[20:21], v[20:21]
	v_pk_mul_f32 v[44:45], v[22:23], v[22:23]
	v_pk_mul_f32 v[46:47], v[34:35], v[34:35]
	v_pk_mul_f32 v[48:49], v[36:37], v[36:37]
	v_add_f32_e32 v46, v46, v47
	v_add_f32_e32 v48, v48, v49
	v_add_f32_e32 v44, v44, v45
	v_add_f32_e32 v40, v40, v41
	v_add_f32_e32 v38, v38, v39
	v_add_f32_e32 v30, v30, v31
	v_add_f32_e32 v28, v28, v29
	v_add_f32_e32 v18, v18, v19
	v_add_f32_e32 v19, v46, v48
	v_add_f32_e32 v29, v40, v44
	v_add_f32_e32 v30, v30, v38
	v_add_f32_e32 v18, v18, v28
	v_add_f32_e32 v19, v29, v19
	v_add_f32_e32 v18, v18, v30
	v_add_f32_e32 v28, v18, v19
	v_mov_b32_e32 v29, v28
	s_nop 1
	v_permlane16_swap_b32_e32 v28, v29
	v_cvt_pk_bf16_f32 v18, v24, v25
	v_cvt_pk_bf16_f32 v19, v26, v27
	global_store_dwordx4 v[42:43], v[16:19], off
	s_waitcnt lgkmcnt(0)
	s_nop 0
	v_add_f32_e32 v16, v28, v29
	v_mov_b32_e32 v17, v16
	s_nop 1
	v_permlane32_swap_b32_e32 v16, v17
	v_cvt_pk_bf16_f32 v18, v20, v21
	v_cvt_pk_bf16_f32 v19, v22, v23
	v_cvt_pk_bf16_f32 v20, v34, v35
	v_cvt_pk_bf16_f32 v21, v36, v37
	global_store_dwordx4 v[42:43], v[18:21], off offset:256
	s_and_saveexec_b64 s[26:27], s[4:5]
	s_cbranch_execz .LBB0_726
	v_lshlrev_b64 v[18:19], 6, v[32:33]
	v_lshl_add_u64 v[18:19], s[16:17], 0, v[18:19]
	v_lshl_add_u64 v[18:19], s[24:25], 2, v[18:19]
	s_lshl_b32 s10, s40, 2
	v_lshl_add_u64 v[18:19], v[18:19], 0, s[10:11]
	s_waitcnt lgkmcnt(0)
	v_add_f32_e32 v16, v16, v17
	global_store_dword v[18:19], v16, off
.LBB0_726:
	s_or_b64 exec, exec, s[26:27]
	v_add_u32_e32 v16, 0xb0, v150
	s_waitcnt lgkmcnt(0)
	v_ashrrev_i32_e32 v17, 31, v16
	v_lshlrev_b64 v[18:19], 11, v[16:17]
	v_lshl_add_u64 v[18:19], s[14:15], 0, v[18:19]
	v_lshl_add_u64 v[26:27], v[148:149], 1, v[18:19]
	s_nop 1
	v_pk_mov_b32 v[18:19], v[238:239], v[238:239] op_sel:[0,1]
	v_pk_mov_b32 v[20:21], v[240:241], v[240:241] op_sel:[0,1]
	v_pk_mov_b32 v[22:23], v[242:243], v[242:243] op_sel:[0,1]
	v_pk_mov_b32 v[24:25], v[244:245], v[244:245] op_sel:[0,1]
	v_lshlrev_b32_e32 v28, 16, v18
	v_and_b32_e32 v29, 0xffff0000, v18
	v_lshlrev_b32_e32 v18, 16, v19
	v_and_b32_e32 v19, 0xffff0000, v19
	v_lshlrev_b32_e32 v30, 16, v20
	v_and_b32_e32 v31, 0xffff0000, v20
	v_lshlrev_b32_e32 v20, 16, v21
	v_and_b32_e32 v21, 0xffff0000, v21
	v_lshlrev_b32_e32 v32, 16, v22
	v_and_b32_e32 v33, 0xffff0000, v22
	v_lshlrev_b32_e32 v22, 16, v23
	v_and_b32_e32 v23, 0xffff0000, v23
	v_lshlrev_b32_e32 v34, 16, v24
	v_and_b32_e32 v35, 0xffff0000, v24
	v_lshlrev_b32_e32 v24, 16, v25
	v_and_b32_e32 v25, 0xffff0000, v25
	v_pk_add_f32 v[12:13], v[12:13], v[28:29]
	v_pk_add_f32 v[14:15], v[14:15], v[18:19]
	v_pk_add_f32 v[8:9], v[8:9], v[30:31]
	v_pk_add_f32 v[10:11], v[10:11], v[20:21]
	v_pk_add_f32 v[4:5], v[4:5], v[32:33]
	v_pk_add_f32 v[6:7], v[6:7], v[22:23]
	v_pk_add_f32 v[18:19], v[0:1], v[34:35]
	v_pk_add_f32 v[20:21], v[2:3], v[24:25]
	v_cvt_pk_bf16_f32 v0, v12, v13
	v_cvt_pk_bf16_f32 v1, v14, v15
	v_pk_mul_f32 v[2:3], v[12:13], v[12:13]
	v_pk_mul_f32 v[12:13], v[14:15], v[14:15]
	v_pk_mul_f32 v[14:15], v[8:9], v[8:9]
	v_pk_mul_f32 v[22:23], v[10:11], v[10:11]
	v_pk_mul_f32 v[24:25], v[4:5], v[4:5]
	v_pk_mul_f32 v[28:29], v[6:7], v[6:7]
	v_pk_mul_f32 v[30:31], v[18:19], v[18:19]
	v_pk_mul_f32 v[32:33], v[20:21], v[20:21]
	v_add_f32_e32 v30, v30, v31
	v_add_f32_e32 v32, v32, v33
	v_add_f32_e32 v28, v28, v29
	v_add_f32_e32 v24, v24, v25
	v_add_f32_e32 v22, v22, v23
	v_add_f32_e32 v14, v14, v15
	v_add_f32_e32 v12, v12, v13
	v_add_f32_e32 v2, v2, v3
	v_add_f32_e32 v3, v30, v32
	v_add_f32_e32 v13, v24, v28
	v_add_f32_e32 v14, v14, v22
	v_add_f32_e32 v2, v2, v12
	v_add_f32_e32 v3, v13, v3
	v_add_f32_e32 v2, v2, v14
	v_add_f32_e32 v12, v2, v3
	v_mov_b32_e32 v13, v12
	s_nop 1
	v_permlane16_swap_b32_e32 v12, v13
	v_cvt_pk_bf16_f32 v2, v8, v9
	v_cvt_pk_bf16_f32 v3, v10, v11
	global_store_dwordx4 v[26:27], v[0:3], off
	s_waitcnt lgkmcnt(0)
	s_nop 0
	v_add_f32_e32 v0, v12, v13
	v_mov_b32_e32 v1, v0
	s_nop 1
	v_permlane32_swap_b32_e32 v0, v1
	v_cvt_pk_bf16_f32 v2, v4, v5
	v_cvt_pk_bf16_f32 v3, v6, v7
	v_cvt_pk_bf16_f32 v4, v18, v19
	v_cvt_pk_bf16_f32 v5, v20, v21
	global_store_dwordx4 v[26:27], v[2:5], off offset:256
	s_and_saveexec_b64 s[26:27], s[4:5]
	s_cbranch_execz .LBB0_728
	v_lshlrev_b64 v[2:3], 6, v[16:17]
	v_lshl_add_u64 v[2:3], s[16:17], 0, v[2:3]
	v_lshl_add_u64 v[2:3], s[24:25], 2, v[2:3]
	s_lshl_b32 s10, s40, 2
	v_lshl_add_u64 v[2:3], v[2:3], 0, s[10:11]
	s_waitcnt lgkmcnt(0)
	v_add_f32_e32 v0, v0, v1
	global_store_dword v[2:3], v0, off

.LBB0_813:
	s_or_b64 exec, exec, s[0:1]
	s_nop 0
	v_or_b32_e32 v116, 16, v150
	v_ashrrev_i32_e32 v117, 31, v116
	v_lshlrev_b64 v[112:113], 6, v[116:117]
	v_lshl_add_u64 v[112:113], v[140:141], 0, v[112:113]
	s_nop 1
	v_pk_mov_b32 v[112:113], v[188:189], v[188:189] op_sel:[0,1]
	v_pk_mov_b32 v[114:115], v[190:191], v[190:191] op_sel:[0,1]
	v_mov_b32_e32 v118, v113
	v_mov_b32_e32 v119, v114
	v_mov_b32_e32 v113, v115
	v_pk_add_f32 v[112:113], v[118:119], v[112:113]
	s_nop 0
	v_add_f32_e32 v112, v112, v113
	v_mov_b32_e32 v113, v112
	s_nop 1
	v_permlane16_swap_b32_e32 v112, v113
	s_waitcnt lgkmcnt(0)
	v_add_f32_e32 v112, v112, v113
	v_mov_b32_e32 v113, v112
	s_nop 1
	v_permlane32_swap_b32_e32 v112, v113
	s_waitcnt lgkmcnt(0)
	v_add_f32_e32 v112, v112, v113
	v_fmamk_f32 v112, v112, 0x3a800000, v166
	v_mul_f32_e32 v113, 0x4b800000, v112
	v_cmp_gt_f32_e64 s[0:1], s52, v112
	s_nop 1
	v_cndmask_b32_e64 v112, v112, v113, s[0:1]
	v_rsq_f32_e32 v114, v112
	v_lshlrev_b64 v[112:113], 12, v[116:117]
	v_lshl_add_u64 v[112:113], s[12:13], 0, v[112:113]
	v_lshl_add_u64 v[112:113], v[152:153], 1, v[112:113]
	v_mul_f32_e32 v115, 0x45800000, v114
	v_cndmask_b32_e64 v114, v114, v115, s[0:1]
	v_mov_b32_e32 v115, v114
	s_and_saveexec_b64 s[0:1], vcc
	s_cbranch_execz .LBB0_815
	v_mov_b32_e32 v116, v114
	v_mov_b32_e32 v117, v114
	v_pk_mul_f32 v[110:111], v[110:111], v[116:117]
	v_pk_mul_f32 v[108:109], v[108:109], v[114:115]
	v_pk_mul_f32 v[106:107], v[106:107], v[116:117]
	v_pk_mul_f32 v[104:105], v[104:105], v[114:115]
	v_cvt_pk_bf16_f32 v108, v108, v109
	v_cvt_pk_bf16_f32 v109, v110, v111
	v_cvt_pk_bf16_f32 v110, v104, v105
	v_cvt_pk_bf16_f32 v111, v106, v107
	global_store_dwordx4 v[112:113], v[108:111], off

.LBB0_817:
	s_or_b64 exec, exec, s[0:1]
	s_nop 0
	v_or_b32_e32 v100, 32, v150
	v_ashrrev_i32_e32 v101, 31, v100
	v_lshlrev_b64 v[96:97], 6, v[100:101]
	v_lshl_add_u64 v[96:97], v[140:141], 0, v[96:97]
	s_nop 1
	v_pk_mov_b32 v[96:97], v[192:193], v[192:193] op_sel:[0,1]
	v_pk_mov_b32 v[98:99], v[194:195], v[194:195] op_sel:[0,1]
	v_mov_b32_e32 v102, v97
	v_mov_b32_e32 v103, v98
	v_mov_b32_e32 v97, v99
	v_pk_add_f32 v[96:97], v[102:103], v[96:97]
	s_nop 0
	v_add_f32_e32 v96, v96, v97
	v_mov_b32_e32 v97, v96
	s_nop 1
	v_permlane16_swap_b32_e32 v96, v97
	s_waitcnt lgkmcnt(0)
	v_add_f32_e32 v96, v96, v97
	v_mov_b32_e32 v97, v96
	s_nop 1
	v_permlane32_swap_b32_e32 v96, v97
	s_waitcnt lgkmcnt(0)
	v_add_f32_e32 v96, v96, v97
	v_fmamk_f32 v96, v96, 0x3a800000, v166
	v_mul_f32_e32 v97, 0x4b800000, v96
	v_cmp_gt_f32_e64 s[0:1], s52, v96
	s_nop 1
	v_cndmask_b32_e64 v96, v96, v97, s[0:1]
	v_rsq_f32_e32 v98, v96
	v_lshlrev_b64 v[96:97], 12, v[100:101]
	v_lshl_add_u64 v[96:97], s[12:13], 0, v[96:97]
	v_lshl_add_u64 v[96:97], v[152:153], 1, v[96:97]
	v_mul_f32_e32 v99, 0x45800000, v98
	v_cndmask_b32_e64 v98, v98, v99, s[0:1]
	v_mov_b32_e32 v99, v98
	s_and_saveexec_b64 s[0:1], vcc
	s_cbranch_execz .LBB0_819
	v_mov_b32_e32 v100, v98
	v_mov_b32_e32 v101, v98
	v_pk_mul_f32 v[94:95], v[94:95], v[100:101]
	v_pk_mul_f32 v[92:93], v[92:93], v[98:99]
	v_pk_mul_f32 v[90:91], v[90:91], v[100:101]
	v_pk_mul_f32 v[88:89], v[88:89], v[98:99]
	v_cvt_pk_bf16_f32 v92, v92, v93
	v_cvt_pk_bf16_f32 v93, v94, v95
	v_cvt_pk_bf16_f32 v94, v88, v89
	v_cvt_pk_bf16_f32 v95, v90, v91
	global_store_dwordx4 v[96:97], v[92:95], off

.LBB0_821:
	s_or_b64 exec, exec, s[0:1]
	s_nop 0
	v_or_b32_e32 v84, 48, v150
	v_ashrrev_i32_e32 v85, 31, v84
	v_lshlrev_b64 v[80:81], 6, v[84:85]
	v_lshl_add_u64 v[80:81], v[140:141], 0, v[80:81]
	s_nop 1
	v_pk_mov_b32 v[80:81], v[196:197], v[196:197] op_sel:[0,1]
	v_pk_mov_b32 v[82:83], v[198:199], v[198:199] op_sel:[0,1]
	v_mov_b32_e32 v86, v81
	v_mov_b32_e32 v87, v82
	v_mov_b32_e32 v81, v83
	v_pk_add_f32 v[80:81], v[86:87], v[80:81]
	s_nop 0
	v_add_f32_e32 v80, v80, v81
	v_mov_b32_e32 v81, v80
	s_nop 1
	v_permlane16_swap_b32_e32 v80, v81
	s_waitcnt lgkmcnt(0)
	v_add_f32_e32 v80, v80, v81
	v_mov_b32_e32 v81, v80
	s_nop 1
	v_permlane32_swap_b32_e32 v80, v81
	s_waitcnt lgkmcnt(0)
	v_add_f32_e32 v80, v80, v81
	v_fmamk_f32 v80, v80, 0x3a800000, v166
	v_mul_f32_e32 v81, 0x4b800000, v80
	v_cmp_gt_f32_e64 s[0:1], s52, v80
	s_nop 1
	v_cndmask_b32_e64 v80, v80, v81, s[0:1]
	v_rsq_f32_e32 v82, v80
	v_lshlrev_b64 v[80:81], 12, v[84:85]
	v_lshl_add_u64 v[80:81], s[12:13], 0, v[80:81]
	v_lshl_add_u64 v[80:81], v[152:153], 1, v[80:81]
	v_mul_f32_e32 v83, 0x45800000, v82
	v_cndmask_b32_e64 v82, v82, v83, s[0:1]
	v_mov_b32_e32 v83, v82
	s_and_saveexec_b64 s[0:1], vcc
	s_cbranch_execz .LBB0_823
	v_mov_b32_e32 v84, v82
	v_mov_b32_e32 v85, v82
	v_pk_mul_f32 v[78:79], v[78:79], v[84:85]
	v_pk_mul_f32 v[76:77], v[76:77], v[82:83]
	v_pk_mul_f32 v[74:75], v[74:75], v[84:85]
	v_pk_mul_f32 v[72:73], v[72:73], v[82:83]
	v_cvt_pk_bf16_f32 v76, v76, v77
	v_cvt_pk_bf16_f32 v77, v78, v79
	v_cvt_pk_bf16_f32 v78, v72, v73
	v_cvt_pk_bf16_f32 v79, v74, v75
	global_store_dwordx4 v[80:81], v[76:79], off

.LBB0_825:
	s_or_b64 exec, exec, s[0:1]
	s_nop 0
	v_add_u32_e32 v68, 0x80, v150
	v_ashrrev_i32_e32 v69, 31, v68
	v_lshlrev_b64 v[64:65], 6, v[68:69]
	v_lshl_add_u64 v[64:65], v[140:141], 0, v[64:65]
	s_nop 1
	v_pk_mov_b32 v[64:65], v[200:201], v[200:201] op_sel:[0,1]
	v_pk_mov_b32 v[66:67], v[202:203], v[202:203] op_sel:[0,1]
	v_mov_b32_e32 v70, v65
	v_mov_b32_e32 v71, v66
	v_mov_b32_e32 v65, v67
	v_pk_add_f32 v[64:65], v[70:71], v[64:65]
	s_nop 0
	v_add_f32_e32 v64, v64, v65
	v_mov_b32_e32 v65, v64
	s_nop 1
	v_permlane16_swap_b32_e32 v64, v65
	s_waitcnt lgkmcnt(0)
	v_add_f32_e32 v64, v64, v65
	v_mov_b32_e32 v65, v64
	s_nop 1
	v_permlane32_swap_b32_e32 v64, v65
	s_waitcnt lgkmcnt(0)
	v_add_f32_e32 v64, v64, v65
	v_fmamk_f32 v64, v64, 0x3a800000, v166
	v_mul_f32_e32 v65, 0x4b800000, v64
	v_cmp_gt_f32_e64 s[0:1], s52, v64
	s_nop 1
	v_cndmask_b32_e64 v64, v64, v65, s[0:1]
	v_rsq_f32_e32 v66, v64
	v_lshlrev_b64 v[64:65], 12, v[68:69]
	v_lshl_add_u64 v[64:65], s[12:13], 0, v[64:65]
	v_lshl_add_u64 v[64:65], v[152:153], 1, v[64:65]
	v_mul_f32_e32 v67, 0x45800000, v66
	v_cndmask_b32_e64 v66, v66, v67, s[0:1]
	v_mov_b32_e32 v67, v66
	s_and_saveexec_b64 s[0:1], vcc
	s_cbranch_execz .LBB0_827
	v_mov_b32_e32 v68, v66
	v_mov_b32_e32 v69, v66
	v_pk_mul_f32 v[62:63], v[62:63], v[68:69]
	v_pk_mul_f32 v[60:61], v[60:61], v[66:67]
	v_pk_mul_f32 v[58:59], v[58:59], v[68:69]
	v_pk_mul_f32 v[56:57], v[56:57], v[66:67]
	v_cvt_pk_bf16_f32 v60, v60, v61
	v_cvt_pk_bf16_f32 v61, v62, v63
	v_cvt_pk_bf16_f32 v62, v56, v57
	v_cvt_pk_bf16_f32 v63, v58, v59
	global_store_dwordx4 v[64:65], v[60:63], off

.LBB0_829:
	s_or_b64 exec, exec, s[0:1]
	s_nop 0
	v_add_u32_e32 v52, 0x90, v150
	v_ashrrev_i32_e32 v53, 31, v52
	v_lshlrev_b64 v[48:49], 6, v[52:53]
	v_lshl_add_u64 v[48:49], v[140:141], 0, v[48:49]
	s_nop 1
	v_pk_mov_b32 v[48:49], v[204:205], v[204:205] op_sel:[0,1]
	v_pk_mov_b32 v[50:51], v[206:207], v[206:207] op_sel:[0,1]
	v_mov_b32_e32 v54, v49
	v_mov_b32_e32 v55, v50
	v_mov_b32_e32 v49, v51
	v_pk_add_f32 v[48:49], v[54:55], v[48:49]
	s_nop 0
	v_add_f32_e32 v48, v48, v49
	v_mov_b32_e32 v49, v48
	s_nop 1
	v_permlane16_swap_b32_e32 v48, v49
	s_waitcnt lgkmcnt(0)
	v_add_f32_e32 v48, v48, v49
	v_mov_b32_e32 v49, v48
	s_nop 1
	v_permlane32_swap_b32_e32 v48, v49
	s_waitcnt lgkmcnt(0)
	v_add_f32_e32 v48, v48, v49
	v_fmamk_f32 v48, v48, 0x3a800000, v166
	v_mul_f32_e32 v49, 0x4b800000, v48
	v_cmp_gt_f32_e64 s[0:1], s52, v48
	s_nop 1
	v_cndmask_b32_e64 v48, v48, v49, s[0:1]
	v_rsq_f32_e32 v50, v48
	v_lshlrev_b64 v[48:49], 12, v[52:53]
	v_lshl_add_u64 v[48:49], s[12:13], 0, v[48:49]
	v_lshl_add_u64 v[48:49], v[152:153], 1, v[48:49]
	v_mul_f32_e32 v51, 0x45800000, v50
	v_cndmask_b32_e64 v50, v50, v51, s[0:1]
	v_mov_b32_e32 v51, v50
	s_and_saveexec_b64 s[0:1], vcc
	s_cbranch_execz .LBB0_831
	v_mov_b32_e32 v52, v50
	v_mov_b32_e32 v53, v50
	v_pk_mul_f32 v[46:47], v[46:47], v[52:53]
	v_pk_mul_f32 v[44:45], v[44:45], v[50:51]
	v_pk_mul_f32 v[42:43], v[42:43], v[52:53]
	v_pk_mul_f32 v[40:41], v[40:41], v[50:51]
	v_cvt_pk_bf16_f32 v44, v44, v45
	v_cvt_pk_bf16_f32 v45, v46, v47
	v_cvt_pk_bf16_f32 v46, v40, v41
	v_cvt_pk_bf16_f32 v47, v42, v43
	global_store_dwordx4 v[48:49], v[44:47], off

.LBB0_833:
	s_or_b64 exec, exec, s[0:1]
	s_nop 0
	v_add_u32_e32 v36, 0xa0, v150
	v_ashrrev_i32_e32 v37, 31, v36
	v_lshlrev_b64 v[32:33], 6, v[36:37]
	v_lshl_add_u64 v[32:33], v[140:141], 0, v[32:33]
	s_nop 1
	v_pk_mov_b32 v[32:33], v[208:209], v[208:209] op_sel:[0,1]
	v_pk_mov_b32 v[34:35], v[210:211], v[210:211] op_sel:[0,1]
	v_mov_b32_e32 v38, v33
	v_mov_b32_e32 v39, v34
	v_mov_b32_e32 v33, v35
	v_pk_add_f32 v[32:33], v[38:39], v[32:33]
	s_nop 0
	v_add_f32_e32 v32, v32, v33
	v_mov_b32_e32 v33, v32
	s_nop 1
	v_permlane16_swap_b32_e32 v32, v33
	s_waitcnt lgkmcnt(0)
	v_add_f32_e32 v32, v32, v33
	v_mov_b32_e32 v33, v32
	s_nop 1
	v_permlane32_swap_b32_e32 v32, v33
	s_waitcnt lgkmcnt(0)
	v_add_f32_e32 v32, v32, v33
	v_fmamk_f32 v32, v32, 0x3a800000, v166
	v_mul_f32_e32 v33, 0x4b800000, v32
	v_cmp_gt_f32_e64 s[0:1], s52, v32
	s_nop 1
	v_cndmask_b32_e64 v32, v32, v33, s[0:1]
	v_rsq_f32_e32 v34, v32
	v_lshlrev_b64 v[32:33], 12, v[36:37]
	v_lshl_add_u64 v[32:33], s[12:13], 0, v[32:33]
	v_lshl_add_u64 v[32:33], v[152:153], 1, v[32:33]
	v_mul_f32_e32 v35, 0x45800000, v34
	v_cndmask_b32_e64 v34, v34, v35, s[0:1]
	v_mov_b32_e32 v35, v34
	s_and_saveexec_b64 s[0:1], vcc
	s_cbranch_execz .LBB0_835
	v_mov_b32_e32 v36, v34
	v_mov_b32_e32 v37, v34
	v_pk_mul_f32 v[30:31], v[30:31], v[36:37]
	v_pk_mul_f32 v[28:29], v[28:29], v[34:35]
	v_pk_mul_f32 v[26:27], v[26:27], v[36:37]
	v_pk_mul_f32 v[24:25], v[24:25], v[34:35]
	v_cvt_pk_bf16_f32 v28, v28, v29
	v_cvt_pk_bf16_f32 v29, v30, v31
	v_cvt_pk_bf16_f32 v30, v24, v25
	v_cvt_pk_bf16_f32 v31, v26, v27
	global_store_dwordx4 v[32:33], v[28:31], off

.LBB0_837:
	s_or_b64 exec, exec, s[0:1]
	s_nop 0
	v_add_u32_e32 v20, 0xb0, v150
	v_ashrrev_i32_e32 v21, 31, v20
	v_lshlrev_b64 v[16:17], 6, v[20:21]
	v_lshl_add_u64 v[16:17], v[140:141], 0, v[16:17]
	s_nop 1
	v_pk_mov_b32 v[16:17], v[212:213], v[212:213] op_sel:[0,1]
	v_pk_mov_b32 v[18:19], v[214:215], v[214:215] op_sel:[0,1]
	v_mov_b32_e32 v22, v17
	v_mov_b32_e32 v23, v18
	v_mov_b32_e32 v17, v19
	v_pk_add_f32 v[16:17], v[22:23], v[16:17]
	s_nop 0
	v_add_f32_e32 v16, v16, v17
	v_mov_b32_e32 v17, v16
	s_nop 1
	v_permlane16_swap_b32_e32 v16, v17
	s_waitcnt lgkmcnt(0)
	v_add_f32_e32 v16, v16, v17
	v_mov_b32_e32 v17, v16
	s_nop 1
	v_permlane32_swap_b32_e32 v16, v17
	s_waitcnt lgkmcnt(0)
	v_add_f32_e32 v16, v16, v17
	v_fmamk_f32 v16, v16, 0x3a800000, v166
	v_mul_f32_e32 v17, 0x4b800000, v16
	v_cmp_gt_f32_e64 s[0:1], s52, v16
	s_nop 1
	v_cndmask_b32_e64 v16, v16, v17, s[0:1]
	v_rsq_f32_e32 v18, v16
	v_lshlrev_b64 v[16:17], 12, v[20:21]
	v_lshl_add_u64 v[16:17], s[12:13], 0, v[16:17]
	v_lshl_add_u64 v[16:17], v[152:153], 1, v[16:17]
	v_mul_f32_e32 v19, 0x45800000, v18
	v_cndmask_b32_e64 v18, v18, v19, s[0:1]
	v_mov_b32_e32 v19, v18
	s_and_saveexec_b64 s[0:1], vcc
	s_cbranch_execnz .LBB0_840
	s_or_b64 exec, exec, s[0:1]
	s_and_saveexec_b64 s[0:1], s[6:7]
	s_cbranch_execnz .LBB0_841

.LBB0_985:
	s_setprio 0
	s_waitcnt lgkmcnt(0)
	s_barrier
	s_waitcnt vmcnt(0)
	v_pk_mov_b32 v[16:17], v[32:33], v[32:33] op_sel:[0,1]
	s_nop 2
	v_pk_mov_b32 v[82:83], v[118:119], v[118:119] op_sel:[0,1]
	v_pk_mov_b32 v[18:19], v[34:35], v[34:35] op_sel:[0,1]
	v_pk_mov_b32 v[20:21], v[36:37], v[36:37] op_sel:[0,1]
	v_pk_mov_b32 v[22:23], v[38:39], v[38:39] op_sel:[0,1]
	v_pk_mov_b32 v[24:25], v[40:41], v[40:41] op_sel:[0,1]
	v_pk_mov_b32 v[26:27], v[42:43], v[42:43] op_sel:[0,1]
	v_pk_mov_b32 v[28:29], v[44:45], v[44:45] op_sel:[0,1]
	v_pk_mov_b32 v[30:31], v[46:47], v[46:47] op_sel:[0,1]
	v_pk_mov_b32 v[84:85], v[120:121], v[120:121] op_sel:[0,1]
.LBB0_986:
	s_waitcnt vmcnt(2)
	v_lshlrev_b32_e32 v33, 16, v145
	v_mul_f32_e32 v33, 0xbfb8aa3b, v33
	v_exp_f32_e32 v33, v33
	v_lshlrev_b32_e32 v32, 16, v183
	v_mul_f32_e32 v32, 0xbfb8aa3b, v32
	v_exp_f32_e32 v32, v32
	v_add_f32_e32 v33, 1.0, v33
	v_rcp_f32_e32 v33, v33
	v_pk_mov_b32 v[58:59], v[54:55], v[54:55] op_sel:[0,1]
	v_add_f32_e32 v32, 1.0, v32
	v_rcp_f32_e32 v32, v32
	v_div_scale_f32 v34, s[0:1], v80, v80, v33
	v_rcp_f32_e32 v35, v34
	v_div_scale_f32 v36, vcc, v33, v80, v33
	v_mul_f32_e32 v32, v32, v135
	v_fma_f32 v37, -v34, v35, 1.0
	v_fmac_f32_e32 v35, v37, v35
	v_mul_f32_e32 v37, v36, v35
	v_fma_f32 v38, -v34, v37, v36
	v_fmac_f32_e32 v37, v38, v35
	v_fma_f32 v34, -v34, v37, v36
	v_div_fmas_f32 v34, v34, v35, v37
	v_div_fixup_f32 v33, v34, v80, v33
	v_cmp_lt_f32_e32 vcc, 0, v80
	v_alignbit_b32 v37, v185, v133, 16
	v_pk_mov_b32 v[62:63], v[50:51], v[50:51] op_sel:[0,1]
	v_cndmask_b32_e32 v34, 0, v33, vcc
	v_pk_mul_f32 v[0:1], v[0:1], v[34:35] op_sel_hi:[1,0]
	v_pk_mul_f32 v[2:3], v[2:3], v[34:35] op_sel_hi:[1,0]
	v_pk_mul_f32 v[4:5], v[4:5], v[34:35] op_sel_hi:[1,0]
	v_pk_mul_f32 v[6:7], v[6:7], v[34:35] op_sel_hi:[1,0]
	v_pk_mul_f32 v[8:9], v[8:9], v[34:35] op_sel_hi:[1,0]
	v_pk_fma_f32 v[0:1], v[72:73], v[32:33], v[0:1] op_sel_hi:[1,0,1]
	v_pk_fma_f32 v[2:3], v[74:75], v[32:33], v[2:3] op_sel_hi:[1,0,1]
	v_pk_fma_f32 v[4:5], v[76:77], v[32:33], v[4:5] op_sel_hi:[1,0,1]
	v_pk_fma_f32 v[6:7], v[78:79], v[32:33], v[6:7] op_sel_hi:[1,0,1]
	v_pk_fma_f32 v[8:9], v[68:69], v[32:33], v[8:9] op_sel_hi:[1,0,1]
	v_and_b32_e32 v33, 0xffff0000, v145
	v_mul_f32_e32 v33, 0xbfb8aa3b, v33
	v_exp_f32_e32 v33, v33
	v_pk_mul_f32 v[10:11], v[10:11], v[34:35] op_sel_hi:[1,0]
	v_pk_mul_f32 v[12:13], v[12:13], v[34:35] op_sel_hi:[1,0]
	v_ashrrev_i32_e32 v145, 31, v144
	v_pk_fma_f32 v[10:11], v[70:71], v[32:33], v[10:11] op_sel_hi:[1,0,1]
	v_pk_fma_f32 v[12:13], v[64:65], v[32:33], v[12:13] op_sel_hi:[1,0,1]
	v_add_f32_e32 v33, 1.0, v33
	v_rcp_f32_e32 v35, v33
	v_pk_mov_b32 v[56:57], v[52:53], v[52:53] op_sel:[0,1]
	v_pk_mov_b32 v[60:61], v[48:49], v[48:49] op_sel:[0,1]
	v_mov_b32_e32 v183, v133
	v_pk_mul_f32 v[14:15], v[14:15], v[34:35] op_sel_hi:[1,0]
	v_div_scale_f32 v34, s[0:1], v82, v82, v35
	v_rcp_f32_e32 v36, v34
	v_pk_fma_f32 v[14:15], v[66:67], v[32:33], v[14:15] op_sel_hi:[1,0,1]
	v_lshl_add_u64 v[32:33], v[144:145], 0, s[40:41]
	s_mov_b32 s22, s73
	v_fma_f32 v38, -v34, v36, 1.0
	v_fmac_f32_e32 v36, v38, v36
	v_div_scale_f32 v38, vcc, v35, v82, v35
	v_mul_f32_e32 v39, v38, v36
	s_waitcnt vmcnt(0)
	v_fma_f32 v40, -v34, v39, v38
	v_fmac_f32_e32 v39, v40, v36
	v_fma_f32 v34, -v34, v39, v38
	v_div_fmas_f32 v34, v34, v36, v39
	v_div_fixup_f32 v34, v34, v82, v35
	v_cmp_lt_f32_e32 vcc, 0, v82
	v_mov_b32_e32 v145, v37
	s_nop 0
	v_cndmask_b32_e32 v34, 0, v34, vcc
	v_pk_fma_f32 v[0:1], v[16:17], v[34:35], v[0:1] op_sel_hi:[1,0,1]
	v_lshlrev_b64 v[16:17], 11, v[32:33]
	v_pk_fma_f32 v[2:3], v[18:19], v[34:35], v[2:3] op_sel_hi:[1,0,1]
	v_lshl_add_u64 v[16:17], s[38:39], 0, v[16:17]
	v_lshlrev_b32_e32 v18, 7, v184
	v_mov_b32_e32 v19, v123
	v_lshl_add_u64 v[16:17], v[16:17], 0, v[18:19]
	v_lshlrev_b32_e32 v18, 1, v124
	v_pk_fma_f32 v[4:5], v[20:21], v[34:35], v[4:5] op_sel_hi:[1,0,1]
	v_pk_fma_f32 v[6:7], v[22:23], v[34:35], v[6:7] op_sel_hi:[1,0,1]
	v_lshl_add_u64 v[16:17], v[16:17], 0, v[18:19]
	v_cvt_pk_bf16_f32 v0, v0, v1
	v_cvt_pk_bf16_f32 v1, v2, v3
	v_pk_fma_f32 v[8:9], v[24:25], v[34:35], v[8:9] op_sel_hi:[1,0,1]
	v_pk_fma_f32 v[10:11], v[26:27], v[34:35], v[10:11] op_sel_hi:[1,0,1]
	global_store_dwordx2 v[16:17], v[0:1], off
	v_cvt_pk_bf16_f32 v0, v4, v5
	v_cvt_pk_bf16_f32 v1, v6, v7
	v_pk_fma_f32 v[12:13], v[28:29], v[34:35], v[12:13] op_sel_hi:[1,0,1]
	v_pk_fma_f32 v[14:15], v[30:31], v[34:35], v[14:15] op_sel_hi:[1,0,1]
	global_store_dwordx2 v[16:17], v[0:1], off offset:32
	v_cvt_pk_bf16_f32 v0, v8, v9
	v_cvt_pk_bf16_f32 v1, v10, v11
	global_store_dwordx2 v[16:17], v[0:1], off offset:64
	v_cvt_pk_bf16_f32 v0, v12, v13
	v_cvt_pk_bf16_f32 v1, v14, v15
	s_andn2_b64 vcc, exec, s[48:49]
	global_store_dwordx2 v[16:17], v[0:1], off offset:96
	s_cbranch_vccz .LBB0_1074

.LBB0_1007:
	s_mov_b32 s90, s20
	s_lshl_b32 s0, s23, 13
	s_lshl_b32 s1, s20, 4
	s_and_b32 s40, s22, 3
	s_bfe_u32 s29, s22, 0x10002
	s_bfe_u32 s98, s22, 0x1000b
	s_xor_b32 s29, s29, s98
	s_lshl_b32 s74, s75, 4
	s_and_b32 s0, s0, 0x6000
	s_ashr_i32 s20, s1, 31
	s_add_u32 s0, s1, s0
	s_addc_u32 s1, s20, 0
	v_or_b32_e32 v0, s0, v130
	s_lshl_b32 s0, s23, 1
	v_mov_b32_e32 v1, s1
	s_and_b32 s0, s0, 8
	s_lshr_b32 s98, s23, 8
	s_and_b32 s98, s98, 8
	s_xor_b32 s0, s0, s98
	v_add_u32_e32 v4, s0, v131
	v_lshlrev_b64 v[0:1], 12, v[0:1]
	v_lshl_add_u64 v[0:1], s[36:37], 0, v[0:1]
	v_lshlrev_b32_e32 v2, 7, v4
	v_mov_b32_e32 v3, v123
	v_lshl_add_u64 v[2:3], v[0:1], 0, v[2:3]
	v_mov_b32_e32 v133, v123
	v_lshl_add_u64 v[2:3], v[2:3], 0, v[132:133]
	global_load_dwordx4 v[48:51], v[2:3], off
	global_load_dwordx4 v[52:55], v[2:3], off offset:64
	v_mul_u32_u24_e32 v2, 3, v4
	v_lshlrev_b32_e32 v2, 1, v2
	v_mov_b32_e32 v3, v123
	v_lshl_add_u64 v[0:1], v[0:1], 0, v[2:3]
	global_load_dword v133, v[0:1], off offset:3584
	global_load_ushort v185, v[0:1], off offset:3588
	v_lshl_add_u32 v184, s29, 3, v131
	v_add_u32_e32 v0, 1, v184
	v_cvt_f32_ubyte0_e32 v0, v0
	v_mul_f32_e32 v1, -0.5, v0
	v_cmp_gt_f32_e32 vcc, s64, v1
	s_lshl_b32 s0, s40, 1
	s_or_b32 s47, s0, s29
	v_cndmask_b32_e32 v1, 0, v177, vcc
	v_fmac_f32_e32 v1, -0.5, v0
	v_exp_f32_e32 v0, v1
	s_add_i32 s0, s75, -1
	s_ashr_i32 s0, s0, 6
	s_add_i32 s0, s0, 1
	v_cndmask_b32_e32 v1, 0, v178, vcc
	s_cmp_gt_i32 s75, 0
	v_ldexp_f32 v0, v0, v1
	s_cselect_b32 s20, s0, 0
	v_mov_b32_e32 v75, 0
	v_mul_f32_e32 v146, 0x3fb8aa3b, v0
	v_or_b32_e32 v144, s74, v130
	s_cmp_lt_i32 s20, 1
	v_add_u32_e32 v187, 0xa000, v152
	v_add_u32_e32 v186, 0xc800, v152
	v_mov_b32_e32 v74, 0
	v_mov_b32_e32 v73, 0
	v_mov_b32_e32 v72, 0
	v_mov_b32_e32 v79, 0
	v_mov_b32_e32 v78, 0
	v_mov_b32_e32 v77, 0
	v_mov_b32_e32 v76, 0
	v_mov_b32_e32 v71, 0
	v_mov_b32_e32 v70, 0
	v_mov_b32_e32 v69, 0
	v_mov_b32_e32 v68, 0
	v_mov_b32_e32 v67, 0
	v_mov_b32_e32 v66, 0
	v_mov_b32_e32 v65, 0
	v_mov_b32_e32 v64, 0
	v_mov_b32_e32 v80, 0
	v_mov_b32_e32 v81, 0
	s_cbranch_scc1 .LBB0_1027
	s_lshl_b32 s21, s47, 16
	s_add_u32 s0, s3, s21
	s_addc_u32 s1, s52, 0
	s_add_u32 s22, s53, s21
	s_addc_u32 s23, s54, 0
	s_add_i32 s21, s20, -1
	s_cmp_eq_u32 s20, 1
	s_cselect_b64 s[24:25], -1, 0
	s_and_b64 vcc, s[24:25], exec
	s_cselect_b32 s26, 0, 64
	s_lshl_b32 s24, s26, 7
	v_mov_b32_e32 v135, v123
	s_add_u32 s24, s0, s24
	v_lshl_add_u64 v[0:1], s[0:1], 0, v[134:135]
	v_mov_b32_e32 v137, v123
	s_addc_u32 s25, s1, 0
	s_lshl_b32 s26, s26, 1
	v_lshl_add_u64 v[44:45], v[0:1], 0, v[122:123]
	v_lshl_add_u64 v[0:1], s[22:23], 0, v[136:137]
	s_add_u32 s26, s22, s26
	v_lshl_add_u64 v[46:47], v[0:1], 0, v[122:123]
	s_addc_u32 s27, s23, 0
	v_lshl_add_u64 v[0:1], s[24:25], 0, v[134:135]
	v_pk_mov_b32 v[8:9], v[240:241], v[240:241] op_sel:[0,1]
	v_pk_mov_b32 v[10:11], v[242:243], v[242:243] op_sel:[0,1]
	v_pk_mov_b32 v[12:13], v[244:245], v[244:245] op_sel:[0,1]
	v_pk_mov_b32 v[14:15], v[246:247], v[246:247] op_sel:[0,1]
	v_lshl_add_u64 v[0:1], v[0:1], 0, v[122:123]
	v_lshl_add_u64 v[2:3], s[26:27], 0, v[136:137]
	v_lshl_add_u64 v[2:3], v[2:3], 0, v[122:123]
	v_pk_mov_b32 v[16:17], v[248:249], v[248:249] op_sel:[0,1]
	v_pk_mov_b32 v[18:19], v[250:251], v[250:251] op_sel:[0,1]
	v_pk_mov_b32 v[20:21], v[252:253], v[252:253] op_sel:[0,1]
	v_pk_mov_b32 v[22:23], v[254:255], v[254:255] op_sel:[0,1]
	s_min_u32 s26, s21, 2
	s_lshl_b32 s24, s26, 13
	s_add_u32 s24, s0, s24
	s_addc_u32 s25, s1, 0
	s_lshl_b32 s26, s26, 7
	s_add_u32 s26, s22, s26
	v_lshl_add_u64 v[0:1], s[24:25], 0, v[134:135]
	s_addc_u32 s27, s23, 0
	s_min_u32 s24, s21, 3
	s_lshl_b32 s25, s24, 13
	s_add_u32 s0, s0, s25
	v_lshl_add_u64 v[2:3], s[26:27], 0, v[136:137]
	s_addc_u32 s1, s1, 0
	s_lshl_b32 s24, s24, 7
	v_lshl_add_u64 v[0:1], v[0:1], 0, v[122:123]
	v_lshl_add_u64 v[2:3], v[2:3], 0, v[122:123]
	s_add_u32 s22, s22, s24
	global_load_dwordx4 v[4:7], v[0:1], off
	s_nop 0
	global_load_dwordx4 v[0:3], v[2:3], off
	v_lshl_add_u64 v[24:25], s[0:1], 0, v[134:135]
	s_addc_u32 s23, s23, 0
	v_lshl_add_u64 v[24:25], v[24:25], 0, v[122:123]
	v_lshl_add_u64 v[26:27], s[22:23], 0, v[136:137]
	v_lshl_add_u64 v[26:27], v[26:27], 0, v[122:123]
	v_mov_b32_e32 v75, 0
	s_mov_b32 s0, 0
	v_mov_b32_e32 v74, v75
	v_mov_b32_e32 v73, v75
	v_mov_b32_e32 v72, v75
	v_mov_b32_e32 v79, v75
	v_mov_b32_e32 v78, v75
	v_mov_b32_e32 v77, v75
	v_mov_b32_e32 v76, v75
	v_mov_b32_e32 v71, v75
	v_mov_b32_e32 v70, v75
	v_mov_b32_e32 v69, v75
	v_mov_b32_e32 v68, v75
	v_mov_b32_e32 v67, v75
	v_mov_b32_e32 v66, v75
	v_mov_b32_e32 v65, v75
	v_mov_b32_e32 v64, v75
	v_mov_b32_e32 v80, v75
	v_mov_b32_e32 v81, v75
	ds_write_b128 v151, v[8:11]
	ds_write2_b64 v187, v[12:13], v[14:15] offset1:2
	ds_write_b128 v151, v[16:19] offset:10240
	ds_write2_b64 v186, v[20:21], v[22:23] offset1:2
	global_load_dwordx4 v[12:15], v[24:25], off
	global_load_dwordx4 v[8:11], v[26:27], off
	s_waitcnt lgkmcnt(0)
	s_barrier
	s_cbranch_vccnz .LBB0_1021
	v_mov_b32_e32 v80, 0
	s_add_i32 s22, s75, -2
	v_mul_f32_e32 v82, 0x41800000, v146
	v_mul_f32_e32 v83, 0x42000000, v146
	v_mul_f32_e32 v84, 0x42400000, v146
	v_mul_f32_e32 v85, 0, v146
	s_waitcnt lgkmcnt(7)
	v_mul_f32_e32 v86, 0x43800000, v146
	v_mul_f32_e32 v87, 0x44000000, v146
	v_mul_f32_e32 v88, 0x44400000, v146
	v_add_u32_e32 v89, s74, v169
	s_mov_b32 s24, 5
	s_movk_i32 s23, 0xc0
	v_mov_b32_e32 v81, 0
	v_mov_b32_e32 v64, 0
	v_mov_b32_e32 v65, v80
	v_mov_b32_e32 v66, v80
	v_mov_b32_e32 v67, v80
	v_mov_b32_e32 v68, 0
	v_mov_b32_e32 v69, v80
	v_mov_b32_e32 v70, v80
	v_mov_b32_e32 v71, v80
	v_mov_b32_e32 v76, 0
	v_mov_b32_e32 v77, v80
	v_mov_b32_e32 v78, v80
	v_mov_b32_e32 v79, v80
	v_mov_b32_e32 v72, 0
	v_mov_b32_e32 v73, v80
	v_mov_b32_e32 v74, v80
	v_mov_b32_e32 v75, v80

.LBB0_1044:
	s_lshl_b32 s29, s22, 6
	v_subrev_u32_e32 v1, s29, v139
	s_add_i32 s29, s81, 0xffffff80
	s_and_b32 s29, s29, 0x80
	s_mulk_i32 s29, 0xa0
	v_add_u32_e32 v143, s29, v153
	ds_read_b128 v[88:91], v143
	ds_read_b128 v[92:95], v143 offset:64
	ds_read_b128 v[96:99], v143 offset:2560
	ds_read_b128 v[100:103], v143 offset:2624
	ds_read_b128 v[104:107], v143 offset:5120
	ds_read_b128 v[108:111], v143 offset:5184
	ds_read_b128 v[112:115], v143 offset:7680
	ds_read_b128 v[116:119], v143 offset:7744
	s_lshl_b32 s29, s23, 6
	v_subrev_u32_e32 v0, s29, v139
	s_max_i32 s22, s22, s23
	s_cmp_ge_i32 s22, s76
	s_setprio 1
	v_cvt_f32_i32_e32 v147, v1
	v_cvt_f32_i32_e32 v141, v0
	s_mov_b64 s[22:23], -1
	s_cbranch_scc0 .LBB0_1046
	s_waitcnt lgkmcnt(7)
	v_mfma_f32_16x16x32_bf16 v[2:5], v[88:91], v[60:63], 0
	s_waitcnt lgkmcnt(5)
	v_mfma_f32_16x16x32_bf16 v[6:9], v[96:99], v[60:63], 0
	s_waitcnt lgkmcnt(3)
	v_mfma_f32_16x16x32_bf16 v[10:13], v[104:107], v[60:63], 0
	s_waitcnt lgkmcnt(1)
	v_mfma_f32_16x16x32_bf16 v[80:83], v[112:115], v[60:63], 0
	v_mfma_f32_16x16x32_bf16 v[2:5], v[92:95], v[56:59], v[2:5]
	v_mfma_f32_16x16x32_bf16 v[6:9], v[100:103], v[56:59], v[6:9]
	v_mfma_f32_16x16x32_bf16 v[10:13], v[108:111], v[56:59], v[10:13]
	s_waitcnt lgkmcnt(0)
	v_mfma_f32_16x16x32_bf16 v[80:83], v[116:119], v[56:59], v[80:83]
	s_setprio 0
	v_fma_f32 v14, -v146, v147, v192
	s_nop 1
	v_fmamk_f32 v2, v2, 0x3e38aa3b, v14
	v_cmp_gt_u32_e32 vcc, s70, v1
	v_add_f32_e32 v15, v146, v14
	s_and_b64 vcc, vcc, s[20:21]
	v_fmac_f32_e32 v15, 0x3e38aa3b, v3
	v_add_f32_e32 v3, v137, v14
	v_cndmask_b32_e32 v2, v179, v2, vcc
	v_cmp_lt_i32_e32 vcc, 0, v1
	v_fmac_f32_e32 v3, 0x3e38aa3b, v4
	v_add_f32_e32 v4, v188, v14
	s_and_b64 vcc, vcc, s[20:21]
	v_add_u32_e32 v14, -2, v1
	v_fmac_f32_e32 v4, 0x3e38aa3b, v5
	s_nop 0
	v_cndmask_b32_e32 v5, v179, v15, vcc
	v_cmp_gt_u32_e32 vcc, s70, v14
	s_and_b64 vcc, s[20:21], vcc
	v_add_u32_e32 v14, -3, v1
	v_cndmask_b32_e32 v3, v179, v3, vcc
	v_cmp_gt_u32_e32 vcc, s70, v14
	v_exp_f32_e32 v14, v2
	v_fma_f32 v2, -v146, v147, v189
	s_and_b64 vcc, s[20:21], vcc
	v_exp_f32_e32 v193, v3
	v_fmamk_f32 v3, v6, 0x3e38aa3b, v2
	v_add_u32_e32 v6, -16, v1
	v_cndmask_b32_e32 v4, v179, v4, vcc
	v_cmp_gt_u32_e32 vcc, s70, v6
	v_exp_f32_e32 v195, v4
	v_add_f32_e32 v4, v146, v2
	s_and_b64 vcc, s[20:21], vcc
	v_subrev_u32_e32 v6, 17, v1
	v_fmac_f32_e32 v4, 0x3e38aa3b, v7
	v_cndmask_b32_e32 v3, v179, v3, vcc
	v_cmp_gt_u32_e32 vcc, s70, v6
	v_exp_f32_e32 v15, v5
	v_add_f32_e32 v5, v137, v2
	s_and_b64 vcc, vcc, s[20:21]
	v_subrev_u32_e32 v6, 18, v1
	v_fmac_f32_e32 v5, 0x3e38aa3b, v8
	v_cndmask_b32_e32 v4, v179, v4, vcc
	v_cmp_gt_u32_e32 vcc, s70, v6
	v_add_f32_e32 v2, v188, v2
	s_and_b64 vcc, s[20:21], vcc
	v_subrev_u32_e32 v6, 19, v1
	v_fmac_f32_e32 v2, 0x3e38aa3b, v9
	v_cndmask_b32_e32 v5, v179, v5, vcc
	v_cmp_gt_u32_e32 vcc, s70, v6
	s_and_b64 vcc, s[20:21], vcc
	v_subrev_u32_e32 v6, 32, v1
	v_cndmask_b32_e32 v2, v179, v2, vcc
	v_exp_f32_e32 v199, v2
	v_fma_f32 v2, -v146, v147, v190
	v_exp_f32_e32 v196, v3
	v_fmamk_f32 v3, v10, 0x3e38aa3b, v2
	v_cmp_gt_u32_e32 vcc, s70, v6
	v_exp_f32_e32 v197, v4
	v_add_f32_e32 v4, v146, v2
	s_and_b64 vcc, s[20:21], vcc
	v_subrev_u32_e32 v6, 33, v1
	v_fmac_f32_e32 v4, 0x3e38aa3b, v11
	v_cndmask_b32_e32 v3, v179, v3, vcc
	v_cmp_gt_u32_e32 vcc, s70, v6
	v_exp_f32_e32 v198, v5
	v_add_f32_e32 v5, v137, v2
	s_and_b64 vcc, vcc, s[20:21]
	v_subrev_u32_e32 v6, 34, v1
	v_fmac_f32_e32 v5, 0x3e38aa3b, v12
	v_cndmask_b32_e32 v4, v179, v4, vcc
	v_cmp_gt_u32_e32 vcc, s70, v6
	v_add_f32_e32 v2, v188, v2
	s_and_b64 vcc, s[20:21], vcc
	v_subrev_u32_e32 v6, 35, v1
	v_fmac_f32_e32 v2, 0x3e38aa3b, v13
	v_cndmask_b32_e32 v5, v179, v5, vcc
	v_cmp_gt_u32_e32 vcc, s70, v6
	s_and_b64 vcc, s[20:21], vcc
	v_subrev_u32_e32 v6, 48, v1
	v_cndmask_b32_e32 v2, v179, v2, vcc
	v_exp_f32_e32 v221, v2
	v_fma_f32 v2, -v146, v147, v191
	v_exp_f32_e32 v218, v3
	v_fmamk_f32 v3, v80, 0x3e38aa3b, v2
	v_cmp_gt_u32_e32 vcc, s70, v6
	v_exp_f32_e32 v219, v4
	v_add_f32_e32 v4, v146, v2
	s_and_b64 vcc, s[20:21], vcc
	v_subrev_u32_e32 v6, 49, v1
	v_fmac_f32_e32 v4, 0x3e38aa3b, v81
	v_cndmask_b32_e32 v3, v179, v3, vcc
	v_cmp_gt_u32_e32 vcc, s70, v6
	v_exp_f32_e32 v220, v5
	v_add_f32_e32 v5, v137, v2
	s_and_b64 vcc, vcc, s[20:21]
	v_subrev_u32_e32 v6, 50, v1
	v_fmac_f32_e32 v5, 0x3e38aa3b, v82
	v_cndmask_b32_e32 v4, v179, v4, vcc
	v_cmp_gt_u32_e32 vcc, s70, v6
	v_add_f32_e32 v2, v188, v2
	s_and_b64 vcc, s[20:21], vcc
	v_subrev_u32_e32 v1, 51, v1
	v_fmac_f32_e32 v2, 0x3e38aa3b, v83
	v_cndmask_b32_e32 v5, v179, v5, vcc
	v_cmp_gt_u32_e32 vcc, s70, v1
	s_and_b64 vcc, s[20:21], vcc
	v_exp_f32_e32 v222, v3
	v_cndmask_b32_e32 v1, v179, v2, vcc
	v_exp_f32_e32 v223, v4
	v_exp_f32_e32 v224, v5
	ds_read_b128 v[2:5], v143 offset:40960
	ds_read_b128 v[6:9], v143 offset:43520
	ds_read_b128 v[10:13], v143 offset:46080
	ds_read_b128 v[80:83], v143 offset:48640
	v_exp_f32_e32 v1, v1
	s_nop 0
	v_cvt_pk_bf16_f32 v194, v14, v15
	v_cvt_pk_bf16_f32 v195, v193, v195
	v_cvt_pk_bf16_f32 v196, v196, v197
	v_cvt_pk_bf16_f32 v197, v198, v199
	s_setprio 1
	s_mov_b32 s30, s28
	s_mov_b32 s31, s28
	s_waitcnt lgkmcnt(0)
	v_mfma_f32_16x16x32_bf16 v[198:201], v[80:83], v[194:197], v[84:87]
	s_mov_b32 s29, s28
	v_pk_mov_b32 v[82:83], s[30:31], s[30:31] op_sel:[0,1]
	v_pk_mov_b32 v[80:81], s[28:29], s[28:29] op_sel:[0,1]
	v_mfma_f32_16x16x32_bf16 v[2:5], v[2:5], v[194:197], v[36:39]
	v_mfma_f32_16x16x32_bf16 v[6:9], v[6:9], v[194:197], v[40:43]
	v_mfma_f32_16x16x32_bf16 v[10:13], v[10:13], v[194:197], v[44:47]
	v_mfma_f32_16x16x32_bf16 v[194:197], v[80:83], v[194:197], v[32:35]
	s_setprio 0
	ds_read_b128 v[202:205], v143 offset:41024
	ds_read_b128 v[206:209], v143 offset:43584
	ds_read_b128 v[210:213], v143 offset:46144
	ds_read_b128 v[214:217], v143 offset:48704
	v_cvt_pk_bf16_f32 v218, v218, v219
	v_cvt_pk_bf16_f32 v219, v220, v221
	v_cvt_pk_bf16_f32 v220, v222, v223
	v_cvt_pk_bf16_f32 v221, v224, v1
	s_setprio 1
	s_waitcnt lgkmcnt(3)
	v_mfma_f32_16x16x32_bf16 v[2:5], v[202:205], v[218:221], v[2:5]
	s_waitcnt lgkmcnt(2)
	v_mfma_f32_16x16x32_bf16 v[6:9], v[206:209], v[218:221], v[6:9]
	s_waitcnt lgkmcnt(1)
	v_mfma_f32_16x16x32_bf16 v[10:13], v[210:213], v[218:221], v[10:13]
	s_waitcnt lgkmcnt(0)
	v_mfma_f32_16x16x32_bf16 v[198:201], v[214:217], v[218:221], v[198:201]
	v_mfma_f32_16x16x32_bf16 v[194:197], v[80:83], v[218:221], v[194:197]
	s_setprio 0
	s_sub_i32 s22, s81, 64
	s_and_b32 s22, s22, 0xc0
	s_mulk_i32 s22, 0xa0
	v_add_u32_e32 v193, s22, v153
	ds_read_b128 v[202:205], v193
	ds_read_b128 v[206:209], v193 offset:64
	ds_read_b128 v[210:213], v193 offset:2560
	ds_read_b128 v[214:217], v193 offset:2624
	ds_read_b128 v[218:221], v193 offset:5120
	ds_read_b128 v[222:225], v193 offset:5184
	ds_read_b128 v[226:229], v193 offset:7680
	ds_read_b128 v[230:233], v193 offset:7744
	s_setprio 1
	s_waitcnt lgkmcnt(7)
	v_mfma_f32_16x16x32_bf16 v[202:205], v[202:205], v[60:63], 0
	s_waitcnt lgkmcnt(6)
	v_mfma_f32_16x16x32_bf16 v[202:205], v[206:209], v[56:59], v[202:205]
	s_waitcnt lgkmcnt(5)
	v_mfma_f32_16x16x32_bf16 v[206:209], v[210:213], v[60:63], 0
	s_waitcnt lgkmcnt(4)
	v_mfma_f32_16x16x32_bf16 v[206:209], v[214:217], v[56:59], v[206:209]
	s_waitcnt lgkmcnt(3)
	v_mfma_f32_16x16x32_bf16 v[210:213], v[218:221], v[60:63], 0
	s_waitcnt lgkmcnt(1)
	v_mfma_f32_16x16x32_bf16 v[214:217], v[226:229], v[60:63], 0
	v_mfma_f32_16x16x32_bf16 v[210:213], v[222:225], v[56:59], v[210:213]
	s_waitcnt lgkmcnt(0)
	v_mfma_f32_16x16x32_bf16 v[214:217], v[230:233], v[56:59], v[214:217]
	s_setprio 0
	v_fma_f32 v1, -v146, v141, v192
	v_fmamk_f32 v14, v202, 0x3e38aa3b, v1
	v_cmp_gt_u32_e32 vcc, s70, v0
	v_add_f32_e32 v15, v146, v1
	s_and_b64 vcc, vcc, s[0:1]
	v_fmac_f32_e32 v15, 0x3e38aa3b, v203
	v_cndmask_b32_e32 v14, v179, v14, vcc
	v_cmp_lt_i32_e32 vcc, 0, v0
	v_add_f32_e32 v202, v137, v1
	s_and_b64 vcc, vcc, s[0:1]
	v_add_u32_e32 v203, -2, v0
	v_fmac_f32_e32 v202, 0x3e38aa3b, v204
	v_cndmask_b32_e32 v15, v179, v15, vcc
	v_cmp_gt_u32_e32 vcc, s70, v203
	s_and_b64 vcc, s[0:1], vcc
	v_add_f32_e32 v1, v188, v1
	v_cndmask_b32_e32 v202, v179, v202, vcc
	v_add_u32_e32 v203, -3, v0
	v_fmac_f32_e32 v1, 0x3e38aa3b, v205
	v_cmp_gt_u32_e32 vcc, s70, v203
	v_exp_f32_e32 v219, v202
	v_fma_f32 v202, -v146, v141, v189
	s_and_b64 vcc, s[0:1], vcc
	v_fmamk_f32 v203, v206, 0x3e38aa3b, v202
	v_add_u32_e32 v206, -16, v0
	v_cndmask_b32_e32 v1, v179, v1, vcc
	v_cmp_gt_u32_e32 vcc, s70, v206
	v_add_f32_e32 v204, v146, v202
	s_and_b64 vcc, s[0:1], vcc
	v_subrev_u32_e32 v206, 17, v0
	v_fmac_f32_e32 v204, 0x3e38aa3b, v207
	v_cndmask_b32_e32 v203, v179, v203, vcc
	v_cmp_gt_u32_e32 vcc, s70, v206
	v_add_f32_e32 v205, v137, v202
	s_and_b64 vcc, vcc, s[0:1]
	v_subrev_u32_e32 v206, 18, v0
	v_fmac_f32_e32 v205, 0x3e38aa3b, v208
	v_cndmask_b32_e32 v204, v179, v204, vcc
	v_cmp_gt_u32_e32 vcc, s70, v206
	v_add_f32_e32 v202, v188, v202
	s_and_b64 vcc, s[0:1], vcc
	v_subrev_u32_e32 v206, 19, v0
	v_fmac_f32_e32 v202, 0x3e38aa3b, v209
	v_cndmask_b32_e32 v205, v179, v205, vcc
	v_cmp_gt_u32_e32 vcc, s70, v206
	s_and_b64 vcc, s[0:1], vcc
	v_subrev_u32_e32 v206, 32, v0
	v_cndmask_b32_e32 v202, v179, v202, vcc
	v_exp_f32_e32 v223, v202
	v_fma_f32 v202, -v146, v141, v190
	v_exp_f32_e32 v220, v203
	v_fmamk_f32 v203, v210, 0x3e38aa3b, v202
	v_cmp_gt_u32_e32 vcc, s70, v206
	v_exp_f32_e32 v221, v204
	v_add_f32_e32 v204, v146, v202
	s_and_b64 vcc, s[0:1], vcc
	v_subrev_u32_e32 v206, 33, v0
	v_fmac_f32_e32 v204, 0x3e38aa3b, v211
	v_cndmask_b32_e32 v203, v179, v203, vcc
	v_cmp_gt_u32_e32 vcc, s70, v206
	v_exp_f32_e32 v222, v205
	v_add_f32_e32 v205, v137, v202
	s_and_b64 vcc, vcc, s[0:1]
	v_subrev_u32_e32 v206, 34, v0
	v_fmac_f32_e32 v205, 0x3e38aa3b, v212
	v_cndmask_b32_e32 v204, v179, v204, vcc
	v_cmp_gt_u32_e32 vcc, s70, v206
	v_add_f32_e32 v202, v188, v202
	s_and_b64 vcc, s[0:1], vcc
	v_subrev_u32_e32 v206, 35, v0
	v_fmac_f32_e32 v202, 0x3e38aa3b, v213
	v_cndmask_b32_e32 v205, v179, v205, vcc
	v_cmp_gt_u32_e32 vcc, s70, v206
	s_and_b64 vcc, s[0:1], vcc
	v_subrev_u32_e32 v206, 48, v0
	v_cndmask_b32_e32 v202, v179, v202, vcc
	v_exp_f32_e32 v227, v202
	v_fma_f32 v202, -v146, v141, v191
	v_exp_f32_e32 v224, v203
	v_fmamk_f32 v203, v214, 0x3e38aa3b, v202
	v_cmp_gt_u32_e32 vcc, s70, v206
	v_exp_f32_e32 v225, v204
	v_add_f32_e32 v204, v146, v202
	s_and_b64 vcc, s[0:1], vcc
	v_subrev_u32_e32 v206, 49, v0
	v_fmac_f32_e32 v204, 0x3e38aa3b, v215
	v_cndmask_b32_e32 v203, v179, v203, vcc
	v_cmp_gt_u32_e32 vcc, s70, v206
	v_exp_f32_e32 v226, v205
	v_add_f32_e32 v205, v137, v202
	s_and_b64 vcc, vcc, s[0:1]
	v_subrev_u32_e32 v206, 50, v0
	v_fmac_f32_e32 v205, 0x3e38aa3b, v216
	v_cndmask_b32_e32 v204, v179, v204, vcc
	v_cmp_gt_u32_e32 vcc, s70, v206
	v_add_f32_e32 v202, v188, v202
	s_and_b64 vcc, s[0:1], vcc
	v_subrev_u32_e32 v0, 51, v0
	v_fmac_f32_e32 v202, 0x3e38aa3b, v217
	v_cndmask_b32_e32 v205, v179, v205, vcc
	v_cmp_gt_u32_e32 vcc, s70, v0
	s_and_b64 vcc, s[0:1], vcc
	v_exp_f32_e32 v228, v203
	v_cndmask_b32_e32 v0, v179, v202, vcc
	v_exp_f32_e32 v229, v204
	v_exp_f32_e32 v230, v205
	ds_read_b128 v[202:205], v193 offset:40960
	ds_read_b128 v[206:209], v193 offset:43520
	ds_read_b128 v[210:213], v193 offset:46080
	ds_read_b128 v[214:217], v193 offset:48640
	v_exp_f32_e32 v14, v14
	v_exp_f32_e32 v15, v15
	v_exp_f32_e32 v1, v1
	v_exp_f32_e32 v231, v0
	s_nop 0
	v_cvt_pk_bf16_f32 v218, v14, v15
	v_cvt_pk_bf16_f32 v219, v219, v1
	v_cvt_pk_bf16_f32 v220, v220, v221
	v_cvt_pk_bf16_f32 v221, v222, v223
	s_setprio 1
	s_waitcnt lgkmcnt(3)
	v_mfma_f32_16x16x32_bf16 v[0:3], v[202:205], v[218:221], v[2:5]
	s_waitcnt lgkmcnt(2)
	v_mfma_f32_16x16x32_bf16 v[4:7], v[206:209], v[218:221], v[6:9]
	s_waitcnt lgkmcnt(1)
	v_mfma_f32_16x16x32_bf16 v[8:11], v[210:213], v[218:221], v[10:13]
	s_waitcnt lgkmcnt(0)
	v_mfma_f32_16x16x32_bf16 v[12:15], v[214:217], v[218:221], v[198:201]
	v_mfma_f32_16x16x32_bf16 v[194:197], v[80:83], v[218:221], v[194:197]
	s_setprio 0
	s_nop 0
	ds_read_b128 v[198:201], v193 offset:41024
	ds_read_b128 v[202:205], v193 offset:43584
	ds_read_b128 v[206:209], v193 offset:46144
	ds_read_b128 v[210:213], v193 offset:48704
	v_cvt_pk_bf16_f32 v214, v224, v225
	v_cvt_pk_bf16_f32 v215, v226, v227
	v_cvt_pk_bf16_f32 v216, v228, v229
	v_cvt_pk_bf16_f32 v217, v230, v231
	s_setprio 1
	s_waitcnt lgkmcnt(3)
	v_mfma_f32_16x16x32_bf16 v[0:3], v[198:201], v[214:217], v[0:3]
	s_mov_b64 s[22:23], 0
	s_waitcnt lgkmcnt(2)
	v_mfma_f32_16x16x32_bf16 v[4:7], v[202:205], v[214:217], v[4:7]
	s_waitcnt lgkmcnt(1)
	v_mfma_f32_16x16x32_bf16 v[8:11], v[206:209], v[214:217], v[8:11]
	s_waitcnt lgkmcnt(0)
	v_mfma_f32_16x16x32_bf16 v[12:15], v[210:213], v[214:217], v[12:15]
	v_mfma_f32_16x16x32_bf16 v[80:83], v[80:83], v[214:217], v[194:197]
.LBB0_1046:
	s_andn2_b64 vcc, exec, s[22:23]
	s_cbranch_vccnz .LBB0_1048
	s_waitcnt lgkmcnt(7)
	v_mfma_f32_16x16x32_bf16 v[0:3], v[88:91], v[60:63], 0
	s_waitcnt lgkmcnt(5)
	v_mfma_f32_16x16x32_bf16 v[4:7], v[96:99], v[60:63], 0
	s_waitcnt lgkmcnt(3)
	v_mfma_f32_16x16x32_bf16 v[8:11], v[104:107], v[60:63], 0
	s_waitcnt lgkmcnt(1)
	v_mfma_f32_16x16x32_bf16 v[12:15], v[112:115], v[60:63], 0
	v_mfma_f32_16x16x32_bf16 v[0:3], v[92:95], v[56:59], v[0:3]
	v_mfma_f32_16x16x32_bf16 v[4:7], v[100:103], v[56:59], v[4:7]
	v_mfma_f32_16x16x32_bf16 v[8:11], v[108:111], v[56:59], v[8:11]
	s_waitcnt lgkmcnt(0)
	v_mfma_f32_16x16x32_bf16 v[12:15], v[116:119], v[56:59], v[12:15]
	s_setprio 0
	v_mul_f32_e64 v80, -v146, v147
	v_cndmask_b32_e64 v80, v179, v80, s[20:21]
	v_add_f32_e32 v81, v192, v80
	v_add_f32_e32 v82, v146, v81
	v_fmac_f32_e32 v82, 0x3e38aa3b, v1
	v_add_f32_e32 v1, v137, v81
	v_fmamk_f32 v0, v0, 0x3e38aa3b, v81
	v_fmac_f32_e32 v1, 0x3e38aa3b, v2
	v_add_f32_e32 v2, v188, v81
	v_fmac_f32_e32 v2, 0x3e38aa3b, v3
	s_nop 0
	v_exp_f32_e32 v81, v0
	v_add_f32_e32 v0, v189, v80
	v_exp_f32_e32 v83, v1
	v_exp_f32_e32 v88, v2
	v_fmamk_f32 v1, v4, 0x3e38aa3b, v0
	v_add_f32_e32 v2, v146, v0
	v_add_f32_e32 v3, v137, v0
	v_add_f32_e32 v0, v188, v0
	v_fmac_f32_e32 v0, 0x3e38aa3b, v7
	v_fmac_f32_e32 v2, 0x3e38aa3b, v5
	v_fmac_f32_e32 v3, 0x3e38aa3b, v6
	v_exp_f32_e32 v82, v82
	v_exp_f32_e32 v92, v0
	v_add_f32_e32 v0, v190, v80
	v_exp_f32_e32 v89, v1
	v_exp_f32_e32 v90, v2
	v_exp_f32_e32 v91, v3
	v_fmamk_f32 v1, v8, 0x3e38aa3b, v0
	v_add_f32_e32 v2, v146, v0
	v_add_f32_e32 v3, v137, v0
	v_add_f32_e32 v0, v188, v0
	v_fmac_f32_e32 v0, 0x3e38aa3b, v11
	v_fmac_f32_e32 v2, 0x3e38aa3b, v9
	v_fmac_f32_e32 v3, 0x3e38aa3b, v10
	s_nop 0
	v_exp_f32_e32 v96, v0
	v_add_f32_e32 v0, v191, v80
	v_exp_f32_e32 v93, v1
	v_exp_f32_e32 v94, v2
	v_exp_f32_e32 v95, v3
	v_fmamk_f32 v1, v12, 0x3e38aa3b, v0
	v_add_f32_e32 v2, v146, v0
	v_add_f32_e32 v3, v137, v0
	v_add_f32_e32 v0, v188, v0
	v_fmac_f32_e32 v2, 0x3e38aa3b, v13
	v_fmac_f32_e32 v3, 0x3e38aa3b, v14
	v_fmac_f32_e32 v0, 0x3e38aa3b, v15
	s_nop 0
	v_exp_f32_e32 v97, v1
	v_exp_f32_e32 v98, v2
	v_exp_f32_e32 v99, v3
	v_exp_f32_e32 v100, v0
	ds_read_b128 v[0:3], v143 offset:40960
	ds_read_b128 v[4:7], v143 offset:43520
	ds_read_b128 v[8:11], v143 offset:46080
	ds_read_b128 v[12:15], v143 offset:48640
	v_cvt_pk_bf16_f32 v80, v81, v82
	v_cvt_pk_bf16_f32 v81, v83, v88
	v_cvt_pk_bf16_f32 v82, v89, v90
	v_cvt_pk_bf16_f32 v83, v91, v92
	s_setprio 1
	s_mov_b32 s30, s28
	s_mov_b32 s31, s28
	s_waitcnt lgkmcnt(3)
	v_mfma_f32_16x16x32_bf16 v[0:3], v[0:3], v[80:83], v[36:39]
	s_mov_b32 s29, s28
	s_nop 1
	v_pk_mov_b32 v[38:39], s[30:31], s[30:31] op_sel:[0,1]
	v_pk_mov_b32 v[36:37], s[28:29], s[28:29] op_sel:[0,1]
	s_waitcnt lgkmcnt(2)
	v_mfma_f32_16x16x32_bf16 v[4:7], v[4:7], v[80:83], v[40:43]
	s_waitcnt lgkmcnt(1)
	v_mfma_f32_16x16x32_bf16 v[8:11], v[8:11], v[80:83], v[44:47]
	s_waitcnt lgkmcnt(0)
	v_mfma_f32_16x16x32_bf16 v[12:15], v[12:15], v[80:83], v[84:87]
	v_mfma_f32_16x16x32_bf16 v[32:35], v[36:39], v[80:83], v[32:35]
	s_setprio 0
	ds_read_b128 v[40:43], v143 offset:41024
	ds_read_b128 v[44:47], v143 offset:43584
	ds_read_b128 v[80:83], v143 offset:46144
	ds_read_b128 v[84:87], v143 offset:48704
	v_cvt_pk_bf16_f32 v88, v93, v94
	v_cvt_pk_bf16_f32 v89, v95, v96
	v_cvt_pk_bf16_f32 v90, v97, v98
	v_cvt_pk_bf16_f32 v91, v99, v100
	s_setprio 1
	s_waitcnt lgkmcnt(3)
	v_mfma_f32_16x16x32_bf16 v[0:3], v[40:43], v[88:91], v[0:3]
	s_waitcnt lgkmcnt(2)
	v_mfma_f32_16x16x32_bf16 v[4:7], v[44:47], v[88:91], v[4:7]
	s_waitcnt lgkmcnt(1)
	v_mfma_f32_16x16x32_bf16 v[8:11], v[80:83], v[88:91], v[8:11]
	s_waitcnt lgkmcnt(0)
	v_mfma_f32_16x16x32_bf16 v[12:15], v[84:87], v[88:91], v[12:15]
	v_mfma_f32_16x16x32_bf16 v[32:35], v[36:39], v[88:91], v[32:35]
	s_setprio 0
	s_sub_i32 s20, s81, 64
	s_and_b32 s20, s20, 0xc0
	s_mulk_i32 s20, 0xa0
	v_add_u32_e32 v104, s20, v153
	ds_read_b128 v[40:43], v104
	ds_read_b128 v[44:47], v104 offset:64
	ds_read_b128 v[80:83], v104 offset:2560
	ds_read_b128 v[84:87], v104 offset:2624
	ds_read_b128 v[88:91], v104 offset:5120
	ds_read_b128 v[92:95], v104 offset:5184
	ds_read_b128 v[96:99], v104 offset:7680
	ds_read_b128 v[100:103], v104 offset:7744
	s_setprio 1
	s_waitcnt lgkmcnt(7)
	v_mfma_f32_16x16x32_bf16 v[40:43], v[40:43], v[60:63], 0
	s_waitcnt lgkmcnt(6)
	v_mfma_f32_16x16x32_bf16 v[40:43], v[44:47], v[56:59], v[40:43]
	s_waitcnt lgkmcnt(5)
	v_mfma_f32_16x16x32_bf16 v[44:47], v[80:83], v[60:63], 0
	s_waitcnt lgkmcnt(3)
	v_mfma_f32_16x16x32_bf16 v[80:83], v[88:91], v[60:63], 0
	v_mfma_f32_16x16x32_bf16 v[44:47], v[84:87], v[56:59], v[44:47]
	s_waitcnt lgkmcnt(2)
	v_mfma_f32_16x16x32_bf16 v[80:83], v[92:95], v[56:59], v[80:83]
	s_waitcnt lgkmcnt(1)
	v_mfma_f32_16x16x32_bf16 v[84:87], v[96:99], v[60:63], 0
	s_waitcnt lgkmcnt(0)
	v_mfma_f32_16x16x32_bf16 v[84:87], v[100:103], v[56:59], v[84:87]
	s_setprio 0
	v_mul_f32_e64 v88, -v146, v141
	v_cndmask_b32_e64 v88, v179, v88, s[0:1]
	v_add_f32_e32 v89, v192, v88
	v_add_f32_e32 v90, v146, v89
	v_fmac_f32_e32 v90, 0x3e38aa3b, v41
	v_add_f32_e32 v41, v137, v89
	v_fmamk_f32 v40, v40, 0x3e38aa3b, v89
	v_fmac_f32_e32 v41, 0x3e38aa3b, v42
	v_add_f32_e32 v42, v188, v89
	v_fmac_f32_e32 v42, 0x3e38aa3b, v43
	s_nop 0
	v_exp_f32_e32 v89, v40
	v_add_f32_e32 v40, v189, v88
	v_exp_f32_e32 v91, v41
	v_exp_f32_e32 v92, v42
	v_fmamk_f32 v41, v44, 0x3e38aa3b, v40
	v_add_f32_e32 v42, v146, v40
	v_add_f32_e32 v43, v137, v40
	v_add_f32_e32 v40, v188, v40
	v_fmac_f32_e32 v40, 0x3e38aa3b, v47
	v_fmac_f32_e32 v42, 0x3e38aa3b, v45
	v_fmac_f32_e32 v43, 0x3e38aa3b, v46
	v_exp_f32_e32 v90, v90
	v_exp_f32_e32 v96, v40
	v_add_f32_e32 v40, v190, v88
	v_exp_f32_e32 v93, v41
	v_exp_f32_e32 v94, v42
	v_exp_f32_e32 v95, v43
	v_fmamk_f32 v41, v80, 0x3e38aa3b, v40
	v_add_f32_e32 v42, v146, v40
	v_add_f32_e32 v43, v137, v40
	v_add_f32_e32 v40, v188, v40
	v_fmac_f32_e32 v40, 0x3e38aa3b, v83
	v_fmac_f32_e32 v42, 0x3e38aa3b, v81
	v_fmac_f32_e32 v43, 0x3e38aa3b, v82
	s_nop 0
	v_exp_f32_e32 v100, v40
	v_add_f32_e32 v40, v191, v88
	v_exp_f32_e32 v97, v41
	v_exp_f32_e32 v98, v42
	v_exp_f32_e32 v99, v43
	v_fmamk_f32 v41, v84, 0x3e38aa3b, v40
	v_add_f32_e32 v42, v146, v40
	v_add_f32_e32 v43, v137, v40
	v_add_f32_e32 v40, v188, v40
	v_fmac_f32_e32 v42, 0x3e38aa3b, v85
	v_fmac_f32_e32 v43, 0x3e38aa3b, v86
	v_fmac_f32_e32 v40, 0x3e38aa3b, v87
	s_nop 0
	v_exp_f32_e32 v101, v41
	v_exp_f32_e32 v102, v42
	v_exp_f32_e32 v103, v43
	v_exp_f32_e32 v105, v40
	ds_read_b128 v[40:43], v104 offset:40960
	ds_read_b128 v[44:47], v104 offset:43520
	ds_read_b128 v[80:83], v104 offset:46080
	ds_read_b128 v[84:87], v104 offset:48640
	v_cvt_pk_bf16_f32 v88, v89, v90
	v_cvt_pk_bf16_f32 v89, v91, v92
	v_cvt_pk_bf16_f32 v90, v93, v94
	v_cvt_pk_bf16_f32 v91, v95, v96
	s_setprio 1
	s_waitcnt lgkmcnt(3)
	v_mfma_f32_16x16x32_bf16 v[0:3], v[40:43], v[88:91], v[0:3]
	s_waitcnt lgkmcnt(2)
	v_mfma_f32_16x16x32_bf16 v[4:7], v[44:47], v[88:91], v[4:7]
	s_waitcnt lgkmcnt(1)
	v_mfma_f32_16x16x32_bf16 v[8:11], v[80:83], v[88:91], v[8:11]
	s_waitcnt lgkmcnt(0)
	v_mfma_f32_16x16x32_bf16 v[12:15], v[84:87], v[88:91], v[12:15]
	v_mfma_f32_16x16x32_bf16 v[32:35], v[36:39], v[88:91], v[32:35]
	s_setprio 0
	ds_read_b128 v[40:43], v104 offset:41024
	ds_read_b128 v[44:47], v104 offset:43584
	ds_read_b128 v[80:83], v104 offset:46144
	ds_read_b128 v[84:87], v104 offset:48704
	v_cvt_pk_bf16_f32 v88, v97, v98
	v_cvt_pk_bf16_f32 v89, v99, v100
	v_cvt_pk_bf16_f32 v90, v101, v102
	v_cvt_pk_bf16_f32 v91, v103, v105
	s_setprio 1
	s_waitcnt lgkmcnt(3)
	v_mfma_f32_16x16x32_bf16 v[0:3], v[40:43], v[88:91], v[0:3]
	s_waitcnt lgkmcnt(2)
	v_mfma_f32_16x16x32_bf16 v[4:7], v[44:47], v[88:91], v[4:7]
	s_waitcnt lgkmcnt(1)
	v_mfma_f32_16x16x32_bf16 v[8:11], v[80:83], v[88:91], v[8:11]
	s_waitcnt lgkmcnt(0)
	v_mfma_f32_16x16x32_bf16 v[12:15], v[84:87], v[88:91], v[12:15]
	v_mfma_f32_16x16x32_bf16 v[80:83], v[36:39], v[88:91], v[32:35]

.Lsel_skip_pf:
	s_waitcnt lgkmcnt(0)
	s_barrier
	s_mov_b32 s32, s89
	s_mov_b32 s97, s91
	s_mov_b32 s89, s98
	s_mov_b32 s91, s99
	s_add_i32 s0, s83, 2
	s_add_i32 s1, s83, -2
	s_cmp_lt_u32 s1, s79
	s_cbranch_scc0 .LBB0_1051
	v_pk_mov_b32 v[32:33], v[80:81], v[80:81] op_sel:[0,1]
	s_mov_b32 s83, s0
	v_pk_mov_b32 v[34:35], v[82:83], v[82:83] op_sel:[0,1]
	v_pk_mov_b32 v[36:37], v[0:1], v[0:1] op_sel:[0,1]
	v_pk_mov_b32 v[38:39], v[2:3], v[2:3] op_sel:[0,1]
	v_pk_mov_b32 v[40:41], v[4:5], v[4:5] op_sel:[0,1]
	v_pk_mov_b32 v[42:43], v[6:7], v[6:7] op_sel:[0,1]
	v_pk_mov_b32 v[44:45], v[8:9], v[8:9] op_sel:[0,1]
	v_pk_mov_b32 v[46:47], v[10:11], v[10:11] op_sel:[0,1]
	v_pk_mov_b32 v[84:85], v[12:13], v[12:13] op_sel:[0,1]
	v_pk_mov_b32 v[86:87], v[14:15], v[14:15] op_sel:[0,1]
	s_branch .LBB0_1040

.LBB0_1054:
	s_lshl_b32 s20, s20, 6
	s_and_b32 s20, s20, 0x80
	s_mulk_i32 s20, 0xa0
	v_add_u32_e32 v104, s20, v153
	ds_read_b128 v[84:87], v104
	ds_read_b128 v[88:91], v104 offset:64
	ds_read_b128 v[92:95], v104 offset:2560
	ds_read_b128 v[96:99], v104 offset:2624
	ds_read_b128 v[32:35], v104 offset:5120
	ds_read_b128 v[36:39], v104 offset:5184
	ds_read_b128 v[40:43], v104 offset:7680
	ds_read_b128 v[44:47], v104 offset:7744
	v_lshl_or_b32 v16, s21, 6, v124
	v_sub_u32_e32 v16, v144, v16
	s_cmp_ge_i32 s21, s76
	s_setprio 1
	v_cvt_f32_i32_e32 v143, v16
	s_cbranch_scc0 .LBB0_1056
	s_waitcnt lgkmcnt(7)
	v_mfma_f32_16x16x32_bf16 v[18:21], v[84:87], v[60:63], 0
	s_waitcnt vmcnt(0) lgkmcnt(5)
	v_mfma_f32_16x16x32_bf16 v[22:25], v[92:95], v[60:63], 0
	s_waitcnt lgkmcnt(3)
	v_mfma_f32_16x16x32_bf16 v[26:29], v[32:35], v[60:63], 0
	s_waitcnt lgkmcnt(1)
	v_mfma_f32_16x16x32_bf16 v[100:103], v[40:43], v[60:63], 0
	v_mfma_f32_16x16x32_bf16 v[18:21], v[88:91], v[56:59], v[18:21]
	v_mfma_f32_16x16x32_bf16 v[22:25], v[96:99], v[56:59], v[22:25]
	v_mfma_f32_16x16x32_bf16 v[26:29], v[36:39], v[56:59], v[26:29]
	s_waitcnt lgkmcnt(0)
	v_mfma_f32_16x16x32_bf16 v[100:103], v[44:47], v[56:59], v[100:103]
	s_setprio 0
	v_add_u32_e32 v17, -2, v16
	v_cmp_gt_u32_e64 s[20:21], s70, v17
	v_add_u32_e32 v17, -3, v16
	v_pk_mul_f32 v[30:31], v[146:147], v[142:143] op_sel_hi:[0,1]
	v_cmp_gt_u32_e64 s[22:23], s70, v17
	v_fma_f32 v17, v146, 0, -v31
	v_cmp_gt_u32_e32 vcc, s70, v16
	v_fmamk_f32 v18, v18, 0x3e38aa3b, v17
	v_cmp_lt_i32_e64 s[0:1], 0, v16
	v_add_f32_e32 v105, v146, v17
	s_and_b64 vcc, vcc, s[26:27]
	v_fmac_f32_e32 v105, 0x3e38aa3b, v19
	v_cndmask_b32_e32 v18, v179, v18, vcc
	s_and_b64 vcc, s[0:1], s[26:27]
	v_mov_b32_e32 v147, v24
	v_cndmask_b32_e32 v19, v179, v105, vcc
	v_exp_f32_e32 v105, v18
	v_exp_f32_e32 v106, v19
	v_sub_f32_e32 v30, v30, v31
	v_pk_mul_f32 v[18:19], v[146:147], s[44:45]
	v_fmamk_f32 v107, v22, 0x3e38aa3b, v30
	v_add_f32_e32 v22, v18, v17
	v_fmac_f32_e32 v22, 0x3e38aa3b, v20
	v_add_f32_e32 v108, v146, v30
	s_and_b64 vcc, s[26:27], s[20:21]
	v_mov_b32_e32 v147, v25
	s_mov_b32 s47, s45
	v_fmac_f32_e32 v108, 0x3e38aa3b, v23
	v_cndmask_b32_e32 v20, v179, v22, vcc
	v_pk_mul_f32 v[22:23], v[146:147], s[46:47]
	v_exp_f32_e32 v109, v20
	v_add_f32_e32 v17, v22, v17
	v_add_f32_e32 v20, v18, v30
	v_fmac_f32_e32 v17, 0x3e38aa3b, v21
	v_add_f32_e32 v19, v20, v19
	s_and_b64 vcc, s[26:27], s[22:23]
	v_add_u32_e32 v20, -16, v16
	v_cndmask_b32_e32 v17, v179, v17, vcc
	v_cmp_gt_u32_e32 vcc, s70, v20
	s_and_b64 vcc, s[26:27], vcc
	v_subrev_u32_e32 v21, 17, v16
	v_exp_f32_e32 v110, v17
	v_add_f32_e32 v17, v22, v30
	v_add_f32_e32 v17, v17, v23
	v_cndmask_b32_e32 v20, v179, v107, vcc
	v_cmp_gt_u32_e32 vcc, s70, v21
	s_and_b64 vcc, vcc, s[26:27]
	v_subrev_u32_e32 v23, 18, v16
	v_exp_f32_e32 v107, v20
	v_cndmask_b32_e32 v21, v179, v108, vcc
	v_cmp_gt_u32_e32 vcc, s70, v23
	s_and_b64 vcc, s[26:27], vcc
	v_subrev_u32_e32 v23, 19, v16
	v_cndmask_b32_e32 v19, v179, v19, vcc
	v_cmp_gt_u32_e32 vcc, s70, v23
	s_and_b64 vcc, s[26:27], vcc
	v_subrev_u32_e32 v23, 32, v16
	v_cndmask_b32_e32 v17, v179, v17, vcc
	v_exp_f32_e32 v112, v17
	v_fma_f32 v17, v146, s65, -v31
	v_exp_f32_e32 v111, v19
	v_fmamk_f32 v19, v26, 0x3e38aa3b, v17
	v_cmp_gt_u32_e32 vcc, s70, v23
	v_add_f32_e32 v20, v146, v17
	s_and_b64 vcc, s[26:27], vcc
	v_subrev_u32_e32 v23, 33, v16
	v_fmac_f32_e32 v20, 0x3e38aa3b, v27
	v_cndmask_b32_e32 v19, v179, v19, vcc
	v_cmp_gt_u32_e32 vcc, s70, v23
	v_exp_f32_e32 v108, v21
	v_add_f32_e32 v21, v18, v17
	s_and_b64 vcc, vcc, s[26:27]
	v_subrev_u32_e32 v23, 34, v16
	v_fmac_f32_e32 v21, 0x3e38aa3b, v28
	v_cndmask_b32_e32 v20, v179, v20, vcc
	v_cmp_gt_u32_e32 vcc, s70, v23
	v_add_f32_e32 v17, v22, v17
	s_and_b64 vcc, s[26:27], vcc
	v_subrev_u32_e32 v23, 35, v16
	v_fmac_f32_e32 v17, 0x3e38aa3b, v29
	v_cndmask_b32_e32 v21, v179, v21, vcc
	v_cmp_gt_u32_e32 vcc, s70, v23
	s_and_b64 vcc, s[26:27], vcc
	v_exp_f32_e32 v139, v21
	v_cndmask_b32_e32 v17, v179, v17, vcc
	v_exp_f32_e32 v141, v17
	v_fma_f32 v17, v146, s66, -v31
	v_subrev_u32_e32 v21, 48, v16
	v_exp_f32_e32 v118, v19
	v_fmamk_f32 v19, v100, 0x3e38aa3b, v17
	v_cmp_gt_u32_e32 vcc, s70, v21
	v_exp_f32_e32 v119, v20
	v_add_f32_e32 v20, v146, v17
	s_and_b64 vcc, s[26:27], vcc
	v_subrev_u32_e32 v21, 49, v16
	v_fmac_f32_e32 v20, 0x3e38aa3b, v101
	v_cndmask_b32_e32 v19, v179, v19, vcc
	v_cmp_gt_u32_e32 vcc, s70, v21
	v_add_f32_e32 v18, v18, v17
	s_and_b64 vcc, vcc, s[26:27]
	v_subrev_u32_e32 v21, 50, v16
	v_fmac_f32_e32 v18, 0x3e38aa3b, v102
	v_cndmask_b32_e32 v20, v179, v20, vcc
	v_cmp_gt_u32_e32 vcc, s70, v21
	s_and_b64 vcc, s[26:27], vcc
	v_subrev_u32_e32 v16, 51, v16
	v_add_f32_e32 v17, v22, v17
	v_cndmask_b32_e32 v18, v179, v18, vcc
	v_cmp_gt_u32_e32 vcc, s70, v16
	v_fmac_f32_e32 v17, 0x3e38aa3b, v103
	s_and_b64 vcc, s[26:27], vcc
	v_exp_f32_e32 v147, v19
	v_cndmask_b32_e32 v16, v179, v17, vcc
	v_exp_f32_e32 v148, v20
	v_exp_f32_e32 v149, v18
	v_exp_f32_e32 v193, v16
	ds_read_b128 v[16:19], v104 offset:40960
	ds_read_b128 v[20:23], v104 offset:43520
	ds_read_b128 v[24:27], v104 offset:46080
	ds_read_b128 v[28:31], v104 offset:48640
	s_nop 0
	v_cvt_pk_bf16_f32 v100, v105, v106
	v_cvt_pk_bf16_f32 v101, v109, v110
	v_cvt_pk_bf16_f32 v102, v107, v108
	v_cvt_pk_bf16_f32 v103, v111, v112
	s_setprio 1
	s_mov_b32 s30, s28
	s_mov_b32 s31, s28
	s_mov_b32 s29, s28
	v_pk_mov_b32 v[108:109], s[30:31], s[30:31] op_sel:[0,1]
	v_pk_mov_b32 v[106:107], s[28:29], s[28:29] op_sel:[0,1]
	s_waitcnt lgkmcnt(3)
	v_mfma_f32_16x16x32_bf16 v[16:19], v[16:19], v[100:103], v[0:3]
	s_waitcnt lgkmcnt(2)
	v_mfma_f32_16x16x32_bf16 v[20:23], v[20:23], v[100:103], v[4:7]
	s_waitcnt lgkmcnt(1)
	v_mfma_f32_16x16x32_bf16 v[24:27], v[24:27], v[100:103], v[8:11]
	s_waitcnt lgkmcnt(0)
	v_mfma_f32_16x16x32_bf16 v[28:31], v[28:31], v[100:103], v[12:15]
	v_mfma_f32_16x16x32_bf16 v[100:103], v[106:109], v[100:103], v[80:83]
	s_setprio 0
	ds_read_b128 v[110:113], v104 offset:41024
	ds_read_b128 v[114:117], v104 offset:43584
	ds_read_b128 v[194:197], v104 offset:46144
	ds_read_b128 v[198:201], v104 offset:48704
	v_cvt_pk_bf16_f32 v202, v118, v119
	v_cvt_pk_bf16_f32 v203, v139, v141
	v_cvt_pk_bf16_f32 v204, v147, v148
	v_cvt_pk_bf16_f32 v205, v149, v193
	s_setprio 1
	s_waitcnt lgkmcnt(3)
	v_mfma_f32_16x16x32_bf16 v[16:19], v[110:113], v[202:205], v[16:19]
	s_mov_b64 s[0:1], 0
	s_waitcnt lgkmcnt(2)
	v_mfma_f32_16x16x32_bf16 v[20:23], v[114:117], v[202:205], v[20:23]
	s_waitcnt lgkmcnt(1)
	v_mfma_f32_16x16x32_bf16 v[24:27], v[194:197], v[202:205], v[24:27]
	s_waitcnt lgkmcnt(0)
	v_mfma_f32_16x16x32_bf16 v[28:31], v[198:201], v[202:205], v[28:31]
	v_mfma_f32_16x16x32_bf16 v[100:103], v[106:109], v[202:205], v[100:103]
.LBB0_1056:
	s_andn2_b64 vcc, exec, s[0:1]
	s_cbranch_vccnz .LBB0_1058
	s_waitcnt lgkmcnt(7)
	v_mfma_f32_16x16x32_bf16 v[16:19], v[84:87], v[60:63], 0
	s_waitcnt lgkmcnt(5)
	v_mfma_f32_16x16x32_bf16 v[20:23], v[92:95], v[60:63], 0
	s_waitcnt vmcnt(0) lgkmcnt(3)
	v_mfma_f32_16x16x32_bf16 v[24:27], v[32:35], v[60:63], 0
	s_waitcnt lgkmcnt(1)
	v_mfma_f32_16x16x32_bf16 v[28:31], v[40:43], v[60:63], 0
	v_mfma_f32_16x16x32_bf16 v[16:19], v[88:91], v[56:59], v[16:19]
	v_mfma_f32_16x16x32_bf16 v[20:23], v[96:99], v[56:59], v[20:23]
	v_mfma_f32_16x16x32_bf16 v[24:27], v[36:39], v[56:59], v[24:27]
	s_waitcnt lgkmcnt(0)
	v_mfma_f32_16x16x32_bf16 v[28:31], v[44:47], v[56:59], v[28:31]
	s_setprio 0
	v_mul_f32_e64 v32, -v146, v143
	v_cndmask_b32_e64 v32, v179, v32, s[26:27]
	v_fma_f32 v33, 0, v146, v32
	v_fmamk_f32 v16, v16, 0x3e38aa3b, v33
	v_add_f32_e32 v34, v146, v33
	v_mov_b32_e32 v147, v22
	v_fmac_f32_e32 v34, 0x3e38aa3b, v17
	v_exp_f32_e32 v35, v16
	v_fmamk_f32 v36, v146, 0x41800000, v32
	v_pk_mul_f32 v[16:17], v[146:147], s[44:45]
	v_fmamk_f32 v37, v20, 0x3e38aa3b, v36
	v_add_f32_e32 v20, v16, v33
	v_fmac_f32_e32 v20, 0x3e38aa3b, v18
	v_add_f32_e32 v38, v146, v36
	v_mov_b32_e32 v147, v23
	s_mov_b32 s47, s45
	v_fmac_f32_e32 v38, 0x3e38aa3b, v21
	v_exp_f32_e32 v39, v20
	v_add_f32_e32 v18, v16, v36
	v_pk_mul_f32 v[20:21], v[146:147], s[46:47]
	v_add_f32_e32 v17, v18, v17
	v_add_f32_e32 v18, v20, v33
	v_fmac_f32_e32 v18, 0x3e38aa3b, v19
	s_nop 0
	v_exp_f32_e32 v33, v18
	v_add_f32_e32 v18, v20, v36
	v_add_f32_e32 v18, v18, v21
	v_exp_f32_e32 v36, v37
	v_exp_f32_e32 v37, v38
	v_exp_f32_e32 v38, v17
	v_fmamk_f32 v17, v146, 0x42000000, v32
	v_add_f32_e32 v19, v146, v17
	v_exp_f32_e32 v40, v18
	v_fmamk_f32 v18, v24, 0x3e38aa3b, v17
	v_fmac_f32_e32 v19, 0x3e38aa3b, v25
	v_add_f32_e32 v21, v16, v17
	v_add_f32_e32 v17, v20, v17
	v_fmac_f32_e32 v17, 0x3e38aa3b, v27
	v_fmac_f32_e32 v32, 0x42400000, v146
	v_exp_f32_e32 v41, v18
	v_exp_f32_e32 v42, v19
	v_add_f32_e32 v18, v146, v32
	v_add_f32_e32 v16, v16, v32
	v_add_f32_e32 v19, v20, v32
	v_fmac_f32_e32 v21, 0x3e38aa3b, v26
	v_exp_f32_e32 v44, v17
	v_fmamk_f32 v17, v28, 0x3e38aa3b, v32
	v_fmac_f32_e32 v18, 0x3e38aa3b, v29
	v_fmac_f32_e32 v16, 0x3e38aa3b, v30
	v_fmac_f32_e32 v19, 0x3e38aa3b, v31
	v_exp_f32_e32 v34, v34
	v_exp_f32_e32 v43, v21
	v_exp_f32_e32 v45, v17
	v_exp_f32_e32 v46, v18
	v_exp_f32_e32 v47, v16
	v_exp_f32_e32 v84, v19
	ds_read_b128 v[16:19], v104 offset:40960
	ds_read_b128 v[20:23], v104 offset:43520
	ds_read_b128 v[24:27], v104 offset:46080
	ds_read_b128 v[28:31], v104 offset:48640
	s_nop 0
	v_cvt_pk_bf16_f32 v32, v35, v34
	v_cvt_pk_bf16_f32 v33, v39, v33
	v_cvt_pk_bf16_f32 v34, v36, v37
	v_cvt_pk_bf16_f32 v35, v38, v40
	s_setprio 1
	s_mov_b32 s30, s28
	s_mov_b32 s31, s28
	s_mov_b32 s29, s28
	v_pk_mov_b32 v[38:39], s[30:31], s[30:31] op_sel:[0,1]
	v_pk_mov_b32 v[36:37], s[28:29], s[28:29] op_sel:[0,1]
	s_waitcnt lgkmcnt(3)
	v_mfma_f32_16x16x32_bf16 v[0:3], v[16:19], v[32:35], v[0:3]
	s_waitcnt lgkmcnt(2)
	v_mfma_f32_16x16x32_bf16 v[4:7], v[20:23], v[32:35], v[4:7]
	s_waitcnt lgkmcnt(1)
	v_mfma_f32_16x16x32_bf16 v[8:11], v[24:27], v[32:35], v[8:11]
	s_waitcnt lgkmcnt(0)
	v_mfma_f32_16x16x32_bf16 v[12:15], v[28:31], v[32:35], v[12:15]
	v_mfma_f32_16x16x32_bf16 v[32:35], v[36:39], v[32:35], v[80:83]
	s_setprio 0
	ds_read_b128 v[16:19], v104 offset:41024
	ds_read_b128 v[20:23], v104 offset:43584
	ds_read_b128 v[24:27], v104 offset:46144
	ds_read_b128 v[28:31], v104 offset:48704
	v_cvt_pk_bf16_f32 v40, v41, v42
	v_cvt_pk_bf16_f32 v41, v43, v44
	v_cvt_pk_bf16_f32 v42, v45, v46
	v_cvt_pk_bf16_f32 v43, v47, v84
	s_setprio 1
	s_waitcnt lgkmcnt(3)
	v_mfma_f32_16x16x32_bf16 v[16:19], v[16:19], v[40:43], v[0:3]
	s_waitcnt lgkmcnt(2)
	v_mfma_f32_16x16x32_bf16 v[20:23], v[20:23], v[40:43], v[4:7]
	s_waitcnt lgkmcnt(1)
	v_mfma_f32_16x16x32_bf16 v[24:27], v[24:27], v[40:43], v[8:11]
	s_waitcnt lgkmcnt(0)
	v_mfma_f32_16x16x32_bf16 v[28:31], v[28:31], v[40:43], v[12:15]
	v_mfma_f32_16x16x32_bf16 v[100:103], v[36:39], v[40:43], v[32:35]
.LBB0_1058:
	s_setprio 0
	s_waitcnt lgkmcnt(0)
	s_barrier
	s_waitcnt vmcnt(0)
	v_pk_mov_b32 v[0:1], v[16:17], v[16:17] op_sel:[0,1]
	s_nop 3
	v_pk_mov_b32 v[80:81], v[100:101], v[100:101] op_sel:[0,1]
	v_pk_mov_b32 v[2:3], v[18:19], v[18:19] op_sel:[0,1]
	v_pk_mov_b32 v[4:5], v[20:21], v[20:21] op_sel:[0,1]
	v_pk_mov_b32 v[6:7], v[22:23], v[22:23] op_sel:[0,1]
	v_pk_mov_b32 v[8:9], v[24:25], v[24:25] op_sel:[0,1]
	v_pk_mov_b32 v[10:11], v[26:27], v[26:27] op_sel:[0,1]
	v_pk_mov_b32 v[12:13], v[28:29], v[28:29] op_sel:[0,1]
	v_pk_mov_b32 v[14:15], v[30:31], v[30:31] op_sel:[0,1]
	v_pk_mov_b32 v[82:83], v[102:103], v[102:103] op_sel:[0,1]
.LBB0_1059:
	s_lshl_b32 s0, s80, 1
	s_add_u32 s0, s57, s0
	s_addc_u32 s1, s60, 0
	s_add_i32 s20, s74, 0xfffffe01
	s_andn2_b32 s20, s20, 63
	s_cmp_gt_i32 s75, 31
	s_cselect_b32 s20, s20, 0
	s_sub_i32 s21, s74, s20
	s_ashr_i32 s21, s21, 6
	s_min_i32 s22, s21, 0
	s_lshl_b32 s22, s22, 6
	s_add_i32 s22, s22, s20
	s_ashr_i32 s23, s22, 31
	s_lshl_b64 s[26:27], s[22:23], 12
	s_add_u32 s26, s24, s26
	s_addc_u32 s27, s25, s27
	s_lshl_b64 s[22:23], s[22:23], 1
	s_add_u32 s22, s0, s22
	s_addc_u32 s23, s1, s23
	v_mov_b32_e32 v141, v123
	s_waitcnt vmcnt(2)
	v_lshl_add_u64 v[18:19], s[22:23], 0, v[140:141]
	s_min_i32 s22, s21, 1
	s_lshl_b32 s22, s22, 6
	s_add_i32 s22, s22, s20
	v_mov_b32_e32 v139, v123
	s_ashr_i32 s23, s22, 31
	v_lshl_add_u64 v[16:17], s[26:27], 0, v[138:139]
	s_lshl_b64 s[26:27], s[22:23], 12
	s_add_u32 s26, s24, s26
	s_addc_u32 s27, s25, s27
	s_lshl_b64 s[22:23], s[22:23], 1
	s_add_u32 s22, s0, s22
	s_addc_u32 s23, s1, s23
	v_lshl_add_u64 v[16:17], v[16:17], 0, v[122:123]
	v_lshl_add_u64 v[20:21], v[18:19], 0, v[122:123]
	s_waitcnt vmcnt(0)
	v_lshl_add_u64 v[24:25], s[26:27], 0, v[138:139]
	v_lshl_add_u64 v[26:27], s[22:23], 0, v[140:141]
	v_pk_mov_b32 v[16:17], v[240:241], v[240:241] op_sel:[0,1]
	v_pk_mov_b32 v[18:19], v[242:243], v[242:243] op_sel:[0,1]
	s_nop 0
	v_pk_mov_b32 v[20:21], v[244:245], v[244:245] op_sel:[0,1]
	v_pk_mov_b32 v[22:23], v[246:247], v[246:247] op_sel:[0,1]
	v_lshl_add_u64 v[24:25], v[24:25], 0, v[122:123]
	v_lshl_add_u64 v[28:29], v[26:27], 0, v[122:123]
	v_pk_mov_b32 v[24:25], v[248:249], v[248:249] op_sel:[0,1]
	v_pk_mov_b32 v[26:27], v[250:251], v[250:251] op_sel:[0,1]
	s_nop 0
	v_pk_mov_b32 v[28:29], v[252:253], v[252:253] op_sel:[0,1]
	v_pk_mov_b32 v[30:31], v[254:255], v[254:255] op_sel:[0,1]
	s_min_i32 s22, s21, 2
	s_lshl_b32 s22, s22, 6
	s_add_i32 s22, s22, s20
	s_ashr_i32 s23, s22, 31
	s_lshl_b64 s[26:27], s[22:23], 12
	s_add_u32 s26, s24, s26
	s_addc_u32 s27, s25, s27
	s_lshl_b64 s[22:23], s[22:23], 1
	s_add_u32 s22, s0, s22
	s_waitcnt lgkmcnt(3)
	v_lshl_add_u64 v[32:33], s[26:27], 0, v[138:139]
	s_addc_u32 s23, s1, s23
	s_min_i32 s26, s21, 3
	v_lshl_add_u64 v[34:35], s[22:23], 0, v[140:141]
	s_lshl_b32 s22, s26, 6
	s_add_i32 s22, s22, s20
	s_ashr_i32 s23, s22, 31
	s_lshl_b64 s[26:27], s[22:23], 12
	s_add_u32 s24, s24, s26
	s_addc_u32 s25, s25, s27
	s_lshl_b64 s[22:23], s[22:23], 1
	s_add_u32 s22, s0, s22
	v_lshl_add_u64 v[32:33], v[32:33], 0, v[122:123]
	v_lshl_add_u64 v[34:35], v[34:35], 0, v[122:123]
	s_addc_u32 s23, s1, s23
	s_waitcnt lgkmcnt(2)
	global_load_dwordx4 v[36:39], v[32:33], off offset:3072
	s_nop 0
	global_load_dwordx4 v[32:35], v[34:35], off
	s_waitcnt lgkmcnt(1)
	v_lshl_add_u64 v[40:41], s[24:25], 0, v[138:139]
	v_lshl_add_u64 v[42:43], s[22:23], 0, v[140:141]
	v_lshl_add_u64 v[40:41], v[40:41], 0, v[122:123]
	v_lshl_add_u64 v[42:43], v[42:43], 0, v[122:123]
	s_mov_b32 s23, 0
	s_cmp_lt_i32 s21, 1
	s_mov_b32 s24, 0
	s_waitcnt vmcnt(5)
	ds_write_b128 v151, v[16:19]
	s_waitcnt vmcnt(4)
	ds_write2_b64 v187, v[20:21], v[22:23] offset1:2
	s_waitcnt vmcnt(3)
	ds_write_b128 v151, v[24:27] offset:10240
	s_waitcnt vmcnt(2)
	ds_write2_b64 v186, v[28:29], v[30:31] offset1:2
	s_waitcnt lgkmcnt(4)
	global_load_dwordx4 v[44:47], v[40:41], off offset:3072
	s_nop 0
	global_load_dwordx4 v[40:43], v[42:43], off
	s_cselect_b32 s91, 1, 0
	s_add_i32 s98, s90, -1
	s_ashr_i32 s98, s98, 6
	s_cmp_gt_i32 s98, 0
	s_cselect_b32 s99, 0x2000, 0
	s_cselect_b32 s98, 0x80, 0
	s_and_b32 s29, s73, 3
	s_lshl_b32 s29, s29, 1
	s_bfe_u32 s30, s73, 0x10002
	s_or_b32 s29, s29, s30
	s_bfe_u32 s30, s73, 0x1000b
	s_xor_b32 s29, s29, s30
	s_lshl_b32 s29, s29, 16
	s_add_u32 s100, s3, s29
	s_addc_u32 s101, s52, 0
	s_add_u32 s30, s53, s29
	s_addc_u32 s31, s54, 0
	v_mov_b32_e32 v194, v134
	v_mov_b32_e32 v195, 0
	v_mov_b32_e32 v196, v136
	v_mov_b32_e32 v197, 0
	v_lshl_add_u64 v[198:199], s[100:101], 0, v[194:195]
	v_lshl_add_u64 v[200:201], s[30:31], 0, v[196:197]
	v_lshl_add_u64 v[198:199], v[198:199], 0, v[122:123]
	v_lshl_add_u64 v[200:201], v[200:201], 0, v[122:123]
	global_load_dwordx4 v[240:243], v[198:199], off
	global_load_dwordx4 v[244:247], v[200:201], off
	s_add_u32 s100, s100, s99
	s_addc_u32 s101, s101, 0
	s_add_u32 s30, s30, s98
	s_addc_u32 s31, s31, 0
	v_lshl_add_u64 v[198:199], s[100:101], 0, v[194:195]
	v_lshl_add_u64 v[200:201], s[30:31], 0, v[196:197]
	v_lshl_add_u64 v[198:199], v[198:199], 0, v[122:123]
	v_lshl_add_u64 v[200:201], v[200:201], 0, v[122:123]
	global_load_dwordx4 v[248:251], v[198:199], off
	global_load_dwordx4 v[252:255], v[200:201], off
	s_cmp_lg_u32 s91, 0
	s_waitcnt lgkmcnt(0)
	s_barrier
	s_cbranch_scc1 .LBB0_1068
	v_lshl_add_u64 v[16:17], s[0:1], 0, v[140:141]
	v_lshl_add_u64 v[106:107], v[16:17], 0, v[122:123]
	v_add_u32_e32 v16, s74, v171
	v_mov_b32_e32 v86, 0
	s_add_i32 s22, s74, 0xfffffe10
	v_subrev_u32_e32 v81, s20, v16
	v_mov_b32_e32 v87, v86
	v_mov_b32_e32 v88, v86
	v_mov_b32_e32 v89, v86
	s_mov_b32 s23, 5
	v_mov_b32_e32 v90, v86
	v_mov_b32_e32 v91, v86
	v_mov_b32_e32 v92, v86
	v_mov_b32_e32 v93, v86
	v_mov_b32_e32 v94, v86
	v_mov_b32_e32 v95, v86
	v_mov_b32_e32 v96, v86
	v_mov_b32_e32 v97, v86
	v_mov_b32_e32 v98, v86
	v_mov_b32_e32 v99, v86
	v_mov_b32_e32 v100, v86
	v_mov_b32_e32 v101, v86
	v_mov_b32_e32 v102, v86
	v_mov_b32_e32 v103, v86
	v_mov_b32_e32 v104, v86
	v_mov_b32_e32 v105, v86
.LBB0_1061:
	s_add_i32 s26, s20, s24
	s_add_i32 s0, s26, 63
	s_cmp_gt_i32 s0, s74
	s_cselect_b64 s[0:1], -1, 0
	s_cmp_lt_i32 s26, s22
	s_cselect_b64 s[30:31], -1, 0
	s_or_b64 s[0:1], s[0:1], s[30:31]
	v_add_u32_e32 v109, 0x73, v81
	v_add_u32_e32 v108, 51, v81
	s_add_i32 s25, s24, 64
	s_and_b64 vcc, exec, s[0:1]
	s_cbranch_vccnz .LBB0_1064
	s_add_i32 s27, s26, 64
	s_addk_i32 s26, 0x7f
	s_cmp_le_i32 s26, s74
	s_cselect_b64 s[0:1], -1, 0
	s_cmp_ge_i32 s27, s22
	s_cselect_b64 s[26:27], -1, 0
	s_and_b64 s[26:27], s[26:27], s[0:1]
	s_mov_b64 s[0:1], -1
	s_and_b64 vcc, exec, s[26:27]
	s_cbranch_vccz .LBB0_1064
	s_and_b32 s0, s24, 0x80
	s_mulk_i32 s0, 0xa0
	v_add_u32_e32 v118, s0, v153
	ds_read_b128 v[16:19], v118
	ds_read_b128 v[20:23], v118 offset:64
	ds_read_b128 v[24:27], v118 offset:2560
	ds_read_b128 v[28:31], v118 offset:2624
	ds_read_b128 v[82:85], v118 offset:5120
	ds_read_b128 v[110:113], v118 offset:5184
	ds_read_b128 v[114:117], v118 offset:7680
	ds_read_b128 v[194:197], v118 offset:7744
	s_setprio 1
	s_waitcnt lgkmcnt(7)
	v_mfma_f32_16x16x32_bf16 v[16:19], v[16:19], v[60:63], 0
	s_waitcnt lgkmcnt(6)
	v_mfma_f32_16x16x32_bf16 v[16:19], v[20:23], v[56:59], v[16:19]
	s_waitcnt lgkmcnt(5)
	v_mfma_f32_16x16x32_bf16 v[20:23], v[24:27], v[60:63], 0
	s_waitcnt lgkmcnt(4)
	v_mfma_f32_16x16x32_bf16 v[20:23], v[28:31], v[56:59], v[20:23]
	s_waitcnt lgkmcnt(3)
	v_mfma_f32_16x16x32_bf16 v[24:27], v[82:85], v[60:63], 0
	s_waitcnt lgkmcnt(1)
	v_mfma_f32_16x16x32_bf16 v[28:31], v[114:117], v[60:63], 0
	v_mfma_f32_16x16x32_bf16 v[24:27], v[110:113], v[56:59], v[24:27]
	s_waitcnt lgkmcnt(0)
	v_mfma_f32_16x16x32_bf16 v[28:31], v[194:197], v[56:59], v[28:31]
	s_setprio 0
	v_cvt_f32_i32_e32 v82, v109
	v_fma_f32 v83, -v146, v82, v192
	v_add_f32_e32 v84, v146, v83
	v_fmamk_f32 v16, v16, 0x3e38aa3b, v83
	v_fmac_f32_e32 v84, 0x3e38aa3b, v17
	v_add_f32_e32 v17, v188, v83
	v_fmac_f32_e32 v17, 0x3e38aa3b, v19
	v_add_f32_e32 v85, v137, v83
	v_exp_f32_e32 v83, v16
	v_fma_f32 v16, -v146, v82, v189
	v_fmac_f32_e32 v85, 0x3e38aa3b, v18
	v_exp_f32_e32 v110, v17
	v_fmamk_f32 v17, v20, 0x3e38aa3b, v16
	v_add_f32_e32 v18, v146, v16
	v_add_f32_e32 v19, v137, v16
	v_add_f32_e32 v16, v188, v16
	v_fmac_f32_e32 v16, 0x3e38aa3b, v23
	v_fmac_f32_e32 v18, 0x3e38aa3b, v21
	v_fmac_f32_e32 v19, 0x3e38aa3b, v22
	s_nop 0
	v_exp_f32_e32 v114, v16
	v_fma_f32 v16, -v146, v82, v190
	v_exp_f32_e32 v111, v17
	v_exp_f32_e32 v112, v18
	v_exp_f32_e32 v113, v19
	v_fmamk_f32 v17, v24, 0x3e38aa3b, v16
	v_add_f32_e32 v18, v146, v16
	v_add_f32_e32 v19, v137, v16
	v_add_f32_e32 v16, v188, v16
	v_fmac_f32_e32 v16, 0x3e38aa3b, v27
	v_fmac_f32_e32 v18, 0x3e38aa3b, v25
	v_fmac_f32_e32 v19, 0x3e38aa3b, v26
	v_exp_f32_e32 v84, v84
	v_exp_f32_e32 v143, v16
	v_fma_f32 v16, -v146, v82, v191
	v_exp_f32_e32 v119, v17
	v_exp_f32_e32 v139, v18
	v_exp_f32_e32 v141, v19
	v_fmamk_f32 v17, v28, 0x3e38aa3b, v16
	v_add_f32_e32 v18, v146, v16
	v_add_f32_e32 v19, v137, v16
	v_add_f32_e32 v16, v188, v16
	v_fmac_f32_e32 v18, 0x3e38aa3b, v29
	v_fmac_f32_e32 v19, 0x3e38aa3b, v30
	v_fmac_f32_e32 v16, 0x3e38aa3b, v31
	v_exp_f32_e32 v85, v85
	v_exp_f32_e32 v147, v17
	v_exp_f32_e32 v148, v18
	v_exp_f32_e32 v149, v19
	v_exp_f32_e32 v186, v16
	ds_read_b128 v[16:19], v118 offset:40960
	ds_read_b128 v[20:23], v118 offset:43520
	ds_read_b128 v[24:27], v118 offset:46080
	ds_read_b128 v[28:31], v118 offset:48640
	s_nop 0
	v_cvt_pk_bf16_f32 v82, v83, v84
	v_cvt_pk_bf16_f32 v83, v85, v110
	v_cvt_pk_bf16_f32 v84, v111, v112
	v_cvt_pk_bf16_f32 v85, v113, v114
	s_setprio 1
	s_mov_b32 s30, s28
	s_mov_b32 s31, s28
	s_mov_b32 s29, s28
	v_pk_mov_b32 v[112:113], s[30:31], s[30:31] op_sel:[0,1]
	v_pk_mov_b32 v[110:111], s[28:29], s[28:29] op_sel:[0,1]
	s_waitcnt lgkmcnt(3)
	v_mfma_f32_16x16x32_bf16 v[16:19], v[16:19], v[82:85], v[90:93]
	s_waitcnt lgkmcnt(2)
	v_mfma_f32_16x16x32_bf16 v[20:23], v[20:23], v[82:85], v[94:97]
	s_waitcnt lgkmcnt(1)
	v_mfma_f32_16x16x32_bf16 v[24:27], v[24:27], v[82:85], v[98:101]
	s_waitcnt lgkmcnt(0)
	v_mfma_f32_16x16x32_bf16 v[28:31], v[28:31], v[82:85], v[102:105]
	v_mfma_f32_16x16x32_bf16 v[82:85], v[110:113], v[82:85], v[86:89]
	s_setprio 0
	ds_read_b128 v[114:117], v118 offset:41024
	ds_read_b128 v[194:197], v118 offset:43584
	ds_read_b128 v[198:201], v118 offset:46144
	ds_read_b128 v[202:205], v118 offset:48704
	v_cvt_pk_bf16_f32 v206, v119, v139
	v_cvt_pk_bf16_f32 v207, v141, v143
	v_cvt_pk_bf16_f32 v208, v147, v148
	v_cvt_pk_bf16_f32 v209, v149, v186
	s_setprio 1
	s_waitcnt lgkmcnt(3)
	v_mfma_f32_16x16x32_bf16 v[16:19], v[114:117], v[206:209], v[16:19]
	s_waitcnt lgkmcnt(2)
	v_mfma_f32_16x16x32_bf16 v[20:23], v[194:197], v[206:209], v[20:23]
	s_waitcnt lgkmcnt(1)
	v_mfma_f32_16x16x32_bf16 v[24:27], v[198:201], v[206:209], v[24:27]
	s_waitcnt lgkmcnt(0)
	v_mfma_f32_16x16x32_bf16 v[28:31], v[202:205], v[206:209], v[28:31]
	v_mfma_f32_16x16x32_bf16 v[82:85], v[110:113], v[206:209], v[82:85]
	s_setprio 0
	s_and_b32 s0, s25, 0xc0
	s_mulk_i32 s0, 0xa0
	v_add_u32_e32 v118, s0, v153
	ds_read_b128 v[114:117], v118
	ds_read_b128 v[194:197], v118 offset:64
	ds_read_b128 v[198:201], v118 offset:2560
	ds_read_b128 v[202:205], v118 offset:2624
	ds_read_b128 v[206:209], v118 offset:5120
	ds_read_b128 v[210:213], v118 offset:5184
	ds_read_b128 v[214:217], v118 offset:7680
	ds_read_b128 v[218:221], v118 offset:7744
	s_setprio 1
	s_waitcnt lgkmcnt(7)
	v_mfma_f32_16x16x32_bf16 v[114:117], v[114:117], v[60:63], 0
	s_waitcnt lgkmcnt(6)
	v_mfma_f32_16x16x32_bf16 v[114:117], v[194:197], v[56:59], v[114:117]
	s_waitcnt lgkmcnt(5)
	v_mfma_f32_16x16x32_bf16 v[194:197], v[198:201], v[60:63], 0
	s_waitcnt lgkmcnt(4)
	v_mfma_f32_16x16x32_bf16 v[194:197], v[202:205], v[56:59], v[194:197]
	s_waitcnt lgkmcnt(3)
	v_mfma_f32_16x16x32_bf16 v[198:201], v[206:209], v[60:63], 0
	s_waitcnt lgkmcnt(1)
	v_mfma_f32_16x16x32_bf16 v[202:205], v[214:217], v[60:63], 0
	v_mfma_f32_16x16x32_bf16 v[198:201], v[210:213], v[56:59], v[198:201]
	s_waitcnt lgkmcnt(0)
	v_mfma_f32_16x16x32_bf16 v[202:205], v[218:221], v[56:59], v[202:205]
	s_setprio 0
	v_cvt_f32_i32_e32 v119, v108
	v_fma_f32 v139, -v146, v119, v192
	v_add_f32_e32 v141, v146, v139
	v_fmamk_f32 v114, v114, 0x3e38aa3b, v139
	v_fmac_f32_e32 v141, 0x3e38aa3b, v115
	v_add_f32_e32 v115, v188, v139
	v_fmac_f32_e32 v115, 0x3e38aa3b, v117
	v_add_f32_e32 v143, v137, v139
	v_exp_f32_e32 v139, v114
	v_fma_f32 v114, -v146, v119, v189
	v_fmac_f32_e32 v143, 0x3e38aa3b, v116
	v_exp_f32_e32 v147, v115
	v_fmamk_f32 v115, v194, 0x3e38aa3b, v114
	v_add_f32_e32 v116, v146, v114
	v_add_f32_e32 v117, v137, v114
	v_add_f32_e32 v114, v188, v114
	v_fmac_f32_e32 v114, 0x3e38aa3b, v197
	v_fmac_f32_e32 v116, 0x3e38aa3b, v195
	v_fmac_f32_e32 v117, 0x3e38aa3b, v196
	s_nop 0
	v_exp_f32_e32 v187, v114
	v_fma_f32 v114, -v146, v119, v190
	v_exp_f32_e32 v148, v115
	v_exp_f32_e32 v149, v116
	v_exp_f32_e32 v186, v117
	v_fmamk_f32 v115, v198, 0x3e38aa3b, v114
	v_add_f32_e32 v116, v146, v114
	v_add_f32_e32 v117, v137, v114
	v_add_f32_e32 v114, v188, v114
	v_fmac_f32_e32 v114, 0x3e38aa3b, v201
	v_fmac_f32_e32 v116, 0x3e38aa3b, v199
	v_fmac_f32_e32 v117, 0x3e38aa3b, v200
	v_exp_f32_e32 v141, v141
	v_exp_f32_e32 v212, v114
	v_fma_f32 v114, -v146, v119, v191
	v_exp_f32_e32 v193, v115
	v_exp_f32_e32 v210, v116
	v_exp_f32_e32 v211, v117
	v_fmamk_f32 v115, v202, 0x3e38aa3b, v114
	v_add_f32_e32 v116, v146, v114
	v_add_f32_e32 v117, v137, v114
	v_add_f32_e32 v114, v188, v114
	v_fmac_f32_e32 v116, 0x3e38aa3b, v203
	v_fmac_f32_e32 v117, 0x3e38aa3b, v204
	v_fmac_f32_e32 v114, 0x3e38aa3b, v205
	v_exp_f32_e32 v143, v143
	v_exp_f32_e32 v119, v115
	v_exp_f32_e32 v213, v116
	v_exp_f32_e32 v214, v117
	v_exp_f32_e32 v215, v114
	ds_read_b128 v[114:117], v118 offset:40960
	ds_read_b128 v[194:197], v118 offset:43520
	ds_read_b128 v[198:201], v118 offset:46080
	ds_read_b128 v[202:205], v118 offset:48640
	s_nop 0
	v_cvt_pk_bf16_f32 v206, v139, v141
	v_cvt_pk_bf16_f32 v207, v143, v147
	v_cvt_pk_bf16_f32 v208, v148, v149
	v_cvt_pk_bf16_f32 v209, v186, v187
	s_setprio 1
	s_waitcnt lgkmcnt(3)
	v_mfma_f32_16x16x32_bf16 v[16:19], v[114:117], v[206:209], v[16:19]
	s_waitcnt lgkmcnt(2)
	v_mfma_f32_16x16x32_bf16 v[20:23], v[194:197], v[206:209], v[20:23]
	s_waitcnt lgkmcnt(1)
	v_mfma_f32_16x16x32_bf16 v[24:27], v[198:201], v[206:209], v[24:27]
	s_waitcnt lgkmcnt(0)
	v_mfma_f32_16x16x32_bf16 v[28:31], v[202:205], v[206:209], v[28:31]
	v_mfma_f32_16x16x32_bf16 v[82:85], v[110:113], v[206:209], v[82:85]
	s_setprio 0
	ds_read_b128 v[114:117], v118 offset:41024
	ds_read_b128 v[194:197], v118 offset:43584
	ds_read_b128 v[198:201], v118 offset:46144
	ds_read_b128 v[202:205], v118 offset:48704
	v_cvt_pk_bf16_f32 v206, v193, v210
	v_cvt_pk_bf16_f32 v207, v211, v212
	v_cvt_pk_bf16_f32 v208, v119, v213
	v_cvt_pk_bf16_f32 v209, v214, v215
	s_setprio 1
	s_waitcnt lgkmcnt(3)
	v_mfma_f32_16x16x32_bf16 v[16:19], v[114:117], v[206:209], v[16:19]
	s_mov_b64 s[0:1], 0
	s_waitcnt lgkmcnt(2)
	v_mfma_f32_16x16x32_bf16 v[20:23], v[194:197], v[206:209], v[20:23]
	s_waitcnt lgkmcnt(1)
	v_mfma_f32_16x16x32_bf16 v[24:27], v[198:201], v[206:209], v[24:27]
	s_waitcnt lgkmcnt(0)
	v_mfma_f32_16x16x32_bf16 v[28:31], v[202:205], v[206:209], v[28:31]
	v_mfma_f32_16x16x32_bf16 v[82:85], v[110:113], v[206:209], v[82:85]
.LBB0_1064:
	s_and_b64 vcc, exec, s[0:1]
	s_cbranch_vccz .LBB0_1066
	s_and_b32 s0, s24, 0x80
	s_mulk_i32 s0, 0xa0
	v_add_u32_e32 v118, s0, v153
	ds_read_b128 v[16:19], v118
	ds_read_b128 v[20:23], v118 offset:64
	ds_read_b128 v[24:27], v118 offset:2560
	ds_read_b128 v[28:31], v118 offset:2624
	ds_read_b128 v[82:85], v118 offset:5120
	ds_read_b128 v[110:113], v118 offset:5184
	ds_read_b128 v[114:117], v118 offset:7680
	ds_read_b128 v[194:197], v118 offset:7744
	s_setprio 1
	s_waitcnt lgkmcnt(7)
	v_mfma_f32_16x16x32_bf16 v[16:19], v[16:19], v[60:63], 0
	s_waitcnt lgkmcnt(6)
	v_mfma_f32_16x16x32_bf16 v[16:19], v[20:23], v[56:59], v[16:19]
	s_waitcnt lgkmcnt(5)
	v_mfma_f32_16x16x32_bf16 v[20:23], v[24:27], v[60:63], 0
	s_waitcnt lgkmcnt(4)
	v_mfma_f32_16x16x32_bf16 v[20:23], v[28:31], v[56:59], v[20:23]
	s_waitcnt lgkmcnt(3)
	v_mfma_f32_16x16x32_bf16 v[24:27], v[82:85], v[60:63], 0
	s_waitcnt lgkmcnt(1)
	v_mfma_f32_16x16x32_bf16 v[28:31], v[114:117], v[60:63], 0
	v_mfma_f32_16x16x32_bf16 v[24:27], v[110:113], v[56:59], v[24:27]
	s_waitcnt lgkmcnt(0)
	v_mfma_f32_16x16x32_bf16 v[28:31], v[194:197], v[56:59], v[28:31]
	s_setprio 0
	v_cvt_f32_i32_e32 v82, v109
	v_cmp_gt_u32_e32 vcc, s71, v109
	v_fma_f32 v83, -v146, v82, v192
	v_fmamk_f32 v16, v16, 0x3e38aa3b, v83
	v_add_f32_e32 v84, v146, v83
	v_add_f32_e32 v85, v137, v83
	v_fmac_f32_e32 v84, 0x3e38aa3b, v17
	v_fmac_f32_e32 v85, 0x3e38aa3b, v18
	v_add_f32_e32 v17, v188, v83
	v_add_u32_e32 v18, 0x72, v81
	v_fmac_f32_e32 v17, 0x3e38aa3b, v19
	v_cndmask_b32_e32 v16, v179, v16, vcc
	v_cmp_gt_u32_e32 vcc, s71, v18
	v_add_u32_e32 v19, 0x71, v81
	v_add_u32_e32 v83, 0x70, v81
	v_cndmask_b32_e32 v18, v179, v84, vcc
	v_cmp_gt_u32_e32 vcc, s71, v19
	v_exp_f32_e32 v84, v18
	s_nop 0
	v_cndmask_b32_e32 v19, v179, v85, vcc
	v_cmp_gt_u32_e32 vcc, s71, v83
	v_exp_f32_e32 v83, v16
	v_fma_f32 v16, -v146, v82, v189
	v_cndmask_b32_e32 v17, v179, v17, vcc
	v_exp_f32_e32 v109, v17
	v_fmamk_f32 v17, v20, 0x3e38aa3b, v16
	v_add_f32_e32 v18, v146, v16
	v_add_u32_e32 v20, 0x63, v81
	v_exp_f32_e32 v85, v19
	v_fmac_f32_e32 v18, 0x3e38aa3b, v21
	v_add_f32_e32 v19, v137, v16
	v_cmp_gt_u32_e32 vcc, s71, v20
	v_add_u32_e32 v20, 0x62, v81
	v_fmac_f32_e32 v19, 0x3e38aa3b, v22
	v_add_f32_e32 v16, v188, v16
	v_cndmask_b32_e32 v17, v179, v17, vcc
	v_cmp_gt_u32_e32 vcc, s71, v20
	v_add_u32_e32 v20, 0x61, v81
	v_fmac_f32_e32 v16, 0x3e38aa3b, v23
	v_cndmask_b32_e32 v18, v179, v18, vcc
	v_cmp_gt_u32_e32 vcc, s71, v20
	v_add_u32_e32 v20, 0x60, v81
	v_exp_f32_e32 v112, v17
	v_cndmask_b32_e32 v19, v179, v19, vcc
	v_cmp_gt_u32_e32 vcc, s71, v20
	v_exp_f32_e32 v113, v18
	v_add_u32_e32 v20, 0x53, v81
	v_cndmask_b32_e32 v16, v179, v16, vcc
	v_exp_f32_e32 v115, v16
	v_fma_f32 v16, -v146, v82, v190
	v_fmamk_f32 v17, v24, 0x3e38aa3b, v16
	v_add_f32_e32 v18, v146, v16
	v_exp_f32_e32 v114, v19
	v_fmac_f32_e32 v18, 0x3e38aa3b, v25
	v_add_f32_e32 v19, v137, v16
	v_cmp_gt_u32_e32 vcc, s71, v20
	v_add_u32_e32 v20, 0x52, v81
	v_fmac_f32_e32 v19, 0x3e38aa3b, v26
	v_add_f32_e32 v16, v188, v16
	v_cndmask_b32_e32 v17, v179, v17, vcc
	v_cmp_gt_u32_e32 vcc, s71, v20
	v_add_u32_e32 v20, 0x51, v81
	v_fmac_f32_e32 v16, 0x3e38aa3b, v27
	v_cndmask_b32_e32 v18, v179, v18, vcc
	v_cmp_gt_u32_e32 vcc, s71, v20
	v_add_u32_e32 v20, 0x50, v81
	v_exp_f32_e32 v116, v17
	v_cndmask_b32_e32 v19, v179, v19, vcc
	v_cmp_gt_u32_e32 vcc, s71, v20
	v_exp_f32_e32 v117, v18
	v_add_u32_e32 v20, 0x43, v81
	v_cndmask_b32_e32 v16, v179, v16, vcc
	v_exp_f32_e32 v139, v16
	v_fma_f32 v16, -v146, v82, v191
	v_fmamk_f32 v17, v28, 0x3e38aa3b, v16
	v_add_f32_e32 v18, v146, v16
	v_exp_f32_e32 v119, v19
	v_fmac_f32_e32 v18, 0x3e38aa3b, v29
	v_add_f32_e32 v19, v137, v16
	v_cmp_gt_u32_e32 vcc, s71, v20
	v_add_u32_e32 v20, 0x42, v81
	v_fmac_f32_e32 v19, 0x3e38aa3b, v30
	v_add_f32_e32 v16, v188, v16
	v_cndmask_b32_e32 v17, v179, v17, vcc
	v_cmp_gt_u32_e32 vcc, s71, v20
	v_add_u32_e32 v20, 0x41, v81
	v_fmac_f32_e32 v16, 0x3e38aa3b, v31
	v_cndmask_b32_e32 v18, v179, v18, vcc
	v_cmp_gt_u32_e32 vcc, s71, v20
	v_add_u32_e32 v20, 64, v81
	v_exp_f32_e32 v141, v17
	v_cndmask_b32_e32 v19, v179, v19, vcc
	v_cmp_gt_u32_e32 vcc, s71, v20
	v_exp_f32_e32 v143, v18
	v_exp_f32_e32 v147, v19
	v_cndmask_b32_e32 v16, v179, v16, vcc
	v_exp_f32_e32 v148, v16
	ds_read_b128 v[16:19], v118 offset:40960
	ds_read_b128 v[20:23], v118 offset:43520
	ds_read_b128 v[24:27], v118 offset:46080
	ds_read_b128 v[28:31], v118 offset:48640
	s_nop 0
	v_cvt_pk_bf16_f32 v110, v83, v84
	v_cvt_pk_bf16_f32 v111, v85, v109
	v_cvt_pk_bf16_f32 v112, v112, v113
	v_cvt_pk_bf16_f32 v113, v114, v115
	s_setprio 1
	s_mov_b32 s30, s28
	s_mov_b32 s31, s28
	s_mov_b32 s29, s28
	v_pk_mov_b32 v[84:85], s[30:31], s[30:31] op_sel:[0,1]
	v_pk_mov_b32 v[82:83], s[28:29], s[28:29] op_sel:[0,1]
	s_waitcnt lgkmcnt(3)
	v_mfma_f32_16x16x32_bf16 v[16:19], v[16:19], v[110:113], v[90:93]
	s_waitcnt lgkmcnt(2)
	v_mfma_f32_16x16x32_bf16 v[20:23], v[20:23], v[110:113], v[94:97]
	s_waitcnt lgkmcnt(1)
	v_mfma_f32_16x16x32_bf16 v[24:27], v[24:27], v[110:113], v[98:101]
	s_waitcnt lgkmcnt(0)
	v_mfma_f32_16x16x32_bf16 v[28:31], v[28:31], v[110:113], v[102:105]
	v_mfma_f32_16x16x32_bf16 v[86:89], v[82:85], v[110:113], v[86:89]
	s_setprio 0
	ds_read_b128 v[90:93], v118 offset:41024
	ds_read_b128 v[94:97], v118 offset:43584
	ds_read_b128 v[98:101], v118 offset:46144
	ds_read_b128 v[102:105], v118 offset:48704
	v_cvt_pk_bf16_f32 v110, v116, v117
	v_cvt_pk_bf16_f32 v111, v119, v139
	v_cvt_pk_bf16_f32 v112, v141, v143
	v_cvt_pk_bf16_f32 v113, v147, v148
	s_setprio 1
	s_waitcnt lgkmcnt(3)
	v_mfma_f32_16x16x32_bf16 v[16:19], v[90:93], v[110:113], v[16:19]
	s_waitcnt lgkmcnt(2)
	v_mfma_f32_16x16x32_bf16 v[20:23], v[94:97], v[110:113], v[20:23]
	s_waitcnt lgkmcnt(1)
	v_mfma_f32_16x16x32_bf16 v[24:27], v[98:101], v[110:113], v[24:27]
	s_waitcnt lgkmcnt(0)
	v_mfma_f32_16x16x32_bf16 v[28:31], v[102:105], v[110:113], v[28:31]
	v_mfma_f32_16x16x32_bf16 v[86:89], v[82:85], v[110:113], v[86:89]
	s_setprio 0
	s_and_b32 s0, s25, 0xc0
	s_mulk_i32 s0, 0xa0
	v_add_u32_e32 v118, s0, v153
	ds_read_b128 v[90:93], v118
	ds_read_b128 v[94:97], v118 offset:64
	ds_read_b128 v[98:101], v118 offset:2560
	ds_read_b128 v[102:105], v118 offset:2624
	ds_read_b128 v[110:113], v118 offset:5120
	ds_read_b128 v[114:117], v118 offset:5184
	ds_read_b128 v[194:197], v118 offset:7680
	ds_read_b128 v[198:201], v118 offset:7744
	s_setprio 1
	s_waitcnt lgkmcnt(7)
	v_mfma_f32_16x16x32_bf16 v[90:93], v[90:93], v[60:63], 0
	s_waitcnt lgkmcnt(6)
	v_mfma_f32_16x16x32_bf16 v[90:93], v[94:97], v[56:59], v[90:93]
	s_waitcnt lgkmcnt(5)
	v_mfma_f32_16x16x32_bf16 v[94:97], v[98:101], v[60:63], 0
	s_waitcnt lgkmcnt(4)
	v_mfma_f32_16x16x32_bf16 v[94:97], v[102:105], v[56:59], v[94:97]
	s_waitcnt lgkmcnt(3)
	v_mfma_f32_16x16x32_bf16 v[98:101], v[110:113], v[60:63], 0
	s_waitcnt lgkmcnt(1)
	v_mfma_f32_16x16x32_bf16 v[102:105], v[194:197], v[60:63], 0
	v_mfma_f32_16x16x32_bf16 v[98:101], v[114:117], v[56:59], v[98:101]
	s_waitcnt lgkmcnt(0)
	v_mfma_f32_16x16x32_bf16 v[102:105], v[198:201], v[56:59], v[102:105]
	s_setprio 0
	v_cvt_f32_i32_e32 v109, v108
	v_cmp_gt_u32_e32 vcc, s71, v108
	v_add_u32_e32 v108, 48, v81
	v_fma_f32 v110, -v146, v109, v192
	v_fmamk_f32 v90, v90, 0x3e38aa3b, v110
	v_add_f32_e32 v111, v146, v110
	v_add_f32_e32 v112, v137, v110
	v_fmac_f32_e32 v111, 0x3e38aa3b, v91
	v_fmac_f32_e32 v112, 0x3e38aa3b, v92
	v_add_f32_e32 v91, v188, v110
	v_add_u32_e32 v92, 50, v81
	v_fmac_f32_e32 v91, 0x3e38aa3b, v93
	v_cndmask_b32_e32 v90, v179, v90, vcc
	v_cmp_gt_u32_e32 vcc, s71, v92
	v_add_u32_e32 v93, 49, v81
	s_nop 0
	v_cndmask_b32_e32 v92, v179, v111, vcc
	v_cmp_gt_u32_e32 vcc, s71, v93
	v_exp_f32_e32 v110, v92
	s_nop 0
	v_cndmask_b32_e32 v93, v179, v112, vcc
	v_cmp_gt_u32_e32 vcc, s71, v108
	v_exp_f32_e32 v108, v90
	v_fma_f32 v90, -v146, v109, v189
	v_cndmask_b32_e32 v91, v179, v91, vcc
	v_exp_f32_e32 v112, v91
	v_fmamk_f32 v91, v94, 0x3e38aa3b, v90
	v_add_f32_e32 v92, v146, v90
	v_add_u32_e32 v94, 35, v81
	v_exp_f32_e32 v111, v93
	v_fmac_f32_e32 v92, 0x3e38aa3b, v95
	v_add_f32_e32 v93, v137, v90
	v_cmp_gt_u32_e32 vcc, s71, v94
	v_add_u32_e32 v94, 34, v81
	v_fmac_f32_e32 v93, 0x3e38aa3b, v96
	v_add_f32_e32 v90, v188, v90
	v_cndmask_b32_e32 v91, v179, v91, vcc
	v_cmp_gt_u32_e32 vcc, s71, v94
	v_add_u32_e32 v94, 33, v81
	v_fmac_f32_e32 v90, 0x3e38aa3b, v97
	v_cndmask_b32_e32 v92, v179, v92, vcc
	v_cmp_gt_u32_e32 vcc, s71, v94
	v_add_u32_e32 v94, 32, v81
	v_exp_f32_e32 v113, v91
	v_cndmask_b32_e32 v93, v179, v93, vcc
	v_cmp_gt_u32_e32 vcc, s71, v94
	v_exp_f32_e32 v114, v92
	v_add_u32_e32 v94, 19, v81
	v_cndmask_b32_e32 v90, v179, v90, vcc
	v_exp_f32_e32 v116, v90
	v_fma_f32 v90, -v146, v109, v190
	v_fmamk_f32 v91, v98, 0x3e38aa3b, v90
	v_add_f32_e32 v92, v146, v90
	v_exp_f32_e32 v115, v93
	v_fmac_f32_e32 v92, 0x3e38aa3b, v99
	v_add_f32_e32 v93, v137, v90
	v_cmp_gt_u32_e32 vcc, s71, v94
	v_add_u32_e32 v94, 18, v81
	v_fmac_f32_e32 v93, 0x3e38aa3b, v100
	v_add_f32_e32 v90, v188, v90
	v_cndmask_b32_e32 v91, v179, v91, vcc
	v_cmp_gt_u32_e32 vcc, s71, v94
	v_add_u32_e32 v94, 17, v81
	v_fmac_f32_e32 v90, 0x3e38aa3b, v101
	v_cndmask_b32_e32 v92, v179, v92, vcc
	v_cmp_gt_u32_e32 vcc, s71, v94
	v_add_u32_e32 v94, 16, v81
	v_exp_f32_e32 v117, v91
	v_cndmask_b32_e32 v93, v179, v93, vcc
	v_cmp_gt_u32_e32 vcc, s71, v94
	v_exp_f32_e32 v119, v92
	v_add_u32_e32 v94, 3, v81
	v_cndmask_b32_e32 v90, v179, v90, vcc
	v_exp_f32_e32 v141, v90
	v_fma_f32 v90, -v146, v109, v191
	v_fmamk_f32 v91, v102, 0x3e38aa3b, v90
	v_add_f32_e32 v92, v146, v90
	v_exp_f32_e32 v139, v93
	v_fmac_f32_e32 v92, 0x3e38aa3b, v103
	v_add_f32_e32 v93, v137, v90
	v_cmp_gt_u32_e32 vcc, s71, v94
	v_add_u32_e32 v94, 2, v81
	v_fmac_f32_e32 v93, 0x3e38aa3b, v104
	v_add_f32_e32 v90, v188, v90
	v_cndmask_b32_e32 v91, v179, v91, vcc
	v_cmp_gt_u32_e32 vcc, s71, v94
	v_add_u32_e32 v94, 1, v81
	v_fmac_f32_e32 v90, 0x3e38aa3b, v105
	v_cndmask_b32_e32 v92, v179, v92, vcc
	v_cmp_gt_u32_e32 vcc, s71, v94
	v_exp_f32_e32 v143, v91
	v_exp_f32_e32 v147, v92
	v_cndmask_b32_e32 v93, v179, v93, vcc
	v_cmp_gt_u32_e32 vcc, s71, v81
	v_exp_f32_e32 v148, v93
	s_nop 0
	v_cndmask_b32_e32 v90, v179, v90, vcc
	v_exp_f32_e32 v149, v90
	ds_read_b128 v[90:93], v118 offset:40960
	ds_read_b128 v[94:97], v118 offset:43520
	ds_read_b128 v[98:101], v118 offset:46080
	ds_read_b128 v[102:105], v118 offset:48640
	v_cvt_pk_bf16_f32 v108, v108, v110
	v_cvt_pk_bf16_f32 v109, v111, v112
	v_cvt_pk_bf16_f32 v110, v113, v114
	v_cvt_pk_bf16_f32 v111, v115, v116
	s_setprio 1
	s_waitcnt lgkmcnt(3)
	v_mfma_f32_16x16x32_bf16 v[16:19], v[90:93], v[108:111], v[16:19]
	s_waitcnt lgkmcnt(2)
	v_mfma_f32_16x16x32_bf16 v[20:23], v[94:97], v[108:111], v[20:23]
	s_waitcnt lgkmcnt(1)
	v_mfma_f32_16x16x32_bf16 v[24:27], v[98:101], v[108:111], v[24:27]
	s_waitcnt lgkmcnt(0)
	v_mfma_f32_16x16x32_bf16 v[28:31], v[102:105], v[108:111], v[28:31]
	v_mfma_f32_16x16x32_bf16 v[86:89], v[82:85], v[108:111], v[86:89]
	s_setprio 0
	ds_read_b128 v[90:93], v118 offset:41024
	ds_read_b128 v[94:97], v118 offset:43584
	ds_read_b128 v[98:101], v118 offset:46144
	ds_read_b128 v[102:105], v118 offset:48704
	v_cvt_pk_bf16_f32 v108, v117, v119
	v_cvt_pk_bf16_f32 v109, v139, v141
	v_cvt_pk_bf16_f32 v110, v143, v147
	v_cvt_pk_bf16_f32 v111, v148, v149
	s_setprio 1
	s_waitcnt lgkmcnt(3)
	v_mfma_f32_16x16x32_bf16 v[16:19], v[90:93], v[108:111], v[16:19]
	s_waitcnt lgkmcnt(2)
	v_mfma_f32_16x16x32_bf16 v[20:23], v[94:97], v[108:111], v[20:23]
	s_waitcnt lgkmcnt(1)
	v_mfma_f32_16x16x32_bf16 v[24:27], v[98:101], v[108:111], v[24:27]
	s_waitcnt lgkmcnt(0)
	v_mfma_f32_16x16x32_bf16 v[28:31], v[102:105], v[108:111], v[28:31]
	v_mfma_f32_16x16x32_bf16 v[82:85], v[82:85], v[108:111], v[86:89]

.Lwin_skip_pf:
	s_waitcnt lgkmcnt(0)
	s_barrier
	s_add_i32 s1, s23, 2
	s_add_i32 s23, s23, -3
	s_cmp_lt_i32 s23, s21
	v_add_u32_e32 v81, 0xffffff80, v81
	s_cbranch_scc0 .LBB0_1069
	v_pk_mov_b32 v[88:89], v[84:85], v[84:85] op_sel:[0,1]
	s_mov_b32 s24, s0
	s_mov_b32 s23, s1
	v_pk_mov_b32 v[86:87], v[82:83], v[82:83] op_sel:[0,1]
	v_pk_mov_b32 v[90:91], v[16:17], v[16:17] op_sel:[0,1]
	v_pk_mov_b32 v[92:93], v[18:19], v[18:19] op_sel:[0,1]
	v_pk_mov_b32 v[94:95], v[20:21], v[20:21] op_sel:[0,1]
	v_pk_mov_b32 v[96:97], v[22:23], v[22:23] op_sel:[0,1]
	v_pk_mov_b32 v[98:99], v[24:25], v[24:25] op_sel:[0,1]
	v_pk_mov_b32 v[100:101], v[26:27], v[26:27] op_sel:[0,1]
	v_pk_mov_b32 v[102:103], v[28:29], v[28:29] op_sel:[0,1]
	v_pk_mov_b32 v[104:105], v[30:31], v[30:31] op_sel:[0,1]
	s_branch .LBB0_1061

.LBB0_1069:
	s_cmp_gt_i32 s23, s21
	s_cbranch_scc1 .LBB0_986
	s_lshl_b32 s22, s23, 6
	s_add_i32 s23, s22, s20
	s_or_b32 s0, s23, 63
	s_cmp_gt_i32 s0, s74
	s_cselect_b64 s[0:1], -1, 0
	s_addk_i32 s74, 0xfe10
	s_cmp_lt_i32 s23, s74
	s_cselect_b64 s[20:21], -1, 0
	s_and_b32 s22, s22, 0x80
	s_mulk_i32 s22, 0xa0
	v_add_u32_e32 v81, s22, v153
	ds_read_b128 v[102:105], v81
	ds_read_b128 v[106:109], v81 offset:64
	ds_read_b128 v[110:113], v81 offset:2560
	ds_read_b128 v[114:117], v81 offset:2624
	ds_read_b128 v[86:89], v81 offset:5120
	ds_read_b128 v[90:93], v81 offset:5184
	ds_read_b128 v[94:97], v81 offset:7680
	ds_read_b128 v[98:101], v81 offset:7744
	s_waitcnt vmcnt(2)
	v_or_b32_e32 v32, s23, v124
	v_sub_u32_e32 v137, v144, v32
	s_or_b64 s[20:21], s[0:1], s[20:21]
	s_setprio 1
	v_cvt_f32_i32_e32 v143, v137
	s_mov_b64 s[0:1], -1
	s_and_b64 vcc, exec, s[20:21]
	s_cbranch_vccnz .LBB0_1072
	s_waitcnt lgkmcnt(7)
	v_mfma_f32_16x16x32_bf16 v[32:35], v[102:105], v[60:63], 0
	s_waitcnt lgkmcnt(5)
	v_mfma_f32_16x16x32_bf16 v[36:39], v[110:113], v[60:63], 0
	s_waitcnt vmcnt(0) lgkmcnt(3)
	v_mfma_f32_16x16x32_bf16 v[40:43], v[86:89], v[60:63], 0
	s_waitcnt lgkmcnt(1)
	v_mfma_f32_16x16x32_bf16 v[44:47], v[94:97], v[60:63], 0
	v_mfma_f32_16x16x32_bf16 v[32:35], v[106:109], v[56:59], v[32:35]
	v_mfma_f32_16x16x32_bf16 v[36:39], v[114:117], v[56:59], v[36:39]
	v_mfma_f32_16x16x32_bf16 v[40:43], v[90:93], v[56:59], v[40:43]
	s_waitcnt lgkmcnt(0)
	v_mfma_f32_16x16x32_bf16 v[44:47], v[98:101], v[56:59], v[44:47]
	s_setprio 0
	v_pk_mul_f32 v[118:119], v[146:147], v[142:143] op_sel_hi:[0,1] neg_hi:[1,0]
	v_fma_f32 v120, 0, v146, v119
	s_nop 0
	v_fmamk_f32 v32, v32, 0x3e38aa3b, v120
	v_add_f32_e32 v121, v146, v120
	v_mov_b32_e32 v147, v38
	v_fmac_f32_e32 v121, 0x3e38aa3b, v33
	v_exp_f32_e32 v139, v32
	v_add_f32_e32 v118, v118, v119
	v_pk_mul_f32 v[32:33], v[146:147], s[44:45]
	v_fmamk_f32 v141, v36, 0x3e38aa3b, v118
	v_add_f32_e32 v36, v32, v120
	v_fmac_f32_e32 v36, 0x3e38aa3b, v34
	v_add_f32_e32 v148, v146, v118
	v_mov_b32_e32 v147, v39
	s_mov_b32 s47, s45
	v_fmac_f32_e32 v148, 0x3e38aa3b, v37
	v_exp_f32_e32 v149, v36
	v_add_f32_e32 v34, v32, v118
	v_pk_mul_f32 v[36:37], v[146:147], s[46:47]
	v_add_f32_e32 v33, v34, v33
	v_add_f32_e32 v34, v36, v120
	v_fmac_f32_e32 v34, 0x3e38aa3b, v35
	s_nop 0
	v_exp_f32_e32 v120, v34
	v_add_f32_e32 v34, v36, v118
	v_add_f32_e32 v34, v34, v37
	v_exp_f32_e32 v147, v148
	v_exp_f32_e32 v148, v33
	v_fmamk_f32 v33, v146, 0x42000000, v119
	v_add_f32_e32 v35, v146, v33
	v_exp_f32_e32 v186, v34
	v_fmamk_f32 v34, v40, 0x3e38aa3b, v33
	v_fmac_f32_e32 v35, 0x3e38aa3b, v41
	v_add_f32_e32 v37, v32, v33
	v_add_f32_e32 v33, v36, v33
	v_fmac_f32_e32 v33, 0x3e38aa3b, v43
	v_fmac_f32_e32 v119, 0x42400000, v146
	v_exp_f32_e32 v206, v34
	v_exp_f32_e32 v207, v35
	v_add_f32_e32 v34, v146, v119
	v_add_f32_e32 v32, v32, v119
	v_add_f32_e32 v35, v36, v119
	v_fmac_f32_e32 v37, 0x3e38aa3b, v42
	v_exp_f32_e32 v209, v33
	v_fmamk_f32 v33, v44, 0x3e38aa3b, v119
	v_fmac_f32_e32 v34, 0x3e38aa3b, v45
	v_fmac_f32_e32 v32, 0x3e38aa3b, v46
	v_fmac_f32_e32 v35, 0x3e38aa3b, v47
	v_exp_f32_e32 v121, v121
	v_exp_f32_e32 v208, v37
	v_exp_f32_e32 v210, v33
	v_exp_f32_e32 v211, v34
	v_exp_f32_e32 v212, v32
	v_exp_f32_e32 v213, v35
	ds_read_b128 v[32:35], v81 offset:40960
	ds_read_b128 v[36:39], v81 offset:43520
	ds_read_b128 v[40:43], v81 offset:46080
	ds_read_b128 v[44:47], v81 offset:48640
	v_exp_f32_e32 v141, v141
	v_cvt_pk_bf16_f32 v118, v139, v121
	v_cvt_pk_bf16_f32 v119, v149, v120
	v_cvt_pk_bf16_f32 v120, v141, v147
	v_cvt_pk_bf16_f32 v121, v148, v186
	s_setprio 1
	s_mov_b32 s30, s28
	s_mov_b32 s31, s28
	s_mov_b32 s29, s28
	v_pk_mov_b32 v[188:189], s[30:31], s[30:31] op_sel:[0,1]
	v_pk_mov_b32 v[186:187], s[28:29], s[28:29] op_sel:[0,1]
	s_waitcnt lgkmcnt(3)
	v_mfma_f32_16x16x32_bf16 v[32:35], v[32:35], v[118:121], v[16:19]
	s_waitcnt lgkmcnt(2)
	v_mfma_f32_16x16x32_bf16 v[36:39], v[36:39], v[118:121], v[20:23]
	s_waitcnt lgkmcnt(1)
	v_mfma_f32_16x16x32_bf16 v[40:43], v[40:43], v[118:121], v[24:27]
	s_waitcnt lgkmcnt(0)
	v_mfma_f32_16x16x32_bf16 v[44:47], v[44:47], v[118:121], v[28:31]
	v_mfma_f32_16x16x32_bf16 v[118:121], v[186:189], v[118:121], v[82:85]
	s_setprio 0
	ds_read_b128 v[190:193], v81 offset:41024
	ds_read_b128 v[194:197], v81 offset:43584
	ds_read_b128 v[198:201], v81 offset:46144
	ds_read_b128 v[202:205], v81 offset:48704
	v_cvt_pk_bf16_f32 v206, v206, v207
	v_cvt_pk_bf16_f32 v207, v208, v209
	v_cvt_pk_bf16_f32 v208, v210, v211
	v_cvt_pk_bf16_f32 v209, v212, v213
	s_setprio 1
	s_waitcnt lgkmcnt(3)
	v_mfma_f32_16x16x32_bf16 v[32:35], v[190:193], v[206:209], v[32:35]
	s_mov_b64 s[0:1], 0
	s_waitcnt lgkmcnt(2)
	v_mfma_f32_16x16x32_bf16 v[36:39], v[194:197], v[206:209], v[36:39]
	s_waitcnt lgkmcnt(1)
	v_mfma_f32_16x16x32_bf16 v[40:43], v[198:201], v[206:209], v[40:43]
	s_waitcnt lgkmcnt(0)
	v_mfma_f32_16x16x32_bf16 v[44:47], v[202:205], v[206:209], v[44:47]
	v_mfma_f32_16x16x32_bf16 v[118:121], v[186:189], v[206:209], v[118:121]
.LBB0_1072:
	s_andn2_b64 vcc, exec, s[0:1]
	s_cbranch_vccnz .LBB0_985
	s_waitcnt lgkmcnt(7)
	v_mfma_f32_16x16x32_bf16 v[32:35], v[102:105], v[60:63], 0
	s_waitcnt lgkmcnt(5)
	v_mfma_f32_16x16x32_bf16 v[36:39], v[110:113], v[60:63], 0
	s_waitcnt vmcnt(0) lgkmcnt(3)
	v_mfma_f32_16x16x32_bf16 v[40:43], v[86:89], v[60:63], 0
	s_waitcnt lgkmcnt(1)
	v_mfma_f32_16x16x32_bf16 v[44:47], v[94:97], v[60:63], 0
	v_mfma_f32_16x16x32_bf16 v[32:35], v[106:109], v[56:59], v[32:35]
	v_mfma_f32_16x16x32_bf16 v[36:39], v[114:117], v[56:59], v[36:39]
	v_mfma_f32_16x16x32_bf16 v[40:43], v[90:93], v[56:59], v[40:43]
	s_waitcnt lgkmcnt(0)
	v_mfma_f32_16x16x32_bf16 v[44:47], v[98:101], v[56:59], v[44:47]
	s_setprio 0
	v_pk_mul_f32 v[56:57], v[146:147], v[142:143] op_sel_hi:[0,1]
	v_fma_f32 v61, v146, 0, -v57
	s_nop 0
	v_fmamk_f32 v32, v32, 0x3e38aa3b, v61
	v_add_u32_e32 v58, -1, v137
	v_add_f32_e32 v62, v146, v61
	v_cmp_gt_u32_e32 vcc, s71, v137
	v_fmac_f32_e32 v62, 0x3e38aa3b, v33
	v_mov_b32_e32 v147, v38
	v_cndmask_b32_e32 v32, v179, v32, vcc
	v_cmp_gt_u32_e32 vcc, s71, v58
	v_exp_f32_e32 v58, v32
	v_sub_f32_e32 v56, v56, v57
	v_cndmask_b32_e32 v33, v179, v62, vcc
	v_exp_f32_e32 v62, v33
	v_pk_mul_f32 v[32:33], v[146:147], s[44:45]
	v_add_u32_e32 v59, -2, v137
	v_fmamk_f32 v63, v36, 0x3e38aa3b, v56
	v_add_f32_e32 v36, v32, v61
	v_fmac_f32_e32 v36, 0x3e38aa3b, v34
	v_cmp_gt_u32_e32 vcc, s71, v59
	v_add_f32_e32 v86, v146, v56
	v_mov_b32_e32 v147, v39
	v_cndmask_b32_e32 v34, v179, v36, vcc
	s_mov_b32 s47, s45
	v_fmac_f32_e32 v86, 0x3e38aa3b, v37
	v_exp_f32_e32 v59, v34
	v_add_f32_e32 v34, v32, v56
	v_pk_mul_f32 v[36:37], v[146:147], s[46:47]
	v_add_f32_e32 v33, v34, v33
	v_add_f32_e32 v34, v36, v61
	v_add_u32_e32 v60, -3, v137
	v_fmac_f32_e32 v34, 0x3e38aa3b, v35
	v_cmp_gt_u32_e32 vcc, s71, v60
	v_add_u32_e32 v35, -16, v137
	v_subrev_u32_e32 v38, 18, v137
	v_cndmask_b32_e32 v34, v179, v34, vcc
	v_exp_f32_e32 v60, v34
	v_add_f32_e32 v34, v36, v56
	v_add_f32_e32 v34, v34, v37
	v_cmp_gt_u32_e32 vcc, s71, v35
	v_subrev_u32_e32 v37, 17, v137
	s_nop 0
	v_cndmask_b32_e32 v35, v179, v63, vcc
	v_cmp_gt_u32_e32 vcc, s71, v37
	v_exp_f32_e32 v61, v35
	s_nop 0
	v_cndmask_b32_e32 v37, v179, v86, vcc
	v_cmp_gt_u32_e32 vcc, s71, v38
	v_subrev_u32_e32 v38, 19, v137
	v_exp_f32_e32 v63, v37
	v_cndmask_b32_e32 v33, v179, v33, vcc
	v_cmp_gt_u32_e32 vcc, s71, v38
	v_exp_f32_e32 v86, v33
	v_fma_f32 v33, v146, s65, -v57
	v_cndmask_b32_e32 v34, v179, v34, vcc
	v_exp_f32_e32 v87, v34
	v_fmamk_f32 v34, v40, 0x3e38aa3b, v33
	v_add_f32_e32 v35, v146, v33
	v_subrev_u32_e32 v38, 32, v137
	v_fmac_f32_e32 v35, 0x3e38aa3b, v41
	v_add_f32_e32 v37, v32, v33
	v_cmp_gt_u32_e32 vcc, s71, v38
	v_subrev_u32_e32 v38, 33, v137
	v_fmac_f32_e32 v37, 0x3e38aa3b, v42
	v_add_f32_e32 v33, v36, v33
	v_cndmask_b32_e32 v34, v179, v34, vcc
	v_cmp_gt_u32_e32 vcc, s71, v38
	v_subrev_u32_e32 v38, 34, v137
	v_fmac_f32_e32 v33, 0x3e38aa3b, v43
	v_cndmask_b32_e32 v35, v179, v35, vcc
	v_cmp_gt_u32_e32 vcc, s71, v38
	v_subrev_u32_e32 v38, 35, v137
	v_exp_f32_e32 v88, v34
	v_cndmask_b32_e32 v37, v179, v37, vcc
	v_cmp_gt_u32_e32 vcc, s71, v38
	v_exp_f32_e32 v89, v35
	v_exp_f32_e32 v90, v37
	v_cndmask_b32_e32 v33, v179, v33, vcc
	v_exp_f32_e32 v91, v33
	v_fma_f32 v33, v146, s66, -v57
	v_fmamk_f32 v34, v44, 0x3e38aa3b, v33
	v_add_f32_e32 v35, v146, v33
	v_add_f32_e32 v32, v32, v33
	v_add_f32_e32 v33, v36, v33
	v_subrev_u32_e32 v36, 48, v137
	v_fmac_f32_e32 v35, 0x3e38aa3b, v45
	v_cmp_gt_u32_e32 vcc, s71, v36
	v_subrev_u32_e32 v36, 49, v137
	v_fmac_f32_e32 v32, 0x3e38aa3b, v46
	v_cndmask_b32_e32 v34, v179, v34, vcc
	v_cmp_gt_u32_e32 vcc, s71, v36
	v_subrev_u32_e32 v36, 50, v137
	v_fmac_f32_e32 v33, 0x3e38aa3b, v47
	v_cndmask_b32_e32 v35, v179, v35, vcc
	v_cmp_gt_u32_e32 vcc, s71, v36
	v_subrev_u32_e32 v36, 51, v137
	v_exp_f32_e32 v92, v34
	v_cndmask_b32_e32 v32, v179, v32, vcc
	v_cmp_gt_u32_e32 vcc, s71, v36
	v_exp_f32_e32 v93, v35
	v_exp_f32_e32 v94, v32
	v_cndmask_b32_e32 v33, v179, v33, vcc
	v_exp_f32_e32 v95, v33
	ds_read_b128 v[32:35], v81 offset:40960
	ds_read_b128 v[36:39], v81 offset:43520
	ds_read_b128 v[40:43], v81 offset:46080
	ds_read_b128 v[44:47], v81 offset:48640
	v_cvt_pk_bf16_f32 v56, v58, v62
	v_cvt_pk_bf16_f32 v57, v59, v60
	v_cvt_pk_bf16_f32 v58, v61, v63
	v_cvt_pk_bf16_f32 v59, v86, v87
	s_setprio 1
	s_mov_b32 s30, s28
	s_mov_b32 s31, s28
	s_mov_b32 s29, s28
	v_pk_mov_b32 v[62:63], s[30:31], s[30:31] op_sel:[0,1]
	v_pk_mov_b32 v[60:61], s[28:29], s[28:29] op_sel:[0,1]
	s_waitcnt lgkmcnt(3)
	v_mfma_f32_16x16x32_bf16 v[16:19], v[32:35], v[56:59], v[16:19]
	s_waitcnt lgkmcnt(2)
	v_mfma_f32_16x16x32_bf16 v[20:23], v[36:39], v[56:59], v[20:23]
	s_waitcnt lgkmcnt(1)
	v_mfma_f32_16x16x32_bf16 v[24:27], v[40:43], v[56:59], v[24:27]
	s_waitcnt lgkmcnt(0)
	v_mfma_f32_16x16x32_bf16 v[28:31], v[44:47], v[56:59], v[28:31]
	v_mfma_f32_16x16x32_bf16 v[56:59], v[60:63], v[56:59], v[82:85]
	s_setprio 0
	ds_read_b128 v[32:35], v81 offset:41024
	ds_read_b128 v[36:39], v81 offset:43584
	ds_read_b128 v[40:43], v81 offset:46144
	ds_read_b128 v[44:47], v81 offset:48704
	v_cvt_pk_bf16_f32 v82, v88, v89
	v_cvt_pk_bf16_f32 v83, v90, v91
	v_cvt_pk_bf16_f32 v84, v92, v93
	v_cvt_pk_bf16_f32 v85, v94, v95
	s_setprio 1
	s_waitcnt lgkmcnt(3)
	v_mfma_f32_16x16x32_bf16 v[32:35], v[32:35], v[82:85], v[16:19]
	s_waitcnt lgkmcnt(2)
	v_mfma_f32_16x16x32_bf16 v[36:39], v[36:39], v[82:85], v[20:23]
	s_waitcnt lgkmcnt(1)
	v_mfma_f32_16x16x32_bf16 v[40:43], v[40:43], v[82:85], v[24:27]
	s_waitcnt lgkmcnt(0)
	v_mfma_f32_16x16x32_bf16 v[44:47], v[44:47], v[82:85], v[28:31]
	v_mfma_f32_16x16x32_bf16 v[118:121], v[60:63], v[82:85], v[56:59]
	s_branch .LBB0_985

.LBB0_1153:
	s_or_b64 exec, exec, s[30:31]
	v_or_b32_e32 v112, 16, v150
	s_waitcnt lgkmcnt(0)
	v_ashrrev_i32_e32 v113, 31, v112
	v_lshlrev_b64 v[114:115], 11, v[112:113]
	v_lshl_add_u64 v[114:115], s[12:13], 0, v[114:115]
	v_lshl_add_u64 v[122:123], v[148:149], 1, v[114:115]
	s_nop 1
	v_pk_mov_b32 v[114:115], v[184:185], v[184:185] op_sel:[0,1]
	v_pk_mov_b32 v[116:117], v[186:187], v[186:187] op_sel:[0,1]
	v_pk_mov_b32 v[118:119], v[188:189], v[188:189] op_sel:[0,1]
	v_pk_mov_b32 v[120:121], v[190:191], v[190:191] op_sel:[0,1]
	v_lshlrev_b32_e32 v124, 16, v114
	v_and_b32_e32 v125, 0xffff0000, v114
	v_lshlrev_b32_e32 v114, 16, v115
	v_and_b32_e32 v115, 0xffff0000, v115
	v_lshlrev_b32_e32 v126, 16, v116
	v_and_b32_e32 v127, 0xffff0000, v116
	v_lshlrev_b32_e32 v116, 16, v117
	v_and_b32_e32 v117, 0xffff0000, v117
	v_lshlrev_b32_e32 v160, 16, v118
	v_and_b32_e32 v161, 0xffff0000, v118
	v_lshlrev_b32_e32 v118, 16, v119
	v_and_b32_e32 v119, 0xffff0000, v119
	v_lshlrev_b32_e32 v162, 16, v120
	v_and_b32_e32 v163, 0xffff0000, v120
	v_lshlrev_b32_e32 v120, 16, v121
	v_and_b32_e32 v121, 0xffff0000, v121
	v_pk_add_f32 v[108:109], v[108:109], v[124:125]
	v_pk_add_f32 v[110:111], v[110:111], v[114:115]
	v_pk_add_f32 v[104:105], v[104:105], v[126:127]
	v_pk_add_f32 v[106:107], v[106:107], v[116:117]
	v_pk_add_f32 v[100:101], v[100:101], v[160:161]
	v_pk_add_f32 v[102:103], v[102:103], v[118:119]
	v_pk_add_f32 v[114:115], v[96:97], v[162:163]
	v_pk_add_f32 v[116:117], v[98:99], v[120:121]
	v_cvt_pk_bf16_f32 v96, v108, v109
	v_cvt_pk_bf16_f32 v97, v110, v111
	v_pk_mul_f32 v[98:99], v[108:109], v[108:109]
	v_pk_mul_f32 v[108:109], v[110:111], v[110:111]
	v_pk_mul_f32 v[110:111], v[104:105], v[104:105]
	v_pk_mul_f32 v[118:119], v[106:107], v[106:107]
	v_pk_mul_f32 v[120:121], v[100:101], v[100:101]
	v_pk_mul_f32 v[124:125], v[102:103], v[102:103]
	v_pk_mul_f32 v[126:127], v[114:115], v[114:115]
	v_pk_mul_f32 v[160:161], v[116:117], v[116:117]
	v_add_f32_e32 v126, v126, v127
	v_add_f32_e32 v151, v160, v161
	v_add_f32_e32 v124, v124, v125
	v_add_f32_e32 v120, v120, v121
	v_add_f32_e32 v118, v118, v119
	v_add_f32_e32 v110, v110, v111
	v_add_f32_e32 v108, v108, v109
	v_add_f32_e32 v98, v98, v99
	v_add_f32_e32 v99, v126, v151
	v_add_f32_e32 v109, v120, v124
	v_add_f32_e32 v110, v110, v118
	v_add_f32_e32 v98, v98, v108
	v_add_f32_e32 v99, v109, v99
	v_add_f32_e32 v98, v98, v110
	v_add_f32_e32 v108, v98, v99
	v_mov_b32_e32 v109, v108
	s_nop 1
	v_permlane16_swap_b32_e32 v108, v109
	v_cvt_pk_bf16_f32 v98, v104, v105
	v_cvt_pk_bf16_f32 v99, v106, v107
	global_store_dwordx4 v[122:123], v[96:99], off
	s_waitcnt lgkmcnt(0)
	s_nop 0
	v_add_f32_e32 v96, v108, v109
	v_mov_b32_e32 v97, v96
	s_nop 1
	v_permlane32_swap_b32_e32 v96, v97
	v_cvt_pk_bf16_f32 v98, v100, v101
	v_cvt_pk_bf16_f32 v99, v102, v103
	v_cvt_pk_bf16_f32 v100, v114, v115
	v_cvt_pk_bf16_f32 v101, v116, v117
	global_store_dwordx4 v[122:123], v[98:101], off offset:256
	s_and_saveexec_b64 s[30:31], s[4:5]
	s_cbranch_execz .LBB0_1155
	v_lshlrev_b64 v[98:99], 6, v[112:113]
	v_lshl_add_u64 v[98:99], s[14:15], 0, v[98:99]
	v_lshl_add_u64 v[98:99], s[28:29], 2, v[98:99]
	s_lshl_b32 s8, s46, 2
	v_lshl_add_u64 v[98:99], v[98:99], 0, s[8:9]
	s_waitcnt lgkmcnt(0)
	v_add_f32_e32 v96, v96, v97
	global_store_dword v[98:99], v96, off
.LBB0_1155:
	s_or_b64 exec, exec, s[30:31]
	v_or_b32_e32 v96, 32, v150
	s_waitcnt lgkmcnt(0)
	v_ashrrev_i32_e32 v97, 31, v96
	v_lshlrev_b64 v[98:99], 11, v[96:97]
	v_lshl_add_u64 v[98:99], s[12:13], 0, v[98:99]
	v_lshl_add_u64 v[106:107], v[148:149], 1, v[98:99]
	s_nop 1
	v_pk_mov_b32 v[98:99], v[192:193], v[192:193] op_sel:[0,1]
	v_pk_mov_b32 v[100:101], v[194:195], v[194:195] op_sel:[0,1]
	v_pk_mov_b32 v[102:103], v[196:197], v[196:197] op_sel:[0,1]
	v_pk_mov_b32 v[104:105], v[198:199], v[198:199] op_sel:[0,1]
	v_lshlrev_b32_e32 v108, 16, v98
	v_and_b32_e32 v109, 0xffff0000, v98
	v_lshlrev_b32_e32 v98, 16, v99
	v_and_b32_e32 v99, 0xffff0000, v99
	v_lshlrev_b32_e32 v110, 16, v100
	v_and_b32_e32 v111, 0xffff0000, v100
	v_lshlrev_b32_e32 v100, 16, v101
	v_and_b32_e32 v101, 0xffff0000, v101
	v_lshlrev_b32_e32 v112, 16, v102
	v_and_b32_e32 v113, 0xffff0000, v102
	v_lshlrev_b32_e32 v102, 16, v103
	v_and_b32_e32 v103, 0xffff0000, v103
	v_lshlrev_b32_e32 v114, 16, v104
	v_and_b32_e32 v115, 0xffff0000, v104
	v_lshlrev_b32_e32 v104, 16, v105
	v_and_b32_e32 v105, 0xffff0000, v105
	v_pk_add_f32 v[92:93], v[92:93], v[108:109]
	v_pk_add_f32 v[94:95], v[94:95], v[98:99]
	v_pk_add_f32 v[88:89], v[88:89], v[110:111]
	v_pk_add_f32 v[90:91], v[90:91], v[100:101]
	v_pk_add_f32 v[84:85], v[84:85], v[112:113]
	v_pk_add_f32 v[86:87], v[86:87], v[102:103]
	v_pk_add_f32 v[98:99], v[80:81], v[114:115]
	v_pk_add_f32 v[100:101], v[82:83], v[104:105]
	v_cvt_pk_bf16_f32 v80, v92, v93
	v_cvt_pk_bf16_f32 v81, v94, v95
	v_pk_mul_f32 v[82:83], v[92:93], v[92:93]
	v_pk_mul_f32 v[92:93], v[94:95], v[94:95]
	v_pk_mul_f32 v[94:95], v[88:89], v[88:89]
	v_pk_mul_f32 v[102:103], v[90:91], v[90:91]
	v_pk_mul_f32 v[104:105], v[84:85], v[84:85]
	v_pk_mul_f32 v[108:109], v[86:87], v[86:87]
	v_pk_mul_f32 v[110:111], v[98:99], v[98:99]
	v_pk_mul_f32 v[112:113], v[100:101], v[100:101]
	v_add_f32_e32 v110, v110, v111
	v_add_f32_e32 v112, v112, v113
	v_add_f32_e32 v108, v108, v109
	v_add_f32_e32 v104, v104, v105
	v_add_f32_e32 v102, v102, v103
	v_add_f32_e32 v94, v94, v95
	v_add_f32_e32 v92, v92, v93
	v_add_f32_e32 v82, v82, v83
	v_add_f32_e32 v83, v110, v112
	v_add_f32_e32 v93, v104, v108
	v_add_f32_e32 v94, v94, v102
	v_add_f32_e32 v82, v82, v92
	v_add_f32_e32 v83, v93, v83
	v_add_f32_e32 v82, v82, v94
	v_add_f32_e32 v92, v82, v83
	v_mov_b32_e32 v93, v92
	s_nop 1
	v_permlane16_swap_b32_e32 v92, v93
	v_cvt_pk_bf16_f32 v82, v88, v89
	v_cvt_pk_bf16_f32 v83, v90, v91
	global_store_dwordx4 v[106:107], v[80:83], off
	s_waitcnt lgkmcnt(0)
	s_nop 0
	v_add_f32_e32 v80, v92, v93
	v_mov_b32_e32 v81, v80
	s_nop 1
	v_permlane32_swap_b32_e32 v80, v81
	v_cvt_pk_bf16_f32 v82, v84, v85
	v_cvt_pk_bf16_f32 v83, v86, v87
	v_cvt_pk_bf16_f32 v84, v98, v99
	v_cvt_pk_bf16_f32 v85, v100, v101
	global_store_dwordx4 v[106:107], v[82:85], off offset:256
	s_and_saveexec_b64 s[30:31], s[4:5]
	s_cbranch_execz .LBB0_1157
	v_lshlrev_b64 v[82:83], 6, v[96:97]
	v_lshl_add_u64 v[82:83], s[14:15], 0, v[82:83]
	v_lshl_add_u64 v[82:83], s[28:29], 2, v[82:83]
	s_lshl_b32 s8, s46, 2
	v_lshl_add_u64 v[82:83], v[82:83], 0, s[8:9]
	s_waitcnt lgkmcnt(0)
	v_add_f32_e32 v80, v80, v81
	global_store_dword v[82:83], v80, off
.LBB0_1157:
	s_or_b64 exec, exec, s[30:31]
	v_or_b32_e32 v80, 48, v150
	s_waitcnt lgkmcnt(0)
	v_ashrrev_i32_e32 v81, 31, v80
	v_lshlrev_b64 v[82:83], 11, v[80:81]
	v_lshl_add_u64 v[82:83], s[12:13], 0, v[82:83]
	v_lshl_add_u64 v[90:91], v[148:149], 1, v[82:83]
	s_nop 1
	v_pk_mov_b32 v[82:83], v[200:201], v[200:201] op_sel:[0,1]
	v_pk_mov_b32 v[84:85], v[202:203], v[202:203] op_sel:[0,1]
	v_pk_mov_b32 v[86:87], v[204:205], v[204:205] op_sel:[0,1]
	v_pk_mov_b32 v[88:89], v[206:207], v[206:207] op_sel:[0,1]
	v_lshlrev_b32_e32 v92, 16, v82
	v_and_b32_e32 v93, 0xffff0000, v82
	v_lshlrev_b32_e32 v82, 16, v83
	v_and_b32_e32 v83, 0xffff0000, v83
	v_lshlrev_b32_e32 v94, 16, v84
	v_and_b32_e32 v95, 0xffff0000, v84
	v_lshlrev_b32_e32 v84, 16, v85
	v_and_b32_e32 v85, 0xffff0000, v85
	v_lshlrev_b32_e32 v96, 16, v86
	v_and_b32_e32 v97, 0xffff0000, v86
	v_lshlrev_b32_e32 v86, 16, v87
	v_and_b32_e32 v87, 0xffff0000, v87
	v_lshlrev_b32_e32 v98, 16, v88
	v_and_b32_e32 v99, 0xffff0000, v88
	v_lshlrev_b32_e32 v88, 16, v89
	v_and_b32_e32 v89, 0xffff0000, v89
	v_pk_add_f32 v[76:77], v[76:77], v[92:93]
	v_pk_add_f32 v[78:79], v[78:79], v[82:83]
	v_pk_add_f32 v[72:73], v[72:73], v[94:95]
	v_pk_add_f32 v[74:75], v[74:75], v[84:85]
	v_pk_add_f32 v[68:69], v[68:69], v[96:97]
	v_pk_add_f32 v[70:71], v[70:71], v[86:87]
	v_pk_add_f32 v[82:83], v[64:65], v[98:99]
	v_pk_add_f32 v[84:85], v[66:67], v[88:89]
	v_cvt_pk_bf16_f32 v64, v76, v77
	v_cvt_pk_bf16_f32 v65, v78, v79
	v_pk_mul_f32 v[66:67], v[76:77], v[76:77]
	v_pk_mul_f32 v[76:77], v[78:79], v[78:79]
	v_pk_mul_f32 v[78:79], v[72:73], v[72:73]
	v_pk_mul_f32 v[86:87], v[74:75], v[74:75]
	v_pk_mul_f32 v[88:89], v[68:69], v[68:69]
	v_pk_mul_f32 v[92:93], v[70:71], v[70:71]
	v_pk_mul_f32 v[94:95], v[82:83], v[82:83]
	v_pk_mul_f32 v[96:97], v[84:85], v[84:85]
	v_add_f32_e32 v94, v94, v95
	v_add_f32_e32 v96, v96, v97
	v_add_f32_e32 v92, v92, v93
	v_add_f32_e32 v88, v88, v89
	v_add_f32_e32 v86, v86, v87
	v_add_f32_e32 v78, v78, v79
	v_add_f32_e32 v76, v76, v77
	v_add_f32_e32 v66, v66, v67
	v_add_f32_e32 v67, v94, v96
	v_add_f32_e32 v77, v88, v92
	v_add_f32_e32 v78, v78, v86
	v_add_f32_e32 v66, v66, v76
	v_add_f32_e32 v67, v77, v67
	v_add_f32_e32 v66, v66, v78
	v_add_f32_e32 v76, v66, v67
	v_mov_b32_e32 v77, v76
	s_nop 1
	v_permlane16_swap_b32_e32 v76, v77
	v_cvt_pk_bf16_f32 v66, v72, v73
	v_cvt_pk_bf16_f32 v67, v74, v75
	global_store_dwordx4 v[90:91], v[64:67], off
	s_waitcnt lgkmcnt(0)
	s_nop 0
	v_add_f32_e32 v64, v76, v77
	v_mov_b32_e32 v65, v64
	s_nop 1
	v_permlane32_swap_b32_e32 v64, v65
	v_cvt_pk_bf16_f32 v66, v68, v69
	v_cvt_pk_bf16_f32 v67, v70, v71
	v_cvt_pk_bf16_f32 v68, v82, v83
	v_cvt_pk_bf16_f32 v69, v84, v85
	global_store_dwordx4 v[90:91], v[66:69], off offset:256
	s_and_saveexec_b64 s[30:31], s[4:5]
	s_cbranch_execz .LBB0_1159
	v_lshlrev_b64 v[66:67], 6, v[80:81]
	v_lshl_add_u64 v[66:67], s[14:15], 0, v[66:67]
	v_lshl_add_u64 v[66:67], s[28:29], 2, v[66:67]
	s_lshl_b32 s8, s46, 2
	v_lshl_add_u64 v[66:67], v[66:67], 0, s[8:9]
	s_waitcnt lgkmcnt(0)
	v_add_f32_e32 v64, v64, v65
	global_store_dword v[66:67], v64, off
.LBB0_1159:
	s_or_b64 exec, exec, s[30:31]
	v_add_u32_e32 v64, 0x80, v150
	s_waitcnt lgkmcnt(0)
	v_ashrrev_i32_e32 v65, 31, v64
	v_lshlrev_b64 v[66:67], 11, v[64:65]
	v_lshl_add_u64 v[66:67], s[12:13], 0, v[66:67]
	v_lshl_add_u64 v[74:75], v[148:149], 1, v[66:67]
	s_nop 1
	v_pk_mov_b32 v[66:67], v[208:209], v[208:209] op_sel:[0,1]
	v_pk_mov_b32 v[68:69], v[210:211], v[210:211] op_sel:[0,1]
	v_pk_mov_b32 v[70:71], v[212:213], v[212:213] op_sel:[0,1]
	v_pk_mov_b32 v[72:73], v[214:215], v[214:215] op_sel:[0,1]
	v_lshlrev_b32_e32 v76, 16, v66
	v_and_b32_e32 v77, 0xffff0000, v66
	v_lshlrev_b32_e32 v66, 16, v67
	v_and_b32_e32 v67, 0xffff0000, v67
	v_lshlrev_b32_e32 v78, 16, v68
	v_and_b32_e32 v79, 0xffff0000, v68
	v_lshlrev_b32_e32 v68, 16, v69
	v_and_b32_e32 v69, 0xffff0000, v69
	v_lshlrev_b32_e32 v80, 16, v70
	v_and_b32_e32 v81, 0xffff0000, v70
	v_lshlrev_b32_e32 v70, 16, v71
	v_and_b32_e32 v71, 0xffff0000, v71
	v_lshlrev_b32_e32 v82, 16, v72
	v_and_b32_e32 v83, 0xffff0000, v72
	v_lshlrev_b32_e32 v72, 16, v73
	v_and_b32_e32 v73, 0xffff0000, v73
	v_pk_add_f32 v[60:61], v[60:61], v[76:77]
	v_pk_add_f32 v[62:63], v[62:63], v[66:67]
	v_pk_add_f32 v[56:57], v[56:57], v[78:79]
	v_pk_add_f32 v[58:59], v[58:59], v[68:69]
	v_pk_add_f32 v[52:53], v[52:53], v[80:81]
	v_pk_add_f32 v[54:55], v[54:55], v[70:71]
	v_pk_add_f32 v[66:67], v[48:49], v[82:83]
	v_pk_add_f32 v[68:69], v[50:51], v[72:73]
	v_cvt_pk_bf16_f32 v48, v60, v61
	v_cvt_pk_bf16_f32 v49, v62, v63
	v_pk_mul_f32 v[50:51], v[60:61], v[60:61]
	v_pk_mul_f32 v[60:61], v[62:63], v[62:63]
	v_pk_mul_f32 v[62:63], v[56:57], v[56:57]
	v_pk_mul_f32 v[70:71], v[58:59], v[58:59]
	v_pk_mul_f32 v[72:73], v[52:53], v[52:53]
	v_pk_mul_f32 v[76:77], v[54:55], v[54:55]
	v_pk_mul_f32 v[78:79], v[66:67], v[66:67]
	v_pk_mul_f32 v[80:81], v[68:69], v[68:69]
	v_add_f32_e32 v78, v78, v79
	v_add_f32_e32 v80, v80, v81
	v_add_f32_e32 v76, v76, v77
	v_add_f32_e32 v72, v72, v73
	v_add_f32_e32 v70, v70, v71
	v_add_f32_e32 v62, v62, v63
	v_add_f32_e32 v60, v60, v61
	v_add_f32_e32 v50, v50, v51
	v_add_f32_e32 v51, v78, v80
	v_add_f32_e32 v61, v72, v76
	v_add_f32_e32 v62, v62, v70
	v_add_f32_e32 v50, v50, v60
	v_add_f32_e32 v51, v61, v51
	v_add_f32_e32 v50, v50, v62
	v_add_f32_e32 v60, v50, v51
	v_mov_b32_e32 v61, v60
	s_nop 1
	v_permlane16_swap_b32_e32 v60, v61
	v_cvt_pk_bf16_f32 v50, v56, v57
	v_cvt_pk_bf16_f32 v51, v58, v59
	global_store_dwordx4 v[74:75], v[48:51], off
	s_waitcnt lgkmcnt(0)
	s_nop 0
	v_add_f32_e32 v48, v60, v61
	v_mov_b32_e32 v49, v48
	s_nop 1
	v_permlane32_swap_b32_e32 v48, v49
	v_cvt_pk_bf16_f32 v50, v52, v53
	v_cvt_pk_bf16_f32 v51, v54, v55
	v_cvt_pk_bf16_f32 v52, v66, v67
	v_cvt_pk_bf16_f32 v53, v68, v69
	global_store_dwordx4 v[74:75], v[50:53], off offset:256
	s_and_saveexec_b64 s[30:31], s[4:5]
	s_cbranch_execz .LBB0_1161
	v_lshlrev_b64 v[50:51], 6, v[64:65]
	v_lshl_add_u64 v[50:51], s[14:15], 0, v[50:51]
	v_lshl_add_u64 v[50:51], s[28:29], 2, v[50:51]
	s_lshl_b32 s8, s46, 2
	v_lshl_add_u64 v[50:51], v[50:51], 0, s[8:9]
	s_waitcnt lgkmcnt(0)
	v_add_f32_e32 v48, v48, v49
	global_store_dword v[50:51], v48, off
.LBB0_1161:
	s_or_b64 exec, exec, s[30:31]
	v_add_u32_e32 v48, 0x90, v150
	s_waitcnt lgkmcnt(0)
	v_ashrrev_i32_e32 v49, 31, v48
	v_lshlrev_b64 v[50:51], 11, v[48:49]
	v_lshl_add_u64 v[50:51], s[12:13], 0, v[50:51]
	v_lshl_add_u64 v[58:59], v[148:149], 1, v[50:51]
	s_nop 1
	v_pk_mov_b32 v[50:51], v[216:217], v[216:217] op_sel:[0,1]
	v_pk_mov_b32 v[52:53], v[218:219], v[218:219] op_sel:[0,1]
	v_pk_mov_b32 v[54:55], v[220:221], v[220:221] op_sel:[0,1]
	v_pk_mov_b32 v[56:57], v[222:223], v[222:223] op_sel:[0,1]
	v_lshlrev_b32_e32 v60, 16, v50
	v_and_b32_e32 v61, 0xffff0000, v50
	v_lshlrev_b32_e32 v50, 16, v51
	v_and_b32_e32 v51, 0xffff0000, v51
	v_lshlrev_b32_e32 v62, 16, v52
	v_and_b32_e32 v63, 0xffff0000, v52
	v_lshlrev_b32_e32 v52, 16, v53
	v_and_b32_e32 v53, 0xffff0000, v53
	v_lshlrev_b32_e32 v64, 16, v54
	v_and_b32_e32 v65, 0xffff0000, v54
	v_lshlrev_b32_e32 v54, 16, v55
	v_and_b32_e32 v55, 0xffff0000, v55
	v_lshlrev_b32_e32 v66, 16, v56
	v_and_b32_e32 v67, 0xffff0000, v56
	v_lshlrev_b32_e32 v56, 16, v57
	v_and_b32_e32 v57, 0xffff0000, v57
	v_pk_add_f32 v[44:45], v[44:45], v[60:61]
	v_pk_add_f32 v[46:47], v[46:47], v[50:51]
	v_pk_add_f32 v[40:41], v[40:41], v[62:63]
	v_pk_add_f32 v[42:43], v[42:43], v[52:53]
	v_pk_add_f32 v[36:37], v[36:37], v[64:65]
	v_pk_add_f32 v[38:39], v[38:39], v[54:55]
	v_pk_add_f32 v[50:51], v[32:33], v[66:67]
	v_pk_add_f32 v[52:53], v[34:35], v[56:57]
	v_cvt_pk_bf16_f32 v32, v44, v45
	v_cvt_pk_bf16_f32 v33, v46, v47
	v_pk_mul_f32 v[34:35], v[44:45], v[44:45]
	v_pk_mul_f32 v[44:45], v[46:47], v[46:47]
	v_pk_mul_f32 v[46:47], v[40:41], v[40:41]
	v_pk_mul_f32 v[54:55], v[42:43], v[42:43]
	v_pk_mul_f32 v[56:57], v[36:37], v[36:37]
	v_pk_mul_f32 v[60:61], v[38:39], v[38:39]
	v_pk_mul_f32 v[62:63], v[50:51], v[50:51]
	v_pk_mul_f32 v[64:65], v[52:53], v[52:53]
	v_add_f32_e32 v62, v62, v63
	v_add_f32_e32 v64, v64, v65
	v_add_f32_e32 v60, v60, v61
	v_add_f32_e32 v56, v56, v57
	v_add_f32_e32 v54, v54, v55
	v_add_f32_e32 v46, v46, v47
	v_add_f32_e32 v44, v44, v45
	v_add_f32_e32 v34, v34, v35
	v_add_f32_e32 v35, v62, v64
	v_add_f32_e32 v45, v56, v60
	v_add_f32_e32 v46, v46, v54
	v_add_f32_e32 v34, v34, v44
	v_add_f32_e32 v35, v45, v35
	v_add_f32_e32 v34, v34, v46
	v_add_f32_e32 v44, v34, v35
	v_mov_b32_e32 v45, v44
	s_nop 1
	v_permlane16_swap_b32_e32 v44, v45
	v_cvt_pk_bf16_f32 v34, v40, v41
	v_cvt_pk_bf16_f32 v35, v42, v43
	global_store_dwordx4 v[58:59], v[32:35], off
	s_waitcnt lgkmcnt(0)
	s_nop 0
	v_add_f32_e32 v32, v44, v45
	v_mov_b32_e32 v33, v32
	s_nop 1
	v_permlane32_swap_b32_e32 v32, v33
	v_cvt_pk_bf16_f32 v34, v36, v37
	v_cvt_pk_bf16_f32 v35, v38, v39
	v_cvt_pk_bf16_f32 v36, v50, v51
	v_cvt_pk_bf16_f32 v37, v52, v53
	global_store_dwordx4 v[58:59], v[34:37], off offset:256
	s_and_saveexec_b64 s[30:31], s[4:5]
	s_cbranch_execz .LBB0_1163
	v_lshlrev_b64 v[34:35], 6, v[48:49]
	v_lshl_add_u64 v[34:35], s[14:15], 0, v[34:35]
	v_lshl_add_u64 v[34:35], s[28:29], 2, v[34:35]
	s_lshl_b32 s8, s46, 2
	v_lshl_add_u64 v[34:35], v[34:35], 0, s[8:9]
	s_waitcnt lgkmcnt(0)
	v_add_f32_e32 v32, v32, v33
	global_store_dword v[34:35], v32, off
.LBB0_1163:
	s_or_b64 exec, exec, s[30:31]
	v_add_u32_e32 v32, 0xa0, v150
	s_waitcnt lgkmcnt(0)
	v_ashrrev_i32_e32 v33, 31, v32
	v_lshlrev_b64 v[34:35], 11, v[32:33]
	v_lshl_add_u64 v[34:35], s[12:13], 0, v[34:35]
	v_lshl_add_u64 v[42:43], v[148:149], 1, v[34:35]
	s_nop 1
	v_pk_mov_b32 v[34:35], v[224:225], v[224:225] op_sel:[0,1]
	v_pk_mov_b32 v[36:37], v[226:227], v[226:227] op_sel:[0,1]
	v_pk_mov_b32 v[38:39], v[228:229], v[228:229] op_sel:[0,1]
	v_pk_mov_b32 v[40:41], v[230:231], v[230:231] op_sel:[0,1]
	v_lshlrev_b32_e32 v44, 16, v34
	v_and_b32_e32 v45, 0xffff0000, v34
	v_lshlrev_b32_e32 v34, 16, v35
	v_and_b32_e32 v35, 0xffff0000, v35
	v_lshlrev_b32_e32 v46, 16, v36
	v_and_b32_e32 v47, 0xffff0000, v36
	v_lshlrev_b32_e32 v36, 16, v37
	v_and_b32_e32 v37, 0xffff0000, v37
	v_lshlrev_b32_e32 v48, 16, v38
	v_and_b32_e32 v49, 0xffff0000, v38
	v_lshlrev_b32_e32 v38, 16, v39
	v_and_b32_e32 v39, 0xffff0000, v39
	v_lshlrev_b32_e32 v50, 16, v40
	v_and_b32_e32 v51, 0xffff0000, v40
	v_lshlrev_b32_e32 v40, 16, v41
	v_and_b32_e32 v41, 0xffff0000, v41
	v_pk_add_f32 v[28:29], v[28:29], v[44:45]
	v_pk_add_f32 v[30:31], v[30:31], v[34:35]
	v_pk_add_f32 v[24:25], v[24:25], v[46:47]
	v_pk_add_f32 v[26:27], v[26:27], v[36:37]
	v_pk_add_f32 v[20:21], v[20:21], v[48:49]
	v_pk_add_f32 v[22:23], v[22:23], v[38:39]
	v_pk_add_f32 v[34:35], v[16:17], v[50:51]
	v_pk_add_f32 v[36:37], v[18:19], v[40:41]
	v_cvt_pk_bf16_f32 v16, v28, v29
	v_cvt_pk_bf16_f32 v17, v30, v31
	v_pk_mul_f32 v[18:19], v[28:29], v[28:29]
	v_pk_mul_f32 v[28:29], v[30:31], v[30:31]
	v_pk_mul_f32 v[30:31], v[24:25], v[24:25]
	v_pk_mul_f32 v[38:39], v[26:27], v[26:27]
	v_pk_mul_f32 v[40:41], v[20:21], v[20:21]
	v_pk_mul_f32 v[44:45], v[22:23], v[22:23]
	v_pk_mul_f32 v[46:47], v[34:35], v[34:35]
	v_pk_mul_f32 v[48:49], v[36:37], v[36:37]
	v_add_f32_e32 v46, v46, v47
	v_add_f32_e32 v48, v48, v49
	v_add_f32_e32 v44, v44, v45
	v_add_f32_e32 v40, v40, v41
	v_add_f32_e32 v38, v38, v39
	v_add_f32_e32 v30, v30, v31
	v_add_f32_e32 v28, v28, v29
	v_add_f32_e32 v18, v18, v19
	v_add_f32_e32 v19, v46, v48
	v_add_f32_e32 v29, v40, v44
	v_add_f32_e32 v30, v30, v38
	v_add_f32_e32 v18, v18, v28
	v_add_f32_e32 v19, v29, v19
	v_add_f32_e32 v18, v18, v30
	v_add_f32_e32 v28, v18, v19
	v_mov_b32_e32 v29, v28
	s_nop 1
	v_permlane16_swap_b32_e32 v28, v29
	v_cvt_pk_bf16_f32 v18, v24, v25
	v_cvt_pk_bf16_f32 v19, v26, v27
	global_store_dwordx4 v[42:43], v[16:19], off
	s_waitcnt lgkmcnt(0)
	s_nop 0
	v_add_f32_e32 v16, v28, v29
	v_mov_b32_e32 v17, v16
	s_nop 1
	v_permlane32_swap_b32_e32 v16, v17
	v_cvt_pk_bf16_f32 v18, v20, v21
	v_cvt_pk_bf16_f32 v19, v22, v23
	v_cvt_pk_bf16_f32 v20, v34, v35
	v_cvt_pk_bf16_f32 v21, v36, v37
	global_store_dwordx4 v[42:43], v[18:21], off offset:256
	s_and_saveexec_b64 s[30:31], s[4:5]
	s_cbranch_execz .LBB0_1165
	v_lshlrev_b64 v[18:19], 6, v[32:33]
	v_lshl_add_u64 v[18:19], s[14:15], 0, v[18:19]
	v_lshl_add_u64 v[18:19], s[28:29], 2, v[18:19]
	s_lshl_b32 s8, s46, 2
	v_lshl_add_u64 v[18:19], v[18:19], 0, s[8:9]
	s_waitcnt lgkmcnt(0)
	v_add_f32_e32 v16, v16, v17
	global_store_dword v[18:19], v16, off
.LBB0_1165:
	s_or_b64 exec, exec, s[30:31]
	v_add_u32_e32 v16, 0xb0, v150
	s_waitcnt lgkmcnt(0)
	v_ashrrev_i32_e32 v17, 31, v16
	v_lshlrev_b64 v[18:19], 11, v[16:17]
	v_lshl_add_u64 v[18:19], s[12:13], 0, v[18:19]
	v_lshl_add_u64 v[26:27], v[148:149], 1, v[18:19]
	s_nop 1
	v_pk_mov_b32 v[18:19], v[238:239], v[238:239] op_sel:[0,1]
	v_pk_mov_b32 v[20:21], v[240:241], v[240:241] op_sel:[0,1]
	v_pk_mov_b32 v[22:23], v[242:243], v[242:243] op_sel:[0,1]
	v_pk_mov_b32 v[24:25], v[244:245], v[244:245] op_sel:[0,1]
	v_lshlrev_b32_e32 v28, 16, v18
	v_and_b32_e32 v29, 0xffff0000, v18
	v_lshlrev_b32_e32 v18, 16, v19
	v_and_b32_e32 v19, 0xffff0000, v19
	v_lshlrev_b32_e32 v30, 16, v20
	v_and_b32_e32 v31, 0xffff0000, v20
	v_lshlrev_b32_e32 v20, 16, v21
	v_and_b32_e32 v21, 0xffff0000, v21
	v_lshlrev_b32_e32 v32, 16, v22
	v_and_b32_e32 v33, 0xffff0000, v22
	v_lshlrev_b32_e32 v22, 16, v23
	v_and_b32_e32 v23, 0xffff0000, v23
	v_lshlrev_b32_e32 v34, 16, v24
	v_and_b32_e32 v35, 0xffff0000, v24
	v_lshlrev_b32_e32 v24, 16, v25
	v_and_b32_e32 v25, 0xffff0000, v25
	v_pk_add_f32 v[12:13], v[12:13], v[28:29]
	v_pk_add_f32 v[14:15], v[14:15], v[18:19]
	v_pk_add_f32 v[8:9], v[8:9], v[30:31]
	v_pk_add_f32 v[10:11], v[10:11], v[20:21]
	v_pk_add_f32 v[4:5], v[4:5], v[32:33]
	v_pk_add_f32 v[6:7], v[6:7], v[22:23]
	v_pk_add_f32 v[18:19], v[0:1], v[34:35]
	v_pk_add_f32 v[20:21], v[2:3], v[24:25]
	v_cvt_pk_bf16_f32 v0, v12, v13
	v_cvt_pk_bf16_f32 v1, v14, v15
	v_pk_mul_f32 v[2:3], v[12:13], v[12:13]
	v_pk_mul_f32 v[12:13], v[14:15], v[14:15]
	v_pk_mul_f32 v[14:15], v[8:9], v[8:9]
	v_pk_mul_f32 v[22:23], v[10:11], v[10:11]
	v_pk_mul_f32 v[24:25], v[4:5], v[4:5]
	v_pk_mul_f32 v[28:29], v[6:7], v[6:7]
	v_pk_mul_f32 v[30:31], v[18:19], v[18:19]
	v_pk_mul_f32 v[32:33], v[20:21], v[20:21]
	v_add_f32_e32 v30, v30, v31
	v_add_f32_e32 v32, v32, v33
	v_add_f32_e32 v28, v28, v29
	v_add_f32_e32 v24, v24, v25
	v_add_f32_e32 v22, v22, v23
	v_add_f32_e32 v14, v14, v15
	v_add_f32_e32 v12, v12, v13
	v_add_f32_e32 v2, v2, v3
	v_add_f32_e32 v3, v30, v32
	v_add_f32_e32 v13, v24, v28
	v_add_f32_e32 v14, v14, v22
	v_add_f32_e32 v2, v2, v12
	v_add_f32_e32 v3, v13, v3
	v_add_f32_e32 v2, v2, v14
	v_add_f32_e32 v12, v2, v3
	v_mov_b32_e32 v13, v12
	s_nop 1
	v_permlane16_swap_b32_e32 v12, v13
	v_cvt_pk_bf16_f32 v2, v8, v9
	v_cvt_pk_bf16_f32 v3, v10, v11
	global_store_dwordx4 v[26:27], v[0:3], off
	s_waitcnt lgkmcnt(0)
	s_nop 0
	v_add_f32_e32 v0, v12, v13
	v_mov_b32_e32 v1, v0
	s_nop 1
	v_permlane32_swap_b32_e32 v0, v1
	v_cvt_pk_bf16_f32 v2, v4, v5
	v_cvt_pk_bf16_f32 v3, v6, v7
	v_cvt_pk_bf16_f32 v4, v18, v19
	v_cvt_pk_bf16_f32 v5, v20, v21
	global_store_dwordx4 v[26:27], v[2:5], off offset:256
	s_and_saveexec_b64 s[30:31], s[4:5]
	s_cbranch_execz .LBB0_1167
	v_lshlrev_b64 v[2:3], 6, v[16:17]
	v_lshl_add_u64 v[2:3], s[14:15], 0, v[2:3]
	v_lshl_add_u64 v[2:3], s[28:29], 2, v[2:3]
	s_lshl_b32 s8, s46, 2
	v_lshl_add_u64 v[2:3], v[2:3], 0, s[8:9]
	s_waitcnt lgkmcnt(0)
	v_add_f32_e32 v0, v0, v1
	global_store_dword v[2:3], v0, off

.LBB0_1238:
	v_lshl_add_u32 v152, s0, 8, v131
	v_ashrrev_i32_e32 v153, 31, v152
	v_lshlrev_b64 v[150:151], 6, v[152:153]
	v_lshl_add_u64 v[150:151], v[140:141], 0, v[150:151]
	global_load_dwordx4 v[162:165], v[150:151], off
	global_load_dwordx4 v[188:191], v[150:151], off offset:1024
	global_load_dwordx4 v[192:195], v[150:151], off offset:2048
	global_load_dwordx4 v[196:199], v[150:151], off offset:3072
	v_mov_b32_e32 v216, 0x2000
	v_mov_b32_e32 v217, 0
	v_lshl_add_u64 v[216:217], v[150:151], 0, v[216:217]
	global_load_dwordx4 v[200:203], v[216:217], off
	global_load_dwordx4 v[204:207], v[216:217], off offset:1024
	global_load_dwordx4 v[208:211], v[216:217], off offset:2048
	global_load_dwordx4 v[212:215], v[216:217], off offset:3072
	v_and_b32_e32 v161, 64, v159
	v_xor_b32_e32 v153, 16, v159
	v_pk_mul_f32 v[168:169], v[114:115], v[122:123]
	v_add_u32_e32 v122, 64, v161
	v_cmp_lt_i32_e32 vcc, v153, v122
	v_pk_mul_f32 v[170:171], v[112:113], v[120:121]
	v_xor_b32_e32 v172, 32, v159
	v_cndmask_b32_e32 v120, v159, v153, vcc
	v_lshlrev_b32_e32 v123, 2, v120
	v_cmp_lt_i32_e32 vcc, v172, v122
	v_pk_mul_f32 v[126:127], v[118:119], v[126:127]
	v_pk_mul_f32 v[124:125], v[116:117], v[124:125]
	v_cndmask_b32_e32 v122, v159, v172, vcc
	v_lshlrev_b32_e32 v122, 2, v122
	v_lshl_or_b32 v166, s1, 7, v155
	v_ashrrev_i32_e32 v167, 31, v166
	v_mov_b64_e32 v[150:151], s[10:11]
	v_pk_mul_f32 v[110:111], v[102:103], v[110:111]
	v_pk_mul_f32 v[108:109], v[100:101], v[108:109]
	v_pk_mul_f32 v[106:107], v[98:99], v[106:107]
	v_pk_mul_f32 v[104:105], v[96:97], v[104:105]
	v_pk_mul_f32 v[94:95], v[86:87], v[94:95]
	v_pk_mul_f32 v[92:93], v[84:85], v[92:93]
	v_pk_mul_f32 v[90:91], v[82:83], v[90:91]
	v_pk_mul_f32 v[88:89], v[80:81], v[88:89]
	v_pk_mul_f32 v[78:79], v[70:71], v[78:79]
	v_pk_mul_f32 v[76:77], v[68:69], v[76:77]
	v_pk_mul_f32 v[74:75], v[66:67], v[74:75]
	v_pk_mul_f32 v[72:73], v[64:65], v[72:73]
	v_pk_mul_f32 v[62:63], v[54:55], v[62:63]
	v_pk_mul_f32 v[60:61], v[52:53], v[60:61]
	v_pk_mul_f32 v[58:59], v[50:51], v[58:59]
	v_pk_mul_f32 v[56:57], v[48:49], v[56:57]
	v_pk_mul_f32 v[46:47], v[38:39], v[46:47]
	v_pk_mul_f32 v[44:45], v[36:37], v[44:45]
	v_pk_mul_f32 v[42:43], v[34:35], v[42:43]
	v_pk_mul_f32 v[40:41], v[32:33], v[40:41]
	v_pk_mul_f32 v[30:31], v[22:23], v[30:31]
	v_pk_mul_f32 v[28:29], v[20:21], v[28:29]
	v_pk_mul_f32 v[26:27], v[18:19], v[26:27]
	v_pk_mul_f32 v[24:25], v[16:17], v[24:25]
	v_pk_mul_f32 v[14:15], v[6:7], v[14:15]
	v_pk_mul_f32 v[12:13], v[4:5], v[12:13]
	v_pk_mul_f32 v[10:11], v[2:3], v[10:11]
	v_pk_mul_f32 v[8:9], v[0:1], v[8:9]
	s_waitcnt vmcnt(0)
	v_mov_b32_e32 v120, v163
	v_mov_b32_e32 v121, v164
	v_mov_b32_e32 v163, v165
	v_pk_add_f32 v[120:121], v[120:121], v[162:163]
	v_or_b32_e32 v164, 16, v152
	v_add_f32_e32 v120, v120, v121
	v_mov_b32_e32 v121, v120
	s_nop 1
	v_permlane16_swap_b32_e32 v120, v121
	v_ashrrev_i32_e32 v165, 31, v164
	v_mad_i64_i32 v[162:163], s[0:1], v152, s49, v[150:151]
	s_waitcnt lgkmcnt(0)
	v_add_f32_e32 v153, v120, v121
	v_mov_b32_e32 v161, v153
	s_nop 1
	v_permlane32_swap_b32_e32 v153, v161
	v_lshlrev_b64 v[120:121], 1, v[166:167]
	v_lshlrev_b64 v[166:167], 6, v[164:165]
	v_lshl_add_u64 v[162:163], v[162:163], 0, v[120:121]
	v_lshl_add_u64 v[166:167], v[140:141], 0, v[166:167]
	s_waitcnt lgkmcnt(0)
	v_add_f32_e32 v153, v153, v161
	v_fmamk_f32 v153, v153, 0x3a800000, v160
	v_mul_f32_e32 v161, 0x4b800000, v153
	v_cmp_gt_f32_e32 vcc, s52, v153
	s_nop 1
	v_cndmask_b32_e32 v153, v153, v161, vcc
	v_rsq_f32_e32 v153, v153
	s_nop 0
	v_mul_f32_e32 v161, 0x45800000, v153
	v_cndmask_b32_e32 v153, v153, v161, vcc
	v_mul_f32_e32 v161, 0xbfb8aa3b, v153
	v_mul_f32_e32 v116, v116, v161
	v_mul_f32_e32 v117, v117, v161
	v_mul_f32_e32 v118, v118, v161
	v_mul_f32_e32 v119, v119, v161
	v_mul_f32_e32 v112, v112, v161
	v_mul_f32_e32 v113, v113, v161
	v_mul_f32_e32 v114, v114, v161
	v_mul_f32_e32 v115, v115, v161
	v_exp_f32_e32 v116, v116
	v_exp_f32_e32 v117, v117
	v_exp_f32_e32 v118, v118
	v_exp_f32_e32 v119, v119
	v_exp_f32_e32 v112, v112
	v_exp_f32_e32 v113, v113
	v_exp_f32_e32 v114, v114
	v_exp_f32_e32 v115, v115
	v_mul_f32_e32 v172, v153, v153
	v_add_f32_e32 v116, 1.0, v116
	v_add_f32_e32 v117, 1.0, v117
	v_add_f32_e32 v118, 1.0, v118
	v_add_f32_e32 v119, 1.0, v119
	v_add_f32_e32 v153, 1.0, v112
	v_add_f32_e32 v161, 1.0, v113
	v_add_f32_e32 v165, 1.0, v114
	v_add_f32_e32 v173, 1.0, v115
	v_rcp_f32_e32 v112, v116
	v_rcp_f32_e32 v113, v117
	v_rcp_f32_e32 v114, v118
	v_rcp_f32_e32 v115, v119
	v_rcp_f32_e32 v116, v153
	v_rcp_f32_e32 v117, v161
	v_rcp_f32_e32 v118, v165
	v_rcp_f32_e32 v119, v173
	v_pk_mul_f32 v[112:113], v[172:173], v[112:113] op_sel_hi:[0,1]
	v_pk_mul_f32 v[114:115], v[172:173], v[114:115] op_sel_hi:[0,1]
	v_pk_mul_f32 v[116:117], v[172:173], v[116:117] op_sel_hi:[0,1]
	v_pk_mul_f32 v[118:119], v[172:173], v[118:119] op_sel_hi:[0,1]
	v_pk_mul_f32 v[112:113], v[124:125], v[112:113]
	v_pk_mul_f32 v[114:115], v[126:127], v[114:115]
	v_pk_mul_f32 v[116:117], v[170:171], v[116:117]
	v_pk_mul_f32 v[118:119], v[168:169], v[118:119]
	v_cvt_pk_bf16_f32 v112, v112, v113
	v_cvt_pk_bf16_f32 v113, v114, v115
	v_cvt_pk_bf16_f32 v114, v116, v117
	v_cvt_pk_bf16_f32 v115, v118, v119
	global_store_dwordx4 v[162:163], v[112:115], off
	s_nop 1
	v_pk_mov_b32 v[112:113], v[188:189], v[188:189] op_sel:[0,1]
	v_pk_mov_b32 v[114:115], v[190:191], v[190:191] op_sel:[0,1]
	v_mov_b32_e32 v116, v113
	v_mov_b32_e32 v117, v114
	v_mov_b32_e32 v113, v115
	v_pk_add_f32 v[112:113], v[116:117], v[112:113]
	v_mad_i64_i32 v[114:115], s[0:1], v164, s49, v[150:151]
	v_add_f32_e32 v112, v112, v113
	v_mov_b32_e32 v113, v112
	s_nop 1
	v_permlane16_swap_b32_e32 v112, v113
	v_lshl_add_u64 v[114:115], v[114:115], 0, v[120:121]
	s_waitcnt lgkmcnt(0)
	v_add_f32_e32 v116, v112, v113
	v_mov_b32_e32 v117, v116
	s_nop 1
	v_permlane32_swap_b32_e32 v116, v117
	v_or_b32_e32 v112, 32, v152
	v_ashrrev_i32_e32 v113, 31, v112
	s_waitcnt lgkmcnt(0)
	v_add_f32_e32 v116, v116, v117
	v_fmamk_f32 v116, v116, 0x3a800000, v160
	v_mul_f32_e32 v117, 0x4b800000, v116
	v_cmp_gt_f32_e32 vcc, s52, v116
	s_nop 1
	v_cndmask_b32_e32 v116, v116, v117, vcc
	v_rsq_f32_e32 v118, v116
	v_lshlrev_b64 v[116:117], 6, v[112:113]
	v_lshl_add_u64 v[116:117], v[140:141], 0, v[116:117]
	v_mul_f32_e32 v113, 0x45800000, v118
	v_cndmask_b32_e32 v113, v118, v113, vcc
	v_mul_f32_e32 v119, 0xbfb8aa3b, v113
	v_mul_f32_e32 v100, v100, v119
	v_mul_f32_e32 v101, v101, v119
	v_mul_f32_e32 v102, v102, v119
	v_mul_f32_e32 v103, v103, v119
	v_mul_f32_e32 v96, v96, v119
	v_mul_f32_e32 v97, v97, v119
	v_mul_f32_e32 v98, v98, v119
	v_mul_f32_e32 v99, v99, v119
	v_exp_f32_e32 v100, v100
	v_exp_f32_e32 v101, v101
	v_exp_f32_e32 v102, v102
	v_exp_f32_e32 v103, v103
	v_exp_f32_e32 v96, v96
	v_exp_f32_e32 v97, v97
	v_exp_f32_e32 v98, v98
	v_exp_f32_e32 v99, v99
	v_mul_f32_e32 v118, v113, v113
	v_add_f32_e32 v100, 1.0, v100
	v_add_f32_e32 v101, 1.0, v101
	v_add_f32_e32 v102, 1.0, v102
	v_add_f32_e32 v103, 1.0, v103
	v_add_f32_e32 v113, 1.0, v96
	v_add_f32_e32 v119, 1.0, v97
	v_add_f32_e32 v124, 1.0, v98
	v_add_f32_e32 v125, 1.0, v99
	v_rcp_f32_e32 v96, v100
	v_rcp_f32_e32 v97, v101
	v_rcp_f32_e32 v98, v102
	v_rcp_f32_e32 v99, v103
	v_rcp_f32_e32 v100, v113
	v_rcp_f32_e32 v101, v119
	v_rcp_f32_e32 v102, v124
	v_rcp_f32_e32 v103, v125
	v_pk_mul_f32 v[96:97], v[118:119], v[96:97] op_sel_hi:[0,1]
	v_pk_mul_f32 v[98:99], v[118:119], v[98:99] op_sel_hi:[0,1]
	v_pk_mul_f32 v[100:101], v[118:119], v[100:101] op_sel_hi:[0,1]
	v_pk_mul_f32 v[102:103], v[118:119], v[102:103] op_sel_hi:[0,1]
	v_pk_mul_f32 v[96:97], v[108:109], v[96:97]
	v_pk_mul_f32 v[98:99], v[110:111], v[98:99]
	v_pk_mul_f32 v[100:101], v[104:105], v[100:101]
	v_pk_mul_f32 v[102:103], v[106:107], v[102:103]
	v_cvt_pk_bf16_f32 v96, v96, v97
	v_cvt_pk_bf16_f32 v97, v98, v99
	v_cvt_pk_bf16_f32 v98, v100, v101
	v_cvt_pk_bf16_f32 v99, v102, v103
	global_store_dwordx4 v[114:115], v[96:99], off
	s_nop 1
	v_pk_mov_b32 v[96:97], v[192:193], v[192:193] op_sel:[0,1]
	v_pk_mov_b32 v[98:99], v[194:195], v[194:195] op_sel:[0,1]
	v_mov_b32_e32 v100, v97
	v_mov_b32_e32 v101, v98
	v_mov_b32_e32 v97, v99
	v_pk_add_f32 v[96:97], v[100:101], v[96:97]
	v_mad_i64_i32 v[98:99], s[0:1], v112, s49, v[150:151]
	v_add_f32_e32 v96, v96, v97
	v_mov_b32_e32 v97, v96
	s_nop 1
	v_permlane16_swap_b32_e32 v96, v97
	v_lshl_add_u64 v[98:99], v[98:99], 0, v[120:121]
	s_waitcnt lgkmcnt(0)
	v_add_f32_e32 v100, v96, v97
	v_mov_b32_e32 v101, v100
	s_nop 1
	v_permlane32_swap_b32_e32 v100, v101
	v_or_b32_e32 v96, 48, v152
	v_ashrrev_i32_e32 v97, 31, v96
	s_waitcnt lgkmcnt(0)
	v_add_f32_e32 v100, v100, v101
	v_fmamk_f32 v100, v100, 0x3a800000, v160
	v_mul_f32_e32 v101, 0x4b800000, v100
	v_cmp_gt_f32_e32 vcc, s52, v100
	s_nop 1
	v_cndmask_b32_e32 v100, v100, v101, vcc
	v_rsq_f32_e32 v102, v100
	v_lshlrev_b64 v[100:101], 6, v[96:97]
	v_lshl_add_u64 v[100:101], v[140:141], 0, v[100:101]
	v_mul_f32_e32 v97, 0x45800000, v102
	v_cndmask_b32_e32 v97, v102, v97, vcc
	v_mul_f32_e32 v103, 0xbfb8aa3b, v97
	v_mul_f32_e32 v84, v84, v103
	v_mul_f32_e32 v85, v85, v103
	v_mul_f32_e32 v86, v86, v103
	v_mul_f32_e32 v87, v87, v103
	v_mul_f32_e32 v80, v80, v103
	v_mul_f32_e32 v81, v81, v103
	v_mul_f32_e32 v82, v82, v103
	v_mul_f32_e32 v83, v83, v103
	v_exp_f32_e32 v84, v84
	v_exp_f32_e32 v85, v85
	v_exp_f32_e32 v86, v86
	v_exp_f32_e32 v87, v87
	v_exp_f32_e32 v80, v80
	v_exp_f32_e32 v81, v81
	v_exp_f32_e32 v82, v82
	v_exp_f32_e32 v83, v83
	v_mul_f32_e32 v102, v97, v97
	v_add_f32_e32 v84, 1.0, v84
	v_add_f32_e32 v85, 1.0, v85
	v_add_f32_e32 v86, 1.0, v86
	v_add_f32_e32 v87, 1.0, v87
	v_add_f32_e32 v97, 1.0, v80
	v_add_f32_e32 v103, 1.0, v81
	v_add_f32_e32 v104, 1.0, v82
	v_add_f32_e32 v105, 1.0, v83
	v_rcp_f32_e32 v80, v84
	v_rcp_f32_e32 v81, v85
	v_rcp_f32_e32 v82, v86
	v_rcp_f32_e32 v83, v87
	v_rcp_f32_e32 v84, v97
	v_rcp_f32_e32 v85, v103
	v_rcp_f32_e32 v86, v104
	v_rcp_f32_e32 v87, v105
	v_pk_mul_f32 v[80:81], v[102:103], v[80:81] op_sel_hi:[0,1]
	v_pk_mul_f32 v[82:83], v[102:103], v[82:83] op_sel_hi:[0,1]
	v_pk_mul_f32 v[84:85], v[102:103], v[84:85] op_sel_hi:[0,1]
	v_pk_mul_f32 v[86:87], v[102:103], v[86:87] op_sel_hi:[0,1]
	v_pk_mul_f32 v[80:81], v[92:93], v[80:81]
	v_pk_mul_f32 v[82:83], v[94:95], v[82:83]
	v_pk_mul_f32 v[84:85], v[88:89], v[84:85]
	v_pk_mul_f32 v[86:87], v[90:91], v[86:87]
	v_cvt_pk_bf16_f32 v80, v80, v81
	v_cvt_pk_bf16_f32 v81, v82, v83
	v_cvt_pk_bf16_f32 v82, v84, v85
	v_cvt_pk_bf16_f32 v83, v86, v87
	global_store_dwordx4 v[98:99], v[80:83], off
	s_nop 1
	v_pk_mov_b32 v[80:81], v[196:197], v[196:197] op_sel:[0,1]
	v_pk_mov_b32 v[82:83], v[198:199], v[198:199] op_sel:[0,1]
	v_mov_b32_e32 v84, v81
	v_mov_b32_e32 v85, v82
	v_mov_b32_e32 v81, v83
	v_pk_add_f32 v[80:81], v[84:85], v[80:81]
	v_mad_i64_i32 v[82:83], s[0:1], v96, s49, v[150:151]
	v_add_f32_e32 v80, v80, v81
	v_mov_b32_e32 v81, v80
	s_nop 1
	v_permlane16_swap_b32_e32 v80, v81
	v_lshl_add_u64 v[82:83], v[82:83], 0, v[120:121]
	s_waitcnt lgkmcnt(0)
	v_add_f32_e32 v84, v80, v81
	v_mov_b32_e32 v85, v84
	s_nop 1
	v_permlane32_swap_b32_e32 v84, v85
	v_add_u32_e32 v80, 0x80, v152
	v_ashrrev_i32_e32 v81, 31, v80
	s_waitcnt lgkmcnt(0)
	v_add_f32_e32 v84, v84, v85
	v_fmamk_f32 v84, v84, 0x3a800000, v160
	v_mul_f32_e32 v85, 0x4b800000, v84
	v_cmp_gt_f32_e32 vcc, s52, v84
	s_nop 1
	v_cndmask_b32_e32 v84, v84, v85, vcc
	v_rsq_f32_e32 v86, v84
	v_lshlrev_b64 v[84:85], 6, v[80:81]
	v_lshl_add_u64 v[84:85], v[140:141], 0, v[84:85]
	v_mul_f32_e32 v81, 0x45800000, v86
	v_cndmask_b32_e32 v81, v86, v81, vcc
	v_mul_f32_e32 v87, 0xbfb8aa3b, v81
	v_mul_f32_e32 v68, v68, v87
	v_mul_f32_e32 v69, v69, v87
	v_mul_f32_e32 v70, v70, v87
	v_mul_f32_e32 v71, v71, v87
	v_mul_f32_e32 v64, v64, v87
	v_mul_f32_e32 v65, v65, v87
	v_mul_f32_e32 v66, v66, v87
	v_mul_f32_e32 v67, v67, v87
	v_exp_f32_e32 v68, v68
	v_exp_f32_e32 v69, v69
	v_exp_f32_e32 v70, v70
	v_exp_f32_e32 v71, v71
	v_exp_f32_e32 v64, v64
	v_exp_f32_e32 v65, v65
	v_exp_f32_e32 v66, v66
	v_exp_f32_e32 v67, v67
	v_mul_f32_e32 v86, v81, v81
	v_add_f32_e32 v68, 1.0, v68
	v_add_f32_e32 v69, 1.0, v69
	v_add_f32_e32 v70, 1.0, v70
	v_add_f32_e32 v71, 1.0, v71
	v_add_f32_e32 v81, 1.0, v64
	v_add_f32_e32 v87, 1.0, v65
	v_add_f32_e32 v88, 1.0, v66
	v_add_f32_e32 v89, 1.0, v67
	v_rcp_f32_e32 v64, v68
	v_rcp_f32_e32 v65, v69
	v_rcp_f32_e32 v66, v70
	v_rcp_f32_e32 v67, v71
	v_rcp_f32_e32 v68, v81
	v_rcp_f32_e32 v69, v87
	v_rcp_f32_e32 v70, v88
	v_rcp_f32_e32 v71, v89
	v_pk_mul_f32 v[64:65], v[86:87], v[64:65] op_sel_hi:[0,1]
	v_pk_mul_f32 v[66:67], v[86:87], v[66:67] op_sel_hi:[0,1]
	v_pk_mul_f32 v[68:69], v[86:87], v[68:69] op_sel_hi:[0,1]
	v_pk_mul_f32 v[70:71], v[86:87], v[70:71] op_sel_hi:[0,1]
	v_pk_mul_f32 v[64:65], v[76:77], v[64:65]
	v_pk_mul_f32 v[66:67], v[78:79], v[66:67]
	v_pk_mul_f32 v[68:69], v[72:73], v[68:69]
	v_pk_mul_f32 v[70:71], v[74:75], v[70:71]
	v_cvt_pk_bf16_f32 v64, v64, v65
	v_cvt_pk_bf16_f32 v65, v66, v67
	v_cvt_pk_bf16_f32 v66, v68, v69
	v_cvt_pk_bf16_f32 v67, v70, v71
	global_store_dwordx4 v[82:83], v[64:67], off
	s_nop 1
	v_pk_mov_b32 v[64:65], v[200:201], v[200:201] op_sel:[0,1]
	v_pk_mov_b32 v[66:67], v[202:203], v[202:203] op_sel:[0,1]
	v_mov_b32_e32 v68, v65
	v_mov_b32_e32 v69, v66
	v_mov_b32_e32 v65, v67
	v_pk_add_f32 v[64:65], v[68:69], v[64:65]
	v_mad_i64_i32 v[66:67], s[0:1], v80, s49, v[150:151]
	v_add_f32_e32 v64, v64, v65
	v_mov_b32_e32 v65, v64
	s_nop 1
	v_permlane16_swap_b32_e32 v64, v65
	v_lshl_add_u64 v[66:67], v[66:67], 0, v[120:121]
	s_waitcnt lgkmcnt(0)
	v_add_f32_e32 v68, v64, v65
	v_mov_b32_e32 v69, v68
	s_nop 1
	v_permlane32_swap_b32_e32 v68, v69
	v_add_u32_e32 v64, 0x90, v152
	v_ashrrev_i32_e32 v65, 31, v64
	s_waitcnt lgkmcnt(0)
	v_add_f32_e32 v68, v68, v69
	v_fmamk_f32 v68, v68, 0x3a800000, v160
	v_mul_f32_e32 v69, 0x4b800000, v68
	v_cmp_gt_f32_e32 vcc, s52, v68
	s_nop 1
	v_cndmask_b32_e32 v68, v68, v69, vcc
	v_rsq_f32_e32 v70, v68
	v_lshlrev_b64 v[68:69], 6, v[64:65]
	v_lshl_add_u64 v[68:69], v[140:141], 0, v[68:69]
	v_mul_f32_e32 v65, 0x45800000, v70
	v_cndmask_b32_e32 v65, v70, v65, vcc
	v_mul_f32_e32 v71, 0xbfb8aa3b, v65
	v_mul_f32_e32 v52, v52, v71
	v_mul_f32_e32 v53, v53, v71
	v_mul_f32_e32 v54, v54, v71
	v_mul_f32_e32 v55, v55, v71
	v_mul_f32_e32 v48, v48, v71
	v_mul_f32_e32 v49, v49, v71
	v_mul_f32_e32 v50, v50, v71
	v_mul_f32_e32 v51, v51, v71
	v_exp_f32_e32 v52, v52
	v_exp_f32_e32 v53, v53
	v_exp_f32_e32 v54, v54
	v_exp_f32_e32 v55, v55
	v_exp_f32_e32 v48, v48
	v_exp_f32_e32 v49, v49
	v_exp_f32_e32 v50, v50
	v_exp_f32_e32 v51, v51
	v_mul_f32_e32 v70, v65, v65
	v_add_f32_e32 v52, 1.0, v52
	v_add_f32_e32 v53, 1.0, v53
	v_add_f32_e32 v54, 1.0, v54
	v_add_f32_e32 v55, 1.0, v55
	v_add_f32_e32 v65, 1.0, v48
	v_add_f32_e32 v71, 1.0, v49
	v_add_f32_e32 v72, 1.0, v50
	v_add_f32_e32 v73, 1.0, v51
	v_rcp_f32_e32 v48, v52
	v_rcp_f32_e32 v49, v53
	v_rcp_f32_e32 v50, v54
	v_rcp_f32_e32 v51, v55
	v_rcp_f32_e32 v52, v65
	v_rcp_f32_e32 v53, v71
	v_rcp_f32_e32 v54, v72
	v_rcp_f32_e32 v55, v73
	v_pk_mul_f32 v[48:49], v[70:71], v[48:49] op_sel_hi:[0,1]
	v_pk_mul_f32 v[50:51], v[70:71], v[50:51] op_sel_hi:[0,1]
	v_pk_mul_f32 v[52:53], v[70:71], v[52:53] op_sel_hi:[0,1]
	v_pk_mul_f32 v[54:55], v[70:71], v[54:55] op_sel_hi:[0,1]
	v_pk_mul_f32 v[48:49], v[60:61], v[48:49]
	v_pk_mul_f32 v[50:51], v[62:63], v[50:51]
	v_pk_mul_f32 v[52:53], v[56:57], v[52:53]
	v_pk_mul_f32 v[54:55], v[58:59], v[54:55]
	v_cvt_pk_bf16_f32 v48, v48, v49
	v_cvt_pk_bf16_f32 v49, v50, v51
	v_cvt_pk_bf16_f32 v50, v52, v53
	v_cvt_pk_bf16_f32 v51, v54, v55
	global_store_dwordx4 v[66:67], v[48:51], off
	s_nop 1
	v_pk_mov_b32 v[48:49], v[204:205], v[204:205] op_sel:[0,1]
	v_pk_mov_b32 v[50:51], v[206:207], v[206:207] op_sel:[0,1]
	v_mov_b32_e32 v52, v49
	v_mov_b32_e32 v53, v50
	v_mov_b32_e32 v49, v51
	v_pk_add_f32 v[48:49], v[52:53], v[48:49]
	v_mad_i64_i32 v[50:51], s[0:1], v64, s49, v[150:151]
	v_add_f32_e32 v48, v48, v49
	v_mov_b32_e32 v49, v48
	s_nop 1
	v_permlane16_swap_b32_e32 v48, v49
	v_lshl_add_u64 v[50:51], v[50:51], 0, v[120:121]
	s_waitcnt lgkmcnt(0)
	v_add_f32_e32 v52, v48, v49
	v_mov_b32_e32 v53, v52
	s_nop 1
	v_permlane32_swap_b32_e32 v52, v53
	v_add_u32_e32 v48, 0xa0, v152
	v_ashrrev_i32_e32 v49, 31, v48
	s_waitcnt lgkmcnt(0)
	v_add_f32_e32 v52, v52, v53
	v_fmamk_f32 v52, v52, 0x3a800000, v160
	v_mul_f32_e32 v53, 0x4b800000, v52
	v_cmp_gt_f32_e32 vcc, s52, v52
	s_nop 1
	v_cndmask_b32_e32 v52, v52, v53, vcc
	v_rsq_f32_e32 v54, v52
	v_lshlrev_b64 v[52:53], 6, v[48:49]
	v_lshl_add_u64 v[52:53], v[140:141], 0, v[52:53]
	v_mul_f32_e32 v49, 0x45800000, v54
	v_cndmask_b32_e32 v49, v54, v49, vcc
	v_mul_f32_e32 v55, 0xbfb8aa3b, v49
	v_mul_f32_e32 v36, v36, v55
	v_mul_f32_e32 v37, v37, v55
	v_mul_f32_e32 v38, v38, v55
	v_mul_f32_e32 v39, v39, v55
	v_mul_f32_e32 v32, v32, v55
	v_mul_f32_e32 v33, v33, v55
	v_mul_f32_e32 v34, v34, v55
	v_mul_f32_e32 v35, v35, v55
	v_exp_f32_e32 v36, v36
	v_exp_f32_e32 v37, v37
	v_exp_f32_e32 v38, v38
	v_exp_f32_e32 v39, v39
	v_exp_f32_e32 v32, v32
	v_exp_f32_e32 v33, v33
	v_exp_f32_e32 v34, v34
	v_exp_f32_e32 v35, v35
	v_mul_f32_e32 v54, v49, v49
	v_add_f32_e32 v36, 1.0, v36
	v_add_f32_e32 v37, 1.0, v37
	v_add_f32_e32 v38, 1.0, v38
	v_add_f32_e32 v39, 1.0, v39
	v_add_f32_e32 v49, 1.0, v32
	v_add_f32_e32 v55, 1.0, v33
	v_add_f32_e32 v56, 1.0, v34
	v_add_f32_e32 v57, 1.0, v35
	v_rcp_f32_e32 v32, v36
	v_rcp_f32_e32 v33, v37
	v_rcp_f32_e32 v34, v38
	v_rcp_f32_e32 v35, v39
	v_rcp_f32_e32 v36, v49
	v_rcp_f32_e32 v37, v55
	v_rcp_f32_e32 v38, v56
	v_rcp_f32_e32 v39, v57
	v_pk_mul_f32 v[32:33], v[54:55], v[32:33] op_sel_hi:[0,1]
	v_pk_mul_f32 v[34:35], v[54:55], v[34:35] op_sel_hi:[0,1]
	v_pk_mul_f32 v[36:37], v[54:55], v[36:37] op_sel_hi:[0,1]
	v_pk_mul_f32 v[38:39], v[54:55], v[38:39] op_sel_hi:[0,1]
	v_pk_mul_f32 v[32:33], v[44:45], v[32:33]
	v_pk_mul_f32 v[34:35], v[46:47], v[34:35]
	v_pk_mul_f32 v[36:37], v[40:41], v[36:37]
	v_pk_mul_f32 v[38:39], v[42:43], v[38:39]
	v_cvt_pk_bf16_f32 v32, v32, v33
	v_cvt_pk_bf16_f32 v33, v34, v35
	v_cvt_pk_bf16_f32 v34, v36, v37
	v_cvt_pk_bf16_f32 v35, v38, v39
	global_store_dwordx4 v[50:51], v[32:35], off
	s_nop 1
	v_pk_mov_b32 v[32:33], v[208:209], v[208:209] op_sel:[0,1]
	v_pk_mov_b32 v[34:35], v[210:211], v[210:211] op_sel:[0,1]
	v_mov_b32_e32 v36, v33
	v_mov_b32_e32 v37, v34
	v_mov_b32_e32 v33, v35
	v_pk_add_f32 v[32:33], v[36:37], v[32:33]
	v_mad_i64_i32 v[34:35], s[0:1], v48, s49, v[150:151]
	v_add_f32_e32 v32, v32, v33
	v_mov_b32_e32 v33, v32
	s_nop 1
	v_permlane16_swap_b32_e32 v32, v33
	v_lshl_add_u64 v[34:35], v[34:35], 0, v[120:121]
	s_waitcnt lgkmcnt(0)
	v_add_f32_e32 v36, v32, v33
	v_mov_b32_e32 v37, v36
	s_nop 1
	v_permlane32_swap_b32_e32 v36, v37
	v_add_u32_e32 v32, 0xb0, v152
	v_ashrrev_i32_e32 v33, 31, v32
	s_waitcnt lgkmcnt(0)
	v_add_f32_e32 v36, v36, v37
	v_fmamk_f32 v36, v36, 0x3a800000, v160
	v_mul_f32_e32 v37, 0x4b800000, v36
	v_cmp_gt_f32_e32 vcc, s52, v36
	s_nop 1
	v_cndmask_b32_e32 v36, v36, v37, vcc
	v_rsq_f32_e32 v38, v36
	v_lshlrev_b64 v[36:37], 6, v[32:33]
	v_lshl_add_u64 v[36:37], v[140:141], 0, v[36:37]
	v_mul_f32_e32 v33, 0x45800000, v38
	v_cndmask_b32_e32 v33, v38, v33, vcc
	v_mul_f32_e32 v39, 0xbfb8aa3b, v33
	v_mul_f32_e32 v20, v20, v39
	v_mul_f32_e32 v21, v21, v39
	v_mul_f32_e32 v22, v22, v39
	v_mul_f32_e32 v23, v23, v39
	v_mul_f32_e32 v16, v16, v39
	v_mul_f32_e32 v17, v17, v39
	v_mul_f32_e32 v18, v18, v39
	v_mul_f32_e32 v19, v19, v39
	v_exp_f32_e32 v20, v20
	v_exp_f32_e32 v21, v21
	v_exp_f32_e32 v22, v22
	v_exp_f32_e32 v23, v23
	v_exp_f32_e32 v16, v16
	v_exp_f32_e32 v17, v17
	v_exp_f32_e32 v18, v18
	v_exp_f32_e32 v19, v19
	v_mul_f32_e32 v38, v33, v33
	v_add_f32_e32 v20, 1.0, v20
	v_add_f32_e32 v21, 1.0, v21
	v_add_f32_e32 v22, 1.0, v22
	v_add_f32_e32 v23, 1.0, v23
	v_add_f32_e32 v33, 1.0, v16
	v_add_f32_e32 v39, 1.0, v17
	v_add_f32_e32 v40, 1.0, v18
	v_add_f32_e32 v41, 1.0, v19
	v_rcp_f32_e32 v16, v20
	v_rcp_f32_e32 v17, v21
	v_rcp_f32_e32 v18, v22
	v_rcp_f32_e32 v19, v23
	v_rcp_f32_e32 v20, v33
	v_rcp_f32_e32 v21, v39
	v_rcp_f32_e32 v22, v40
	v_rcp_f32_e32 v23, v41
	v_pk_mul_f32 v[16:17], v[38:39], v[16:17] op_sel_hi:[0,1]
	v_pk_mul_f32 v[18:19], v[38:39], v[18:19] op_sel_hi:[0,1]
	v_pk_mul_f32 v[20:21], v[38:39], v[20:21] op_sel_hi:[0,1]
	v_pk_mul_f32 v[22:23], v[38:39], v[22:23] op_sel_hi:[0,1]
	v_pk_mul_f32 v[16:17], v[28:29], v[16:17]
	v_pk_mul_f32 v[18:19], v[30:31], v[18:19]
	v_pk_mul_f32 v[20:21], v[24:25], v[20:21]
	v_pk_mul_f32 v[22:23], v[26:27], v[22:23]
	v_cvt_pk_bf16_f32 v16, v16, v17
	v_cvt_pk_bf16_f32 v17, v18, v19
	v_cvt_pk_bf16_f32 v18, v20, v21
	v_cvt_pk_bf16_f32 v19, v22, v23
	global_store_dwordx4 v[34:35], v[16:19], off
	s_andn2_b64 vcc, exec, s[4:5]
	s_nop 1
	v_pk_mov_b32 v[16:17], v[212:213], v[212:213] op_sel:[0,1]
	v_pk_mov_b32 v[18:19], v[214:215], v[214:215] op_sel:[0,1]
	v_mov_b32_e32 v20, v17
	v_mov_b32_e32 v21, v18
	v_mov_b32_e32 v17, v19
	v_pk_add_f32 v[16:17], v[20:21], v[16:17]
	s_nop 0
	v_add_f32_e32 v16, v16, v17
	v_mov_b32_e32 v17, v16
	s_nop 1
	v_permlane16_swap_b32_e32 v16, v17
	s_waitcnt lgkmcnt(0)
	v_add_f32_e32 v16, v16, v17
	v_mov_b32_e32 v17, v16
	s_nop 1
	v_permlane32_swap_b32_e32 v16, v17
	s_waitcnt lgkmcnt(0)
	v_add_f32_e32 v16, v16, v17
	v_fmamk_f32 v16, v16, 0x3a800000, v160
	v_mul_f32_e32 v17, 0x4b800000, v16
	v_cmp_gt_f32_e64 s[0:1], s52, v16
	s_nop 1
	v_cndmask_b32_e64 v16, v16, v17, s[0:1]
	v_rsq_f32_e32 v18, v16
	v_mad_i64_i32 v[16:17], s[24:25], v32, s49, v[150:151]
	v_lshl_add_u64 v[16:17], v[16:17], 0, v[120:121]
	v_mul_f32_e32 v19, 0x45800000, v18
	v_cndmask_b32_e64 v18, v18, v19, s[0:1]
	v_mul_f32_e32 v19, 0xbfb8aa3b, v18
	v_mul_f32_e32 v4, v4, v19
	v_mul_f32_e32 v5, v5, v19
	v_mul_f32_e32 v6, v6, v19
	v_mul_f32_e32 v7, v7, v19
	v_mul_f32_e32 v0, v0, v19
	v_mul_f32_e32 v1, v1, v19
	v_mul_f32_e32 v2, v2, v19
	v_mul_f32_e32 v3, v3, v19
	v_exp_f32_e32 v4, v4
	v_exp_f32_e32 v5, v5
	v_exp_f32_e32 v6, v6
	v_exp_f32_e32 v7, v7
	v_exp_f32_e32 v0, v0
	v_exp_f32_e32 v1, v1
	v_exp_f32_e32 v2, v2
	v_exp_f32_e32 v3, v3
	v_add_f32_e32 v4, 1.0, v4
	v_add_f32_e32 v5, 1.0, v5
	v_add_f32_e32 v6, 1.0, v6
	v_add_f32_e32 v7, 1.0, v7
	v_add_f32_e32 v19, 1.0, v0
	v_add_f32_e32 v20, 1.0, v1
	v_add_f32_e32 v21, 1.0, v2
	v_add_f32_e32 v22, 1.0, v3
	v_rcp_f32_e32 v0, v4
	v_rcp_f32_e32 v1, v5
	v_rcp_f32_e32 v2, v6
	v_rcp_f32_e32 v3, v7
	v_rcp_f32_e32 v4, v19
	v_rcp_f32_e32 v5, v20
	v_rcp_f32_e32 v6, v21
	v_rcp_f32_e32 v7, v22
	v_mul_f32_e32 v18, v18, v18
	v_pk_mul_f32 v[0:1], v[18:19], v[0:1] op_sel_hi:[0,1]
	v_pk_mul_f32 v[2:3], v[18:19], v[2:3] op_sel_hi:[0,1]
	v_pk_mul_f32 v[4:5], v[18:19], v[4:5] op_sel_hi:[0,1]
	v_pk_mul_f32 v[6:7], v[18:19], v[6:7] op_sel_hi:[0,1]
	v_pk_mul_f32 v[0:1], v[12:13], v[0:1]
	v_pk_mul_f32 v[2:3], v[14:15], v[2:3]
	v_pk_mul_f32 v[4:5], v[8:9], v[4:5]
	v_pk_mul_f32 v[6:7], v[10:11], v[6:7]
	v_cvt_pk_bf16_f32 v0, v0, v1
	v_cvt_pk_bf16_f32 v1, v2, v3
	v_cvt_pk_bf16_f32 v2, v4, v5
	v_cvt_pk_bf16_f32 v3, v6, v7
	s_mov_b64 s[0:1], -1
	global_store_dwordx4 v[16:17], v[0:3], off
	s_cbranch_vccnz .LBB0_1231
	s_andn2_b64 vcc, exec, s[8:9]
	s_cbranch_vccnz .LBB0_1230
	s_barrier
	s_branch .LBB0_1230

.LBB0_1325:
	s_or_b64 exec, exec, s[26:27]
	v_or_b32_e32 v112, 16, v150
	s_waitcnt lgkmcnt(0)
	v_ashrrev_i32_e32 v113, 31, v112
	v_lshlrev_b64 v[114:115], 11, v[112:113]
	v_lshl_add_u64 v[114:115], s[14:15], 0, v[114:115]
	v_lshl_add_u64 v[122:123], v[148:149], 1, v[114:115]
	s_nop 1
	v_pk_mov_b32 v[114:115], v[184:185], v[184:185] op_sel:[0,1]
	v_pk_mov_b32 v[116:117], v[186:187], v[186:187] op_sel:[0,1]
	v_pk_mov_b32 v[118:119], v[188:189], v[188:189] op_sel:[0,1]
	v_pk_mov_b32 v[120:121], v[190:191], v[190:191] op_sel:[0,1]
	v_lshlrev_b32_e32 v124, 16, v114
	v_and_b32_e32 v125, 0xffff0000, v114
	v_lshlrev_b32_e32 v114, 16, v115
	v_and_b32_e32 v115, 0xffff0000, v115
	v_lshlrev_b32_e32 v126, 16, v116
	v_and_b32_e32 v127, 0xffff0000, v116
	v_lshlrev_b32_e32 v116, 16, v117
	v_and_b32_e32 v117, 0xffff0000, v117
	v_lshlrev_b32_e32 v160, 16, v118
	v_and_b32_e32 v161, 0xffff0000, v118
	v_lshlrev_b32_e32 v118, 16, v119
	v_and_b32_e32 v119, 0xffff0000, v119
	v_lshlrev_b32_e32 v162, 16, v120
	v_and_b32_e32 v163, 0xffff0000, v120
	v_lshlrev_b32_e32 v120, 16, v121
	v_and_b32_e32 v121, 0xffff0000, v121
	v_pk_add_f32 v[108:109], v[108:109], v[124:125]
	v_pk_add_f32 v[110:111], v[110:111], v[114:115]
	v_pk_add_f32 v[104:105], v[104:105], v[126:127]
	v_pk_add_f32 v[106:107], v[106:107], v[116:117]
	v_pk_add_f32 v[100:101], v[100:101], v[160:161]
	v_pk_add_f32 v[102:103], v[102:103], v[118:119]
	v_pk_add_f32 v[114:115], v[96:97], v[162:163]
	v_pk_add_f32 v[116:117], v[98:99], v[120:121]
	v_cvt_pk_bf16_f32 v96, v108, v109
	v_cvt_pk_bf16_f32 v97, v110, v111
	v_pk_mul_f32 v[98:99], v[108:109], v[108:109]
	v_pk_mul_f32 v[108:109], v[110:111], v[110:111]
	v_pk_mul_f32 v[110:111], v[104:105], v[104:105]
	v_pk_mul_f32 v[118:119], v[106:107], v[106:107]
	v_pk_mul_f32 v[120:121], v[100:101], v[100:101]
	v_pk_mul_f32 v[124:125], v[102:103], v[102:103]
	v_pk_mul_f32 v[126:127], v[114:115], v[114:115]
	v_pk_mul_f32 v[160:161], v[116:117], v[116:117]
	v_add_f32_e32 v126, v126, v127
	v_add_f32_e32 v151, v160, v161
	v_add_f32_e32 v124, v124, v125
	v_add_f32_e32 v120, v120, v121
	v_add_f32_e32 v118, v118, v119
	v_add_f32_e32 v110, v110, v111
	v_add_f32_e32 v108, v108, v109
	v_add_f32_e32 v98, v98, v99
	v_add_f32_e32 v99, v126, v151
	v_add_f32_e32 v109, v120, v124
	v_add_f32_e32 v110, v110, v118
	v_add_f32_e32 v98, v98, v108
	v_add_f32_e32 v99, v109, v99
	v_add_f32_e32 v98, v98, v110
	v_add_f32_e32 v108, v98, v99
	v_mov_b32_e32 v109, v108
	s_nop 1
	v_permlane16_swap_b32_e32 v108, v109
	v_cvt_pk_bf16_f32 v98, v104, v105
	v_cvt_pk_bf16_f32 v99, v106, v107
	global_store_dwordx4 v[122:123], v[96:99], off
	s_waitcnt lgkmcnt(0)
	s_nop 0
	v_add_f32_e32 v96, v108, v109
	v_mov_b32_e32 v97, v96
	s_nop 1
	v_permlane32_swap_b32_e32 v96, v97
	v_cvt_pk_bf16_f32 v98, v100, v101
	v_cvt_pk_bf16_f32 v99, v102, v103
	v_cvt_pk_bf16_f32 v100, v114, v115
	v_cvt_pk_bf16_f32 v101, v116, v117
	global_store_dwordx4 v[122:123], v[98:101], off offset:256
	s_and_saveexec_b64 s[26:27], s[4:5]
	s_cbranch_execz .LBB0_1327
	v_lshlrev_b64 v[98:99], 6, v[112:113]
	v_lshl_add_u64 v[98:99], s[16:17], 0, v[98:99]
	v_lshl_add_u64 v[98:99], s[24:25], 2, v[98:99]
	s_lshl_b32 s10, s40, 2
	v_lshl_add_u64 v[98:99], v[98:99], 0, s[10:11]
	s_waitcnt lgkmcnt(0)
	v_add_f32_e32 v96, v96, v97
	global_store_dword v[98:99], v96, off
